# nt removed from all streaming loads (weights / x / W_down / W_up conversions): plain cached loads
# baseline (speedup 1.0000x reference)
.LBB0_35:
	s_or_b64 exec, exec, s[20:21]
	v_mad_u64_u32 v[96:97], s[2:3], v0, s28, v[92:93]
	v_lshlrev_b32_e32 v98, 6, v0
	v_or_b32_e32 v100, v98, v66
	v_ashrrev_i32_e32 v97, 31, v96
	v_lshl_add_u64 v[0:1], v[96:97], 2, v[80:81]
	v_or_b32_e32 v4, 4, v100
	v_mad_i64_i32 v[2:3], s[2:3], v100, s29, v[0:1]
	v_mad_i64_i32 v[4:5], s[2:3], v4, s29, v[0:1]
	global_load_dwordx4 v[60:63], v[2:3], off
	global_load_dwordx4 v[56:59], v[4:5], off
	v_or_b32_e32 v2, 8, v100
	v_or_b32_e32 v4, 12, v100
	v_mad_i64_i32 v[2:3], s[2:3], v2, s29, v[0:1]
	v_mad_i64_i32 v[4:5], s[2:3], v4, s29, v[0:1]
	global_load_dwordx4 v[52:55], v[2:3], off
	global_load_dwordx4 v[48:51], v[4:5], off
	v_or_b32_e32 v2, 16, v100
	v_or_b32_e32 v4, 20, v100
	v_or_b32_e32 v16, 52, v100
	v_mad_i64_i32 v[2:3], s[2:3], v2, s29, v[0:1]
	v_mad_i64_i32 v[4:5], s[2:3], v4, s29, v[0:1]
	v_mad_i64_i32 v[124:125], s[2:3], v16, s29, v[0:1]
	v_or_b32_e32 v16, 56, v100
	global_load_dwordx4 v[44:47], v[2:3], off
	global_load_dwordx4 v[40:43], v[4:5], off
	v_or_b32_e32 v2, 24, v100
	v_or_b32_e32 v4, 28, v100
	v_or_b32_e32 v6, 32, v100
	v_or_b32_e32 v8, 36, v100
	v_or_b32_e32 v10, 40, v100
	v_or_b32_e32 v12, 44, v100
	v_or_b32_e32 v14, 48, v100
	v_mad_i64_i32 v[126:127], s[2:3], v16, s29, v[0:1]
	v_or_b32_e32 v16, 60, v100
	v_mad_i64_i32 v[2:3], s[2:3], v2, s29, v[0:1]
	v_mad_i64_i32 v[4:5], s[2:3], v4, s29, v[0:1]
	v_mad_i64_i32 v[6:7], s[2:3], v6, s29, v[0:1]
	v_mad_i64_i32 v[8:9], s[2:3], v8, s29, v[0:1]
	v_mad_i64_i32 v[10:11], s[2:3], v10, s29, v[0:1]
	v_mad_i64_i32 v[12:13], s[2:3], v12, s29, v[0:1]
	v_mad_i64_i32 v[14:15], s[2:3], v14, s29, v[0:1]
	v_mad_i64_i32 v[0:1], s[2:3], v16, s29, v[0:1]
	global_load_dwordx4 v[36:39], v[2:3], off
	global_load_dwordx4 v[32:35], v[4:5], off
	global_load_dwordx4 v[28:31], v[6:7], off
	global_load_dwordx4 v[24:27], v[8:9], off
	global_load_dwordx4 v[20:23], v[10:11], off
	global_load_dwordx4 v[16:19], v[12:13], off
	s_nop 0
	global_load_dwordx4 v[12:15], v[14:15], off
	s_nop 0
	global_load_dwordx4 v[8:11], v[124:125], off
	global_load_dwordx4 v[4:7], v[126:127], off
	s_nop 0
	global_load_dwordx4 v[0:3], v[0:1], off
	v_cndmask_b32_e64 v97, 0, 1, s[6:7]
	v_cmp_ne_u32_e64 s[2:3], 1, v97
	s_andn2_b64 vcc, exec, s[6:7]
	v_ashrrev_i32_e32 v99, 31, v98
	s_cbranch_vccnz .LBB0_99
	v_ashrrev_i32_e32 v101, 31, v100
	v_lshl_add_u64 v[100:101], v[100:101], 2, s[54:55]
	global_load_dword v100, v[100:101], off
	s_waitcnt vmcnt(0)
	v_pk_mul_f32 v[124:125], v[60:61], v[100:101] op_sel_hi:[1,0]
	v_pk_mul_f32 v[100:101], v[62:63], v[100:101] op_sel_hi:[1,0]
	ds_write2_b32 v95, v100, v101 offset0:2 offset1:3
	v_lshl_add_u64 v[100:101], v[98:99], 0, v[66:67]
	v_lshl_add_u64 v[100:101], v[100:101], 2, s[54:55]
	global_load_dword v100, v[100:101], off offset:16
	ds_write2_b32 v95, v124, v125 offset1:1
	s_cbranch_execnz .LBB0_38

.LBB0_66:
	v_ashrrev_i32_e32 v0, 31, v123
	v_lshrrev_b32_e32 v0, 27, v0
	v_add_u32_e32 v1, v123, v0
	v_and_b32_e32 v0, 0x3ffffe0, v1
	v_lshlrev_b32_e32 v1, 1, v1
	v_and_b32_e32 v62, 0xffffffc0, v1
	v_sub_u32_e32 v0, v123, v0
	v_or_b32_e32 v96, v62, v66
	v_lshlrev_b32_e32 v0, 6, v0
	v_or_b32_e32 v4, 4, v96
	v_ashrrev_i32_e32 v1, 31, v0
	v_ashrrev_i32_e32 v97, 31, v96
	v_ashrrev_i32_e32 v5, 31, v4
	v_lshl_add_u64 v[98:99], v[0:1], 2, v[82:83]
	v_lshlrev_b64 v[2:3], 13, v[96:97]
	v_lshlrev_b64 v[4:5], 13, v[4:5]
	v_lshl_add_u64 v[2:3], v[98:99], 0, v[2:3]
	v_lshl_add_u64 v[6:7], v[98:99], 0, v[4:5]
	v_or_b32_e32 v10, 8, v96
	v_or_b32_e32 v12, 12, v96
	global_load_dwordx4 v[2:5], v[2:3], off
	s_nop 0
	global_load_dwordx4 v[6:9], v[6:7], off
	v_ashrrev_i32_e32 v11, 31, v10
	v_ashrrev_i32_e32 v13, 31, v12
	v_lshlrev_b64 v[10:11], 13, v[10:11]
	v_lshlrev_b64 v[12:13], 13, v[12:13]
	v_lshl_add_u64 v[10:11], v[98:99], 0, v[10:11]
	v_lshl_add_u64 v[14:15], v[98:99], 0, v[12:13]
	global_load_dwordx4 v[10:13], v[10:11], off
	s_nop 0
	global_load_dwordx4 v[14:17], v[14:15], off
	v_or_b32_e32 v18, 16, v96
	v_or_b32_e32 v20, 20, v96
	v_ashrrev_i32_e32 v19, 31, v18
	v_ashrrev_i32_e32 v21, 31, v20
	v_lshlrev_b64 v[18:19], 13, v[18:19]
	v_lshlrev_b64 v[20:21], 13, v[20:21]
	v_lshl_add_u64 v[18:19], v[98:99], 0, v[18:19]
	v_lshl_add_u64 v[22:23], v[98:99], 0, v[20:21]
	global_load_dwordx4 v[18:21], v[18:19], off
	s_nop 0
	global_load_dwordx4 v[22:25], v[22:23], off
	v_or_b32_e32 v26, 24, v96
	v_or_b32_e32 v28, 28, v96
	v_ashrrev_i32_e32 v27, 31, v26
	v_ashrrev_i32_e32 v29, 31, v28
	v_lshlrev_b64 v[26:27], 13, v[26:27]
	v_lshlrev_b64 v[28:29], 13, v[28:29]
	v_lshl_add_u64 v[26:27], v[98:99], 0, v[26:27]
	v_lshl_add_u64 v[30:31], v[98:99], 0, v[28:29]
	global_load_dwordx4 v[26:29], v[26:27], off
	s_nop 0
	global_load_dwordx4 v[30:33], v[30:31], off
	v_or_b32_e32 v34, 32, v96
	v_or_b32_e32 v36, 36, v96
	v_ashrrev_i32_e32 v35, 31, v34
	v_ashrrev_i32_e32 v37, 31, v36
	v_lshlrev_b64 v[34:35], 13, v[34:35]
	v_lshlrev_b64 v[36:37], 13, v[36:37]
	v_lshl_add_u64 v[34:35], v[98:99], 0, v[34:35]
	v_lshl_add_u64 v[38:39], v[98:99], 0, v[36:37]
	global_load_dwordx4 v[34:37], v[34:35], off
	s_nop 0
	global_load_dwordx4 v[38:41], v[38:39], off
	v_or_b32_e32 v42, 40, v96
	v_or_b32_e32 v44, 44, v96
	v_ashrrev_i32_e32 v43, 31, v42
	v_ashrrev_i32_e32 v45, 31, v44
	v_lshlrev_b64 v[42:43], 13, v[42:43]
	v_lshlrev_b64 v[44:45], 13, v[44:45]
	v_lshl_add_u64 v[42:43], v[98:99], 0, v[42:43]
	v_lshl_add_u64 v[46:47], v[98:99], 0, v[44:45]
	v_or_b32_e32 v50, 48, v96
	global_load_dwordx4 v[42:45], v[42:43], off
	s_nop 0
	global_load_dwordx4 v[46:49], v[46:47], off
	v_ashrrev_i32_e32 v51, 31, v50
	v_lshlrev_b64 v[50:51], 13, v[50:51]
	v_or_b32_e32 v54, 52, v96
	v_lshl_add_u64 v[50:51], v[98:99], 0, v[50:51]
	v_ashrrev_i32_e32 v55, 31, v54
	global_load_dwordx4 v[50:53], v[50:51], off
	v_lshlrev_b64 v[54:55], 13, v[54:55]
	v_or_b32_e32 v58, 56, v96
	v_lshl_add_u64 v[54:55], v[98:99], 0, v[54:55]
	v_ashrrev_i32_e32 v59, 31, v58
	global_load_dwordx4 v[54:57], v[54:55], off
	v_lshlrev_b64 v[58:59], 13, v[58:59]
	v_or_b32_e32 v96, 60, v96
	v_lshl_add_u64 v[58:59], v[98:99], 0, v[58:59]
	v_ashrrev_i32_e32 v97, 31, v96
	global_load_dwordx4 v[58:61], v[58:59], off
	v_lshlrev_b64 v[96:97], 13, v[96:97]
	v_lshl_add_u64 v[96:97], v[98:99], 0, v[96:97]
	global_load_dwordx4 v[96:99], v[96:97], off
	v_add_u32_e32 v1, 0x410, v95
	v_ashrrev_i32_e32 v63, 31, v62
	s_waitcnt vmcnt(15)
	ds_write2_b32 v95, v2, v3 offset1:1
	ds_write2_b32 v95, v4, v5 offset0:2 offset1:3
	s_waitcnt vmcnt(14)
	ds_write2_b32 v1, v6, v7 offset1:1
	v_add_u32_e32 v1, 0x418, v95
	ds_write2_b32 v1, v8, v9 offset1:1
	v_add_u32_e32 v1, 0x820, v95
	v_lshl_add_u64 v[8:9], v[62:63], 1, v[68:69]
	s_waitcnt vmcnt(13)
	ds_write2_b32 v1, v10, v11 offset1:1
	v_add_u32_e32 v1, 0x828, v95
	ds_write2_b32 v1, v12, v13 offset1:1
	v_add_u32_e32 v1, 0xc30, v95
	s_waitcnt vmcnt(12)
	ds_write2_b32 v1, v14, v15 offset1:1
	v_add_u32_e32 v1, 0xc38, v95
	ds_write2_b32 v1, v16, v17 offset1:1
	v_add_u32_e32 v1, 0x1040, v95
	s_waitcnt vmcnt(11)
	ds_write2_b32 v1, v18, v19 offset1:1
	v_add_u32_e32 v1, 0x1048, v95
	ds_write2_b32 v1, v20, v21 offset1:1
	v_add_u32_e32 v1, 0x1450, v95
	s_waitcnt vmcnt(10)
	ds_write2_b32 v1, v22, v23 offset1:1
	v_add_u32_e32 v1, 0x1458, v95
	ds_write2_b32 v1, v24, v25 offset1:1
	v_add_u32_e32 v1, 0x1860, v95
	s_waitcnt vmcnt(9)
	ds_write2_b32 v1, v26, v27 offset1:1
	v_add_u32_e32 v1, 0x1868, v95
	ds_write2_b32 v1, v28, v29 offset1:1
	v_add_u32_e32 v1, 0x1c70, v95
	s_waitcnt vmcnt(8)
	ds_write2_b32 v1, v30, v31 offset1:1
	v_add_u32_e32 v1, 0x1c78, v95
	ds_write2_b32 v1, v32, v33 offset1:1
	v_add_u32_e32 v1, 0x2080, v95
	s_waitcnt vmcnt(7)
	ds_write2_b32 v1, v34, v35 offset1:1
	v_add_u32_e32 v1, 0x2088, v95
	ds_write2_b32 v1, v36, v37 offset1:1
	v_add_u32_e32 v1, 0x2490, v95
	s_waitcnt vmcnt(6)
	ds_write2_b32 v1, v38, v39 offset1:1
	v_add_u32_e32 v1, 0x2498, v95
	ds_write2_b32 v1, v40, v41 offset1:1
	v_add_u32_e32 v1, 0x28a0, v95
	s_waitcnt vmcnt(5)
	ds_write2_b32 v1, v42, v43 offset1:1
	v_add_u32_e32 v1, 0x28a8, v95
	ds_write2_b32 v1, v44, v45 offset1:1
	v_add_u32_e32 v1, 0x2cb0, v95
	s_waitcnt vmcnt(4)
	ds_write2_b32 v1, v46, v47 offset1:1
	v_add_u32_e32 v1, 0x2cb8, v95
	ds_write2_b32 v1, v48, v49 offset1:1
	v_add_u32_e32 v1, 0x30c0, v95
	s_waitcnt vmcnt(3)
	ds_write2_b32 v1, v50, v51 offset1:1
	v_add_u32_e32 v1, 0x30c8, v95
	ds_write2_b32 v1, v52, v53 offset1:1
	v_add_u32_e32 v1, 0x34d0, v95
	s_waitcnt vmcnt(2)
	ds_write2_b32 v1, v54, v55 offset1:1
	v_add_u32_e32 v1, 0x34d8, v95
	ds_write2_b32 v1, v56, v57 offset1:1
	v_add_u32_e32 v1, 0x38e0, v95
	s_waitcnt vmcnt(1)
	ds_write2_b32 v1, v58, v59 offset1:1
	v_add_u32_e32 v1, 0x38e8, v95
	ds_write2_b32 v1, v60, v61 offset1:1
	v_add_u32_e32 v1, 0x3cf0, v95
	s_waitcnt vmcnt(0)
	ds_write2_b32 v1, v96, v97 offset1:1
	v_add_u32_e32 v1, 0x3cf8, v95
	ds_write2_b32 v1, v98, v99 offset1:1
	s_waitcnt lgkmcnt(0)
	ds_read2_b32 v[2:3], v114 offset1:65
	s_waitcnt lgkmcnt(0)
	v_cvt_pk_bf16_f32 v2, v2, v3
	ds_read2_b32 v[4:5], v114 offset0:130 offset1:195
	v_add_u32_e32 v1, 0x400, v114
	s_waitcnt lgkmcnt(0)
	v_cvt_pk_bf16_f32 v3, v4, v5
	ds_read2_b32 v[4:5], v1 offset0:4 offset1:69
	s_waitcnt lgkmcnt(0)
	v_cvt_pk_bf16_f32 v4, v4, v5
	ds_read2_b32 v[6:7], v1 offset0:134 offset1:199
	s_waitcnt lgkmcnt(0)
	v_cvt_pk_bf16_f32 v5, v6, v7
	v_or_b32_e32 v6, 0, v254
	v_or_b32_e32 v6, v0, v6
	v_ashrrev_i32_e32 v7, 31, v6
	v_lshlrev_b64 v[6:7], 12, v[6:7]
	v_lshl_add_u64 v[6:7], v[8:9], 0, v[6:7]
	ds_read2_b32 v[10:11], v114 offset0:8 offset1:73
	global_store_dwordx4 v[6:7], v[2:5], off
	s_waitcnt lgkmcnt(0)
	s_nop 0
	v_cvt_pk_bf16_f32 v2, v10, v11
	ds_read2_b32 v[4:5], v114 offset0:138 offset1:203
	s_waitcnt lgkmcnt(0)
	v_cvt_pk_bf16_f32 v3, v4, v5
	ds_read2_b32 v[4:5], v1 offset0:12 offset1:77
	s_waitcnt lgkmcnt(0)
	v_cvt_pk_bf16_f32 v4, v4, v5
	ds_read2_b32 v[6:7], v1 offset0:142 offset1:207
	s_waitcnt lgkmcnt(0)
	v_cvt_pk_bf16_f32 v5, v6, v7
	v_or_b32_e32 v6, 4, v254
	v_or_b32_e32 v6, v0, v6
	v_ashrrev_i32_e32 v7, 31, v6
	v_lshlrev_b64 v[6:7], 12, v[6:7]
	v_lshl_add_u64 v[6:7], v[8:9], 0, v[6:7]
	ds_read2_b32 v[10:11], v114 offset0:16 offset1:81
	global_store_dwordx4 v[6:7], v[2:5], off
	s_waitcnt lgkmcnt(0)
	s_nop 0
	v_cvt_pk_bf16_f32 v2, v10, v11
	ds_read2_b32 v[4:5], v114 offset0:146 offset1:211
	s_waitcnt lgkmcnt(0)
	v_cvt_pk_bf16_f32 v3, v4, v5
	ds_read2_b32 v[4:5], v1 offset0:20 offset1:85
	s_waitcnt lgkmcnt(0)
	v_cvt_pk_bf16_f32 v4, v4, v5
	ds_read2_b32 v[6:7], v1 offset0:150 offset1:215
	s_waitcnt lgkmcnt(0)
	v_cvt_pk_bf16_f32 v5, v6, v7
	v_or_b32_e32 v6, 8, v254
	v_or_b32_e32 v6, v0, v6
	v_ashrrev_i32_e32 v7, 31, v6
	v_lshlrev_b64 v[6:7], 12, v[6:7]
	v_lshl_add_u64 v[6:7], v[8:9], 0, v[6:7]
	ds_read2_b32 v[10:11], v114 offset0:24 offset1:89
	global_store_dwordx4 v[6:7], v[2:5], off
	s_waitcnt lgkmcnt(0)
	s_nop 0
	v_cvt_pk_bf16_f32 v2, v10, v11
	ds_read2_b32 v[4:5], v114 offset0:154 offset1:219
	s_waitcnt lgkmcnt(0)
	v_cvt_pk_bf16_f32 v3, v4, v5
	ds_read2_b32 v[4:5], v1 offset0:28 offset1:93
	s_waitcnt lgkmcnt(0)
	v_cvt_pk_bf16_f32 v4, v4, v5
	ds_read2_b32 v[6:7], v1 offset0:158 offset1:223
	s_waitcnt lgkmcnt(0)
	v_cvt_pk_bf16_f32 v5, v6, v7
	v_or_b32_e32 v6, 12, v254
	v_or_b32_e32 v6, v0, v6
	v_ashrrev_i32_e32 v7, 31, v6
	v_lshlrev_b64 v[6:7], 12, v[6:7]
	v_lshl_add_u64 v[6:7], v[8:9], 0, v[6:7]
	ds_read2_b32 v[10:11], v114 offset0:32 offset1:97
	global_store_dwordx4 v[6:7], v[2:5], off
	s_waitcnt lgkmcnt(0)
	s_nop 0
	v_cvt_pk_bf16_f32 v2, v10, v11
	ds_read2_b32 v[4:5], v114 offset0:162 offset1:227
	s_waitcnt lgkmcnt(0)
	v_cvt_pk_bf16_f32 v3, v4, v5
	ds_read2_b32 v[4:5], v1 offset0:36 offset1:101
	s_waitcnt lgkmcnt(0)
	v_cvt_pk_bf16_f32 v4, v4, v5
	ds_read2_b32 v[6:7], v1 offset0:166 offset1:231
	s_waitcnt lgkmcnt(0)
	v_cvt_pk_bf16_f32 v5, v6, v7
	v_or_b32_e32 v6, 32, v254
	v_or_b32_e32 v6, v0, v6
	v_ashrrev_i32_e32 v7, 31, v6
	v_lshlrev_b64 v[6:7], 12, v[6:7]
	v_lshl_add_u64 v[6:7], v[8:9], 0, v[6:7]
	ds_read2_b32 v[10:11], v114 offset0:40 offset1:105
	global_store_dwordx4 v[6:7], v[2:5], off
	s_waitcnt lgkmcnt(0)
	s_nop 0
	v_cvt_pk_bf16_f32 v2, v10, v11
	ds_read2_b32 v[4:5], v114 offset0:170 offset1:235
	s_waitcnt lgkmcnt(0)
	v_cvt_pk_bf16_f32 v3, v4, v5
	ds_read2_b32 v[4:5], v1 offset0:44 offset1:109
	s_waitcnt lgkmcnt(0)
	v_cvt_pk_bf16_f32 v4, v4, v5
	ds_read2_b32 v[6:7], v1 offset0:174 offset1:239
	s_waitcnt lgkmcnt(0)
	v_cvt_pk_bf16_f32 v5, v6, v7
	v_or_b32_e32 v6, 36, v254
	v_or_b32_e32 v6, v0, v6
	v_ashrrev_i32_e32 v7, 31, v6
	v_lshlrev_b64 v[6:7], 12, v[6:7]
	v_lshl_add_u64 v[6:7], v[8:9], 0, v[6:7]
	ds_read2_b32 v[10:11], v114 offset0:48 offset1:113
	global_store_dwordx4 v[6:7], v[2:5], off
	s_waitcnt lgkmcnt(0)
	s_nop 0
	v_cvt_pk_bf16_f32 v2, v10, v11
	ds_read2_b32 v[4:5], v114 offset0:178 offset1:243
	s_waitcnt lgkmcnt(0)
	v_cvt_pk_bf16_f32 v3, v4, v5
	ds_read2_b32 v[4:5], v1 offset0:52 offset1:117
	s_waitcnt lgkmcnt(0)
	v_cvt_pk_bf16_f32 v4, v4, v5
	ds_read2_b32 v[6:7], v1 offset0:182 offset1:247
	s_waitcnt lgkmcnt(0)
	v_cvt_pk_bf16_f32 v5, v6, v7
	v_or_b32_e32 v6, 40, v254
	v_or_b32_e32 v6, v0, v6
	v_ashrrev_i32_e32 v7, 31, v6
	v_lshlrev_b64 v[6:7], 12, v[6:7]
	v_lshl_add_u64 v[6:7], v[8:9], 0, v[6:7]
	ds_read2_b32 v[10:11], v114 offset0:56 offset1:121
	global_store_dwordx4 v[6:7], v[2:5], off
	v_or_b32_e32 v255, 44, v254
	v_or_b32_e32 v0, v0, v255
	s_waitcnt lgkmcnt(0)
	v_cvt_pk_bf16_f32 v2, v10, v11
	ds_read2_b32 v[4:5], v114 offset0:186 offset1:251
	s_waitcnt lgkmcnt(0)
	v_cvt_pk_bf16_f32 v3, v4, v5
	ds_read2_b32 v[4:5], v1 offset0:60 offset1:125
	s_waitcnt lgkmcnt(0)
	v_cvt_pk_bf16_f32 v4, v4, v5
	ds_read2_b32 v[6:7], v1 offset0:190 offset1:255
	v_ashrrev_i32_e32 v1, 31, v0
	v_lshlrev_b64 v[0:1], 12, v[0:1]
	v_lshl_add_u64 v[0:1], v[8:9], 0, v[0:1]
	s_waitcnt lgkmcnt(0)
	v_cvt_pk_bf16_f32 v5, v6, v7
	global_store_dwordx4 v[0:1], v[2:5], off
	s_waitcnt lgkmcnt(0)
	s_or_b64 exec, exec, s[0:1]
	s_and_b64 exec, exec, vcc
	s_cbranch_execz .LBB0_24

.LBB0_71:
	v_ashrrev_i32_e32 v0, 31, v123
	v_lshrrev_b32_e32 v0, 29, v0
	v_add_u32_e32 v0, v123, v0
	v_and_b32_e32 v1, 0x3fffff8, v0
	v_lshlrev_b32_e32 v0, 3, v0
	v_and_b32_e32 v98, 0xffffffc0, v0
	v_sub_u32_e32 v1, v123, v1
	v_or_b32_e32 v100, v98, v66
	v_lshlrev_b32_e32 v96, 6, v1
	v_or_b32_e32 v4, 4, v100
	v_ashrrev_i32_e32 v97, 31, v96
	v_ashrrev_i32_e32 v101, 31, v100
	v_ashrrev_i32_e32 v5, 31, v4
	v_lshl_add_u64 v[0:1], v[96:97], 2, v[84:85]
	v_lshlrev_b64 v[2:3], 11, v[100:101]
	v_lshlrev_b64 v[4:5], 11, v[4:5]
	v_lshl_add_u64 v[2:3], v[0:1], 0, v[2:3]
	v_lshl_add_u64 v[4:5], v[0:1], 0, v[4:5]
	global_load_dwordx4 v[60:63], v[2:3], off
	global_load_dwordx4 v[56:59], v[4:5], off
	v_or_b32_e32 v2, 8, v100
	v_or_b32_e32 v4, 12, v100
	v_ashrrev_i32_e32 v3, 31, v2
	v_ashrrev_i32_e32 v5, 31, v4
	v_lshlrev_b64 v[2:3], 11, v[2:3]
	v_lshlrev_b64 v[4:5], 11, v[4:5]
	v_lshl_add_u64 v[2:3], v[0:1], 0, v[2:3]
	v_lshl_add_u64 v[4:5], v[0:1], 0, v[4:5]
	global_load_dwordx4 v[52:55], v[2:3], off
	global_load_dwordx4 v[48:51], v[4:5], off
	v_or_b32_e32 v2, 16, v100
	v_or_b32_e32 v4, 20, v100
	v_ashrrev_i32_e32 v3, 31, v2
	v_ashrrev_i32_e32 v5, 31, v4
	v_lshlrev_b64 v[2:3], 11, v[2:3]
	v_lshlrev_b64 v[4:5], 11, v[4:5]
	v_lshl_add_u64 v[2:3], v[0:1], 0, v[2:3]
	v_lshl_add_u64 v[4:5], v[0:1], 0, v[4:5]
	global_load_dwordx4 v[44:47], v[2:3], off
	global_load_dwordx4 v[40:43], v[4:5], off
	v_or_b32_e32 v2, 24, v100
	v_or_b32_e32 v4, 28, v100
	v_ashrrev_i32_e32 v3, 31, v2
	v_ashrrev_i32_e32 v5, 31, v4
	v_lshlrev_b64 v[2:3], 11, v[2:3]
	v_lshlrev_b64 v[4:5], 11, v[4:5]
	v_lshl_add_u64 v[2:3], v[0:1], 0, v[2:3]
	v_lshl_add_u64 v[4:5], v[0:1], 0, v[4:5]
	global_load_dwordx4 v[36:39], v[2:3], off
	global_load_dwordx4 v[32:35], v[4:5], off
	v_or_b32_e32 v2, 32, v100
	v_or_b32_e32 v4, 36, v100
	v_ashrrev_i32_e32 v3, 31, v2
	v_ashrrev_i32_e32 v5, 31, v4
	v_lshlrev_b64 v[2:3], 11, v[2:3]
	v_lshlrev_b64 v[4:5], 11, v[4:5]
	v_lshl_add_u64 v[2:3], v[0:1], 0, v[2:3]
	v_lshl_add_u64 v[4:5], v[0:1], 0, v[4:5]
	global_load_dwordx4 v[28:31], v[2:3], off
	global_load_dwordx4 v[24:27], v[4:5], off
	v_or_b32_e32 v2, 40, v100
	v_or_b32_e32 v4, 44, v100
	v_ashrrev_i32_e32 v3, 31, v2
	v_ashrrev_i32_e32 v5, 31, v4
	v_lshlrev_b64 v[2:3], 11, v[2:3]
	v_lshlrev_b64 v[4:5], 11, v[4:5]
	v_lshl_add_u64 v[2:3], v[0:1], 0, v[2:3]
	v_lshl_add_u64 v[4:5], v[0:1], 0, v[4:5]
	global_load_dwordx4 v[20:23], v[2:3], off
	global_load_dwordx4 v[16:19], v[4:5], off
	v_or_b32_e32 v2, 48, v100
	v_or_b32_e32 v4, 52, v100
	v_ashrrev_i32_e32 v3, 31, v2
	v_ashrrev_i32_e32 v5, 31, v4
	v_lshlrev_b64 v[2:3], 11, v[2:3]
	v_lshlrev_b64 v[4:5], 11, v[4:5]
	v_lshl_add_u64 v[2:3], v[0:1], 0, v[2:3]
	v_lshl_add_u64 v[4:5], v[0:1], 0, v[4:5]
	global_load_dwordx4 v[12:15], v[2:3], off
	global_load_dwordx4 v[8:11], v[4:5], off
	v_or_b32_e32 v2, 56, v100
	v_or_b32_e32 v4, 60, v100
	v_ashrrev_i32_e32 v3, 31, v2
	v_ashrrev_i32_e32 v5, 31, v4
	v_lshlrev_b64 v[2:3], 11, v[2:3]
	v_lshlrev_b64 v[4:5], 11, v[4:5]
	v_lshl_add_u64 v[2:3], v[0:1], 0, v[2:3]
	v_lshl_add_u64 v[0:1], v[0:1], 0, v[4:5]
	global_load_dwordx4 v[4:7], v[2:3], off
	s_nop 0
	global_load_dwordx4 v[0:3], v[0:1], off
	v_cndmask_b32_e64 v97, 0, 1, s[8:9]
	v_cmp_ne_u32_e64 s[2:3], 1, v97
	s_andn2_b64 vcc, exec, s[8:9]
	v_ashrrev_i32_e32 v99, 31, v98
	s_cbranch_vccnz .LBB0_161
	v_readlane_b32 s64, v252, 7
	v_readlane_b32 s78, v252, 21
	v_readlane_b32 s79, v252, 22
	v_readlane_b32 s65, v252, 8
	s_nop 0
	v_lshl_add_u64 v[100:101], v[100:101], 2, s[78:79]
	global_load_dword v100, v[100:101], off
	v_readlane_b32 s66, v252, 9
	v_readlane_b32 s67, v252, 10
	v_readlane_b32 s68, v252, 11
	v_readlane_b32 s69, v252, 12
	v_readlane_b32 s70, v252, 13
	v_readlane_b32 s71, v252, 14
	v_readlane_b32 s72, v252, 15
	v_readlane_b32 s73, v252, 16
	v_readlane_b32 s74, v252, 17
	v_readlane_b32 s75, v252, 18
	v_readlane_b32 s76, v252, 19
	v_readlane_b32 s77, v252, 20
	s_waitcnt vmcnt(0)
	v_pk_mul_f32 v[124:125], v[60:61], v[100:101] op_sel_hi:[1,0]
	v_pk_mul_f32 v[100:101], v[62:63], v[100:101] op_sel_hi:[1,0]
	ds_write2_b32 v95, v100, v101 offset0:2 offset1:3
	v_lshl_add_u64 v[100:101], v[98:99], 0, v[66:67]
	v_lshl_add_u64 v[100:101], v[100:101], 2, s[78:79]
	global_load_dword v100, v[100:101], off offset:16
	ds_write2_b32 v95, v124, v125 offset1:1
	s_cbranch_execnz .LBB0_74

.LBB0_108:
	v_ashrrev_i32_e32 v0, 31, v123
	v_lshrrev_b32_e32 v0, 28, v0
	v_add_u32_e32 v0, v123, v0
	v_and_b32_e32 v1, 0x3fffff0, v0
	v_lshlrev_b32_e32 v0, 2, v0
	v_and_b32_e32 v98, 0xffffffc0, v0
	v_sub_u32_e32 v1, v123, v1
	v_or_b32_e32 v100, v98, v66
	v_lshlrev_b32_e32 v96, 6, v1
	v_or_b32_e32 v4, 4, v100
	v_ashrrev_i32_e32 v97, 31, v96
	v_ashrrev_i32_e32 v101, 31, v100
	v_ashrrev_i32_e32 v5, 31, v4
	v_lshl_add_u64 v[0:1], v[96:97], 2, v[86:87]
	v_lshlrev_b64 v[2:3], 12, v[100:101]
	v_lshlrev_b64 v[4:5], 12, v[4:5]
	v_lshl_add_u64 v[2:3], v[0:1], 0, v[2:3]
	v_lshl_add_u64 v[4:5], v[0:1], 0, v[4:5]
	global_load_dwordx4 v[60:63], v[2:3], off
	global_load_dwordx4 v[56:59], v[4:5], off
	v_or_b32_e32 v2, 8, v100
	v_or_b32_e32 v4, 12, v100
	v_ashrrev_i32_e32 v3, 31, v2
	v_ashrrev_i32_e32 v5, 31, v4
	v_lshlrev_b64 v[2:3], 12, v[2:3]
	v_lshlrev_b64 v[4:5], 12, v[4:5]
	v_lshl_add_u64 v[2:3], v[0:1], 0, v[2:3]
	v_lshl_add_u64 v[4:5], v[0:1], 0, v[4:5]
	global_load_dwordx4 v[52:55], v[2:3], off
	global_load_dwordx4 v[48:51], v[4:5], off
	v_or_b32_e32 v2, 16, v100
	v_or_b32_e32 v4, 20, v100
	v_ashrrev_i32_e32 v3, 31, v2
	v_ashrrev_i32_e32 v5, 31, v4
	v_lshlrev_b64 v[2:3], 12, v[2:3]
	v_lshlrev_b64 v[4:5], 12, v[4:5]
	v_lshl_add_u64 v[2:3], v[0:1], 0, v[2:3]
	v_lshl_add_u64 v[4:5], v[0:1], 0, v[4:5]
	global_load_dwordx4 v[44:47], v[2:3], off
	global_load_dwordx4 v[40:43], v[4:5], off
	v_or_b32_e32 v2, 24, v100
	v_or_b32_e32 v4, 28, v100
	v_ashrrev_i32_e32 v3, 31, v2
	v_ashrrev_i32_e32 v5, 31, v4
	v_lshlrev_b64 v[2:3], 12, v[2:3]
	v_lshlrev_b64 v[4:5], 12, v[4:5]
	v_lshl_add_u64 v[2:3], v[0:1], 0, v[2:3]
	v_lshl_add_u64 v[4:5], v[0:1], 0, v[4:5]
	global_load_dwordx4 v[36:39], v[2:3], off
	global_load_dwordx4 v[32:35], v[4:5], off
	v_or_b32_e32 v2, 32, v100
	v_or_b32_e32 v4, 36, v100
	v_ashrrev_i32_e32 v3, 31, v2
	v_ashrrev_i32_e32 v5, 31, v4
	v_lshlrev_b64 v[2:3], 12, v[2:3]
	v_lshlrev_b64 v[4:5], 12, v[4:5]
	v_lshl_add_u64 v[2:3], v[0:1], 0, v[2:3]
	v_lshl_add_u64 v[4:5], v[0:1], 0, v[4:5]
	global_load_dwordx4 v[28:31], v[2:3], off
	global_load_dwordx4 v[24:27], v[4:5], off
	v_or_b32_e32 v2, 40, v100
	v_or_b32_e32 v4, 44, v100
	v_ashrrev_i32_e32 v3, 31, v2
	v_ashrrev_i32_e32 v5, 31, v4
	v_lshlrev_b64 v[2:3], 12, v[2:3]
	v_lshlrev_b64 v[4:5], 12, v[4:5]
	v_lshl_add_u64 v[2:3], v[0:1], 0, v[2:3]
	v_lshl_add_u64 v[4:5], v[0:1], 0, v[4:5]
	global_load_dwordx4 v[20:23], v[2:3], off
	global_load_dwordx4 v[16:19], v[4:5], off
	v_or_b32_e32 v2, 48, v100
	v_or_b32_e32 v4, 52, v100
	v_ashrrev_i32_e32 v3, 31, v2
	v_ashrrev_i32_e32 v5, 31, v4
	v_lshlrev_b64 v[2:3], 12, v[2:3]
	v_lshlrev_b64 v[4:5], 12, v[4:5]
	v_lshl_add_u64 v[2:3], v[0:1], 0, v[2:3]
	v_lshl_add_u64 v[4:5], v[0:1], 0, v[4:5]
	global_load_dwordx4 v[12:15], v[2:3], off
	global_load_dwordx4 v[8:11], v[4:5], off
	v_or_b32_e32 v2, 56, v100
	v_or_b32_e32 v4, 60, v100
	v_ashrrev_i32_e32 v3, 31, v2
	v_ashrrev_i32_e32 v5, 31, v4
	v_lshlrev_b64 v[2:3], 12, v[2:3]
	v_lshlrev_b64 v[4:5], 12, v[4:5]
	v_lshl_add_u64 v[2:3], v[0:1], 0, v[2:3]
	v_lshl_add_u64 v[0:1], v[0:1], 0, v[4:5]
	global_load_dwordx4 v[4:7], v[2:3], off
	s_nop 0
	global_load_dwordx4 v[0:3], v[0:1], off
	v_cndmask_b32_e64 v97, 0, 1, s[10:11]
	v_cmp_ne_u32_e64 s[2:3], 1, v97
	s_andn2_b64 vcc, exec, s[10:11]
	v_ashrrev_i32_e32 v99, 31, v98
	s_cbranch_vccnz .LBB0_169
	v_readlane_b32 s64, v252, 23
	v_readlane_b32 s65, v252, 24
	v_readlane_b32 s66, v252, 25
	s_nop 0
	v_lshl_add_u64 v[100:101], v[100:101], 2, s[64:65]
	global_load_dword v100, v[100:101], off
	v_readlane_b32 s67, v252, 26
	v_readlane_b32 s68, v252, 27
	v_readlane_b32 s69, v252, 28
	v_readlane_b32 s70, v252, 29
	v_readlane_b32 s71, v252, 30
	v_readlane_b32 s72, v252, 31
	v_readlane_b32 s73, v252, 32
	v_readlane_b32 s74, v252, 33
	v_readlane_b32 s75, v252, 34
	v_readlane_b32 s76, v252, 35
	v_readlane_b32 s77, v252, 36
	v_readlane_b32 s78, v252, 37
	v_readlane_b32 s79, v252, 38
	s_waitcnt vmcnt(0)
	v_pk_mul_f32 v[124:125], v[60:61], v[100:101] op_sel_hi:[1,0]
	v_pk_mul_f32 v[100:101], v[62:63], v[100:101] op_sel_hi:[1,0]
	ds_write2_b32 v95, v100, v101 offset0:2 offset1:3
	v_lshl_add_u64 v[100:101], v[98:99], 0, v[66:67]
	v_lshl_add_u64 v[100:101], v[100:101], 2, s[64:65]
	global_load_dword v100, v[100:101], off offset:16
	ds_write2_b32 v95, v124, v125 offset1:1
	s_cbranch_execnz .LBB0_111

.LBB0_137:
	v_ashrrev_i32_e32 v0, 31, v123
	v_lshrrev_b32_e32 v0, 27, v0
	v_add_u32_e32 v1, v123, v0
	v_and_b32_e32 v0, 0x3ffffe0, v1
	v_lshlrev_b32_e32 v1, 1, v1
	v_and_b32_e32 v62, 0xffffffc0, v1
	v_sub_u32_e32 v0, v123, v0
	v_or_b32_e32 v96, v62, v66
	v_lshlrev_b32_e32 v0, 6, v0
	v_or_b32_e32 v4, 4, v96
	v_ashrrev_i32_e32 v1, 31, v0
	v_ashrrev_i32_e32 v97, 31, v96
	v_ashrrev_i32_e32 v5, 31, v4
	v_lshl_add_u64 v[98:99], v[0:1], 2, v[88:89]
	v_lshlrev_b64 v[2:3], 13, v[96:97]
	v_lshlrev_b64 v[4:5], 13, v[4:5]
	v_lshl_add_u64 v[2:3], v[98:99], 0, v[2:3]
	v_lshl_add_u64 v[6:7], v[98:99], 0, v[4:5]
	v_or_b32_e32 v10, 8, v96
	v_or_b32_e32 v12, 12, v96
	global_load_dwordx4 v[2:5], v[2:3], off
	s_nop 0
	global_load_dwordx4 v[6:9], v[6:7], off
	v_ashrrev_i32_e32 v11, 31, v10
	v_ashrrev_i32_e32 v13, 31, v12
	v_lshlrev_b64 v[10:11], 13, v[10:11]
	v_lshlrev_b64 v[12:13], 13, v[12:13]
	v_lshl_add_u64 v[10:11], v[98:99], 0, v[10:11]
	v_lshl_add_u64 v[14:15], v[98:99], 0, v[12:13]
	global_load_dwordx4 v[10:13], v[10:11], off
	s_nop 0
	global_load_dwordx4 v[14:17], v[14:15], off
	v_or_b32_e32 v18, 16, v96
	v_or_b32_e32 v20, 20, v96
	v_ashrrev_i32_e32 v19, 31, v18
	v_ashrrev_i32_e32 v21, 31, v20
	v_lshlrev_b64 v[18:19], 13, v[18:19]
	v_lshlrev_b64 v[20:21], 13, v[20:21]
	v_lshl_add_u64 v[18:19], v[98:99], 0, v[18:19]
	v_lshl_add_u64 v[22:23], v[98:99], 0, v[20:21]
	global_load_dwordx4 v[18:21], v[18:19], off
	s_nop 0
	global_load_dwordx4 v[22:25], v[22:23], off
	v_or_b32_e32 v26, 24, v96
	v_or_b32_e32 v28, 28, v96
	v_ashrrev_i32_e32 v27, 31, v26
	v_ashrrev_i32_e32 v29, 31, v28
	v_lshlrev_b64 v[26:27], 13, v[26:27]
	v_lshlrev_b64 v[28:29], 13, v[28:29]
	v_lshl_add_u64 v[26:27], v[98:99], 0, v[26:27]
	v_lshl_add_u64 v[30:31], v[98:99], 0, v[28:29]
	global_load_dwordx4 v[26:29], v[26:27], off
	s_nop 0
	global_load_dwordx4 v[30:33], v[30:31], off
	v_or_b32_e32 v34, 32, v96
	v_or_b32_e32 v36, 36, v96
	v_ashrrev_i32_e32 v35, 31, v34
	v_ashrrev_i32_e32 v37, 31, v36
	v_lshlrev_b64 v[34:35], 13, v[34:35]
	v_lshlrev_b64 v[36:37], 13, v[36:37]
	v_lshl_add_u64 v[34:35], v[98:99], 0, v[34:35]
	v_lshl_add_u64 v[38:39], v[98:99], 0, v[36:37]
	global_load_dwordx4 v[34:37], v[34:35], off
	s_nop 0
	global_load_dwordx4 v[38:41], v[38:39], off
	v_or_b32_e32 v42, 40, v96
	v_or_b32_e32 v44, 44, v96
	v_ashrrev_i32_e32 v43, 31, v42
	v_ashrrev_i32_e32 v45, 31, v44
	v_lshlrev_b64 v[42:43], 13, v[42:43]
	v_lshlrev_b64 v[44:45], 13, v[44:45]
	v_lshl_add_u64 v[42:43], v[98:99], 0, v[42:43]
	v_lshl_add_u64 v[46:47], v[98:99], 0, v[44:45]
	v_or_b32_e32 v50, 48, v96
	global_load_dwordx4 v[42:45], v[42:43], off
	s_nop 0
	global_load_dwordx4 v[46:49], v[46:47], off
	v_ashrrev_i32_e32 v51, 31, v50
	v_lshlrev_b64 v[50:51], 13, v[50:51]
	v_or_b32_e32 v54, 52, v96
	v_lshl_add_u64 v[50:51], v[98:99], 0, v[50:51]
	v_ashrrev_i32_e32 v55, 31, v54
	global_load_dwordx4 v[50:53], v[50:51], off
	v_lshlrev_b64 v[54:55], 13, v[54:55]
	v_or_b32_e32 v58, 56, v96
	v_lshl_add_u64 v[54:55], v[98:99], 0, v[54:55]
	v_ashrrev_i32_e32 v59, 31, v58
	global_load_dwordx4 v[54:57], v[54:55], off
	v_lshlrev_b64 v[58:59], 13, v[58:59]
	v_or_b32_e32 v96, 60, v96
	v_lshl_add_u64 v[58:59], v[98:99], 0, v[58:59]
	v_ashrrev_i32_e32 v97, 31, v96
	global_load_dwordx4 v[58:61], v[58:59], off
	v_lshlrev_b64 v[96:97], 13, v[96:97]
	v_lshl_add_u64 v[96:97], v[98:99], 0, v[96:97]
	global_load_dwordx4 v[96:99], v[96:97], off
	v_add_u32_e32 v1, 0x410, v95
	v_ashrrev_i32_e32 v63, 31, v62
	s_waitcnt vmcnt(15)
	ds_write2_b32 v95, v2, v3 offset1:1
	ds_write2_b32 v95, v4, v5 offset0:2 offset1:3
	s_waitcnt vmcnt(14)
	ds_write2_b32 v1, v6, v7 offset1:1
	v_add_u32_e32 v1, 0x418, v95
	ds_write2_b32 v1, v8, v9 offset1:1
	v_add_u32_e32 v1, 0x820, v95
	v_lshl_add_u64 v[8:9], v[62:63], 1, v[76:77]
	s_waitcnt vmcnt(13)
	ds_write2_b32 v1, v10, v11 offset1:1
	v_add_u32_e32 v1, 0x828, v95
	ds_write2_b32 v1, v12, v13 offset1:1
	v_add_u32_e32 v1, 0xc30, v95
	s_waitcnt vmcnt(12)
	ds_write2_b32 v1, v14, v15 offset1:1
	v_add_u32_e32 v1, 0xc38, v95
	ds_write2_b32 v1, v16, v17 offset1:1
	v_add_u32_e32 v1, 0x1040, v95
	s_waitcnt vmcnt(11)
	ds_write2_b32 v1, v18, v19 offset1:1
	v_add_u32_e32 v1, 0x1048, v95
	ds_write2_b32 v1, v20, v21 offset1:1
	v_add_u32_e32 v1, 0x1450, v95
	s_waitcnt vmcnt(10)
	ds_write2_b32 v1, v22, v23 offset1:1
	v_add_u32_e32 v1, 0x1458, v95
	ds_write2_b32 v1, v24, v25 offset1:1
	v_add_u32_e32 v1, 0x1860, v95
	s_waitcnt vmcnt(9)
	ds_write2_b32 v1, v26, v27 offset1:1
	v_add_u32_e32 v1, 0x1868, v95
	ds_write2_b32 v1, v28, v29 offset1:1
	v_add_u32_e32 v1, 0x1c70, v95
	s_waitcnt vmcnt(8)
	ds_write2_b32 v1, v30, v31 offset1:1
	v_add_u32_e32 v1, 0x1c78, v95
	ds_write2_b32 v1, v32, v33 offset1:1
	v_add_u32_e32 v1, 0x2080, v95
	s_waitcnt vmcnt(7)
	ds_write2_b32 v1, v34, v35 offset1:1
	v_add_u32_e32 v1, 0x2088, v95
	ds_write2_b32 v1, v36, v37 offset1:1
	v_add_u32_e32 v1, 0x2490, v95
	s_waitcnt vmcnt(6)
	ds_write2_b32 v1, v38, v39 offset1:1
	v_add_u32_e32 v1, 0x2498, v95
	ds_write2_b32 v1, v40, v41 offset1:1
	v_add_u32_e32 v1, 0x28a0, v95
	s_waitcnt vmcnt(5)
	ds_write2_b32 v1, v42, v43 offset1:1
	v_add_u32_e32 v1, 0x28a8, v95
	ds_write2_b32 v1, v44, v45 offset1:1
	v_add_u32_e32 v1, 0x2cb0, v95
	s_waitcnt vmcnt(4)
	ds_write2_b32 v1, v46, v47 offset1:1
	v_add_u32_e32 v1, 0x2cb8, v95
	ds_write2_b32 v1, v48, v49 offset1:1
	v_add_u32_e32 v1, 0x30c0, v95
	s_waitcnt vmcnt(3)
	ds_write2_b32 v1, v50, v51 offset1:1
	v_add_u32_e32 v1, 0x30c8, v95
	ds_write2_b32 v1, v52, v53 offset1:1
	v_add_u32_e32 v1, 0x34d0, v95
	s_waitcnt vmcnt(2)
	ds_write2_b32 v1, v54, v55 offset1:1
	v_add_u32_e32 v1, 0x34d8, v95
	ds_write2_b32 v1, v56, v57 offset1:1
	v_add_u32_e32 v1, 0x38e0, v95
	s_waitcnt vmcnt(1)
	ds_write2_b32 v1, v58, v59 offset1:1
	v_add_u32_e32 v1, 0x38e8, v95
	ds_write2_b32 v1, v60, v61 offset1:1
	v_add_u32_e32 v1, 0x3cf0, v95
	s_waitcnt vmcnt(0)
	ds_write2_b32 v1, v96, v97 offset1:1
	v_add_u32_e32 v1, 0x3cf8, v95
	ds_write2_b32 v1, v98, v99 offset1:1
	s_waitcnt lgkmcnt(0)
	ds_read2_b32 v[2:3], v114 offset1:65
	s_waitcnt lgkmcnt(0)
	v_cvt_pk_bf16_f32 v2, v2, v3
	ds_read2_b32 v[4:5], v114 offset0:130 offset1:195
	s_waitcnt lgkmcnt(0)
	v_cvt_pk_bf16_f32 v3, v4, v5
	ds_read2_b32 v[4:5], v124 offset0:4 offset1:69
	s_waitcnt lgkmcnt(0)
	v_cvt_pk_bf16_f32 v4, v4, v5
	ds_read2_b32 v[6:7], v124 offset0:134 offset1:199
	s_waitcnt lgkmcnt(0)
	v_cvt_pk_bf16_f32 v5, v6, v7
	v_or_b32_e32 v6, 0, v254
	v_or_b32_e32 v6, v0, v6
	v_ashrrev_i32_e32 v7, 31, v6
	v_lshlrev_b64 v[6:7], 10, v[6:7]
	v_lshl_add_u64 v[6:7], v[8:9], 0, v[6:7]
	ds_read2_b32 v[10:11], v114 offset0:8 offset1:73
	global_store_dwordx4 v[6:7], v[2:5], off
	s_waitcnt lgkmcnt(0)
	s_nop 0
	v_cvt_pk_bf16_f32 v2, v10, v11
	ds_read2_b32 v[4:5], v114 offset0:138 offset1:203
	s_waitcnt lgkmcnt(0)
	v_cvt_pk_bf16_f32 v3, v4, v5
	ds_read2_b32 v[4:5], v124 offset0:12 offset1:77
	s_waitcnt lgkmcnt(0)
	v_cvt_pk_bf16_f32 v4, v4, v5
	ds_read2_b32 v[6:7], v124 offset0:142 offset1:207
	s_waitcnt lgkmcnt(0)
	v_cvt_pk_bf16_f32 v5, v6, v7
	v_or_b32_e32 v6, 4, v254
	v_or_b32_e32 v6, v0, v6
	v_ashrrev_i32_e32 v7, 31, v6
	v_lshlrev_b64 v[6:7], 10, v[6:7]
	v_lshl_add_u64 v[6:7], v[8:9], 0, v[6:7]
	ds_read2_b32 v[10:11], v114 offset0:16 offset1:81
	global_store_dwordx4 v[6:7], v[2:5], off
	s_waitcnt lgkmcnt(0)
	s_nop 0
	v_cvt_pk_bf16_f32 v2, v10, v11
	ds_read2_b32 v[4:5], v114 offset0:146 offset1:211
	s_waitcnt lgkmcnt(0)
	v_cvt_pk_bf16_f32 v3, v4, v5
	ds_read2_b32 v[4:5], v124 offset0:20 offset1:85
	s_waitcnt lgkmcnt(0)
	v_cvt_pk_bf16_f32 v4, v4, v5
	ds_read2_b32 v[6:7], v124 offset0:150 offset1:215
	s_waitcnt lgkmcnt(0)
	v_cvt_pk_bf16_f32 v5, v6, v7
	v_or_b32_e32 v6, 8, v254
	v_or_b32_e32 v6, v0, v6
	v_ashrrev_i32_e32 v7, 31, v6
	v_lshlrev_b64 v[6:7], 10, v[6:7]
	v_lshl_add_u64 v[6:7], v[8:9], 0, v[6:7]
	ds_read2_b32 v[10:11], v114 offset0:24 offset1:89
	global_store_dwordx4 v[6:7], v[2:5], off
	s_waitcnt lgkmcnt(0)
	s_nop 0
	v_cvt_pk_bf16_f32 v2, v10, v11
	ds_read2_b32 v[4:5], v114 offset0:154 offset1:219
	s_waitcnt lgkmcnt(0)
	v_cvt_pk_bf16_f32 v3, v4, v5
	ds_read2_b32 v[4:5], v124 offset0:28 offset1:93
	s_waitcnt lgkmcnt(0)
	v_cvt_pk_bf16_f32 v4, v4, v5
	ds_read2_b32 v[6:7], v124 offset0:158 offset1:223
	s_waitcnt lgkmcnt(0)
	v_cvt_pk_bf16_f32 v5, v6, v7
	v_or_b32_e32 v6, 12, v254
	v_or_b32_e32 v6, v0, v6
	v_ashrrev_i32_e32 v7, 31, v6
	v_lshlrev_b64 v[6:7], 10, v[6:7]
	v_lshl_add_u64 v[6:7], v[8:9], 0, v[6:7]
	ds_read2_b32 v[10:11], v114 offset0:32 offset1:97
	global_store_dwordx4 v[6:7], v[2:5], off
	s_waitcnt lgkmcnt(0)
	s_nop 0
	v_cvt_pk_bf16_f32 v2, v10, v11
	ds_read2_b32 v[4:5], v114 offset0:162 offset1:227
	s_waitcnt lgkmcnt(0)
	v_cvt_pk_bf16_f32 v3, v4, v5
	ds_read2_b32 v[4:5], v124 offset0:36 offset1:101
	s_waitcnt lgkmcnt(0)
	v_cvt_pk_bf16_f32 v4, v4, v5
	ds_read2_b32 v[6:7], v124 offset0:166 offset1:231
	s_waitcnt lgkmcnt(0)
	v_cvt_pk_bf16_f32 v5, v6, v7
	v_or_b32_e32 v6, 32, v254
	v_or_b32_e32 v6, v0, v6
	v_ashrrev_i32_e32 v7, 31, v6
	v_lshlrev_b64 v[6:7], 10, v[6:7]
	v_lshl_add_u64 v[6:7], v[8:9], 0, v[6:7]
	ds_read2_b32 v[10:11], v114 offset0:40 offset1:105
	global_store_dwordx4 v[6:7], v[2:5], off
	s_waitcnt lgkmcnt(0)
	s_nop 0
	v_cvt_pk_bf16_f32 v2, v10, v11
	ds_read2_b32 v[4:5], v114 offset0:170 offset1:235
	s_waitcnt lgkmcnt(0)
	v_cvt_pk_bf16_f32 v3, v4, v5
	ds_read2_b32 v[4:5], v124 offset0:44 offset1:109
	s_waitcnt lgkmcnt(0)
	v_cvt_pk_bf16_f32 v4, v4, v5
	ds_read2_b32 v[6:7], v124 offset0:174 offset1:239
	s_waitcnt lgkmcnt(0)
	v_cvt_pk_bf16_f32 v5, v6, v7
	v_or_b32_e32 v6, 36, v254
	v_or_b32_e32 v6, v0, v6
	v_ashrrev_i32_e32 v7, 31, v6
	v_lshlrev_b64 v[6:7], 10, v[6:7]
	v_lshl_add_u64 v[6:7], v[8:9], 0, v[6:7]
	ds_read2_b32 v[10:11], v114 offset0:48 offset1:113
	global_store_dwordx4 v[6:7], v[2:5], off
	s_waitcnt lgkmcnt(0)
	s_nop 0
	v_cvt_pk_bf16_f32 v2, v10, v11
	ds_read2_b32 v[4:5], v114 offset0:178 offset1:243
	s_waitcnt lgkmcnt(0)
	v_cvt_pk_bf16_f32 v3, v4, v5
	ds_read2_b32 v[4:5], v124 offset0:52 offset1:117
	s_waitcnt lgkmcnt(0)
	v_cvt_pk_bf16_f32 v4, v4, v5
	ds_read2_b32 v[6:7], v124 offset0:182 offset1:247
	s_waitcnt lgkmcnt(0)
	v_cvt_pk_bf16_f32 v5, v6, v7
	v_or_b32_e32 v6, 40, v254
	v_or_b32_e32 v6, v0, v6
	v_ashrrev_i32_e32 v7, 31, v6
	v_lshlrev_b64 v[6:7], 10, v[6:7]
	v_or_b32_e32 v255, 44, v254
	v_or_b32_e32 v0, v0, v255
	v_lshl_add_u64 v[6:7], v[8:9], 0, v[6:7]
	v_ashrrev_i32_e32 v1, 31, v0
	ds_read2_b32 v[10:11], v114 offset0:56 offset1:121
	global_store_dwordx4 v[6:7], v[2:5], off
	v_lshlrev_b64 v[0:1], 10, v[0:1]
	v_lshl_add_u64 v[0:1], v[8:9], 0, v[0:1]
	s_waitcnt lgkmcnt(0)
	v_cvt_pk_bf16_f32 v2, v10, v11
	ds_read2_b32 v[4:5], v114 offset0:186 offset1:251
	s_waitcnt lgkmcnt(0)
	v_cvt_pk_bf16_f32 v3, v4, v5
	ds_read2_b32 v[4:5], v124 offset0:60 offset1:125
	s_waitcnt lgkmcnt(0)
	v_cvt_pk_bf16_f32 v4, v4, v5
	ds_read2_b32 v[6:7], v124 offset0:190 offset1:255
	s_waitcnt lgkmcnt(0)
	v_cvt_pk_bf16_f32 v5, v6, v7
	global_store_dwordx4 v[0:1], v[2:5], off
	s_waitcnt lgkmcnt(0)
	s_or_b64 exec, exec, s[0:1]
	s_and_b64 exec, exec, vcc
	s_cbranch_execz .LBB0_24
.LBB0_138:
	v_ashrrev_i32_e32 v0, 31, v123
	v_lshrrev_b32_e32 v0, 25, v0
	v_add_u32_e32 v0, v123, v0
	v_ashrrev_i32_e32 v1, 7, v0
	v_and_b32_e32 v0, 0x3ffff80, v0
	v_lshlrev_b32_e32 v98, 6, v1
	v_sub_u32_e32 v0, v123, v0
	v_or_b32_e32 v100, v98, v66
	v_lshlrev_b32_e32 v96, 6, v0
	v_or_b32_e32 v4, 4, v100
	v_ashrrev_i32_e32 v97, 31, v96
	v_ashrrev_i32_e32 v101, 31, v100
	v_ashrrev_i32_e32 v5, 31, v4
	v_lshl_add_u64 v[0:1], v[96:97], 2, v[90:91]
	v_lshlrev_b64 v[2:3], 15, v[100:101]
	v_lshlrev_b64 v[4:5], 15, v[4:5]
	v_lshl_add_u64 v[2:3], v[0:1], 0, v[2:3]
	v_lshl_add_u64 v[4:5], v[0:1], 0, v[4:5]
	global_load_dwordx4 v[60:63], v[2:3], off
	global_load_dwordx4 v[56:59], v[4:5], off
	v_or_b32_e32 v2, 8, v100
	v_or_b32_e32 v4, 12, v100
	v_ashrrev_i32_e32 v3, 31, v2
	v_ashrrev_i32_e32 v5, 31, v4
	v_lshlrev_b64 v[2:3], 15, v[2:3]
	v_lshlrev_b64 v[4:5], 15, v[4:5]
	v_lshl_add_u64 v[2:3], v[0:1], 0, v[2:3]
	v_lshl_add_u64 v[4:5], v[0:1], 0, v[4:5]
	global_load_dwordx4 v[52:55], v[2:3], off
	global_load_dwordx4 v[48:51], v[4:5], off
	v_or_b32_e32 v2, 16, v100
	v_or_b32_e32 v4, 20, v100
	v_ashrrev_i32_e32 v3, 31, v2
	v_ashrrev_i32_e32 v5, 31, v4
	v_lshlrev_b64 v[2:3], 15, v[2:3]
	v_lshlrev_b64 v[4:5], 15, v[4:5]
	v_lshl_add_u64 v[2:3], v[0:1], 0, v[2:3]
	v_lshl_add_u64 v[4:5], v[0:1], 0, v[4:5]
	global_load_dwordx4 v[44:47], v[2:3], off
	global_load_dwordx4 v[40:43], v[4:5], off
	v_or_b32_e32 v2, 24, v100
	v_or_b32_e32 v4, 28, v100
	v_ashrrev_i32_e32 v3, 31, v2
	v_ashrrev_i32_e32 v5, 31, v4
	v_lshlrev_b64 v[2:3], 15, v[2:3]
	v_lshlrev_b64 v[4:5], 15, v[4:5]
	v_lshl_add_u64 v[2:3], v[0:1], 0, v[2:3]
	v_lshl_add_u64 v[4:5], v[0:1], 0, v[4:5]
	global_load_dwordx4 v[36:39], v[2:3], off
	global_load_dwordx4 v[32:35], v[4:5], off
	v_or_b32_e32 v2, 32, v100
	v_or_b32_e32 v4, 36, v100
	v_ashrrev_i32_e32 v3, 31, v2
	v_ashrrev_i32_e32 v5, 31, v4
	v_lshlrev_b64 v[2:3], 15, v[2:3]
	v_lshlrev_b64 v[4:5], 15, v[4:5]
	v_lshl_add_u64 v[2:3], v[0:1], 0, v[2:3]
	v_lshl_add_u64 v[4:5], v[0:1], 0, v[4:5]
	global_load_dwordx4 v[28:31], v[2:3], off
	global_load_dwordx4 v[24:27], v[4:5], off
	v_or_b32_e32 v2, 40, v100
	v_or_b32_e32 v4, 44, v100
	v_ashrrev_i32_e32 v3, 31, v2
	v_ashrrev_i32_e32 v5, 31, v4
	v_lshlrev_b64 v[2:3], 15, v[2:3]
	v_lshlrev_b64 v[4:5], 15, v[4:5]
	v_lshl_add_u64 v[2:3], v[0:1], 0, v[2:3]
	v_lshl_add_u64 v[4:5], v[0:1], 0, v[4:5]
	global_load_dwordx4 v[20:23], v[2:3], off
	global_load_dwordx4 v[16:19], v[4:5], off
	v_or_b32_e32 v2, 48, v100
	v_or_b32_e32 v4, 52, v100
	v_ashrrev_i32_e32 v3, 31, v2
	v_ashrrev_i32_e32 v5, 31, v4
	v_lshlrev_b64 v[2:3], 15, v[2:3]
	v_lshlrev_b64 v[4:5], 15, v[4:5]
	v_lshl_add_u64 v[2:3], v[0:1], 0, v[2:3]
	v_lshl_add_u64 v[4:5], v[0:1], 0, v[4:5]
	global_load_dwordx4 v[12:15], v[2:3], off
	global_load_dwordx4 v[8:11], v[4:5], off
	v_or_b32_e32 v2, 56, v100
	v_or_b32_e32 v4, 60, v100
	v_ashrrev_i32_e32 v3, 31, v2
	v_ashrrev_i32_e32 v5, 31, v4
	v_lshlrev_b64 v[2:3], 15, v[2:3]
	v_lshlrev_b64 v[4:5], 15, v[4:5]
	v_lshl_add_u64 v[2:3], v[0:1], 0, v[2:3]
	v_lshl_add_u64 v[0:1], v[0:1], 0, v[4:5]
	global_load_dwordx4 v[4:7], v[2:3], off
	s_nop 0
	global_load_dwordx4 v[0:3], v[0:1], off
	v_cndmask_b32_e64 v97, 0, 1, s[14:15]
	v_cmp_ne_u32_e64 s[0:1], 1, v97
	s_andn2_b64 vcc, exec, s[14:15]
	v_ashrrev_i32_e32 v99, 31, v98
	s_cbranch_vccnz .LBB0_177
	v_readlane_b32 s64, v252, 23
	v_readlane_b32 s76, v252, 35
	v_readlane_b32 s77, v252, 36
	v_readlane_b32 s65, v252, 24
	s_nop 0
	v_lshl_add_u64 v[100:101], v[100:101], 2, s[76:77]
	global_load_dword v100, v[100:101], off
	v_readlane_b32 s66, v252, 25
	v_readlane_b32 s67, v252, 26
	v_readlane_b32 s68, v252, 27
	v_readlane_b32 s69, v252, 28
	v_readlane_b32 s70, v252, 29
	v_readlane_b32 s71, v252, 30
	v_readlane_b32 s72, v252, 31
	v_readlane_b32 s73, v252, 32
	v_readlane_b32 s74, v252, 33
	v_readlane_b32 s75, v252, 34
	v_readlane_b32 s78, v252, 37
	v_readlane_b32 s79, v252, 38
	s_waitcnt vmcnt(0)
	v_pk_mul_f32 v[126:127], v[60:61], v[100:101] op_sel_hi:[1,0]
	v_pk_mul_f32 v[100:101], v[62:63], v[100:101] op_sel_hi:[1,0]
	ds_write2_b32 v95, v100, v101 offset0:2 offset1:3
	v_lshl_add_u64 v[100:101], v[98:99], 0, v[66:67]
	v_lshl_add_u64 v[100:101], v[100:101], 2, s[76:77]
	global_load_dword v100, v[100:101], off offset:16
	ds_write2_b32 v95, v126, v127 offset1:1
	s_cbranch_execnz .LBB0_141

.LBB0_199:
	global_load_dwordx4 v[28:31], v[38:39], off offset:-4096
	global_load_dwordx4 v[24:27], v[38:39], off offset:-3072
	global_load_dwordx4 v[20:23], v[38:39], off offset:-2048
	global_load_dwordx4 v[16:19], v[38:39], off offset:-1024
	global_load_dwordx4 v[12:15], v[38:39], off
	global_load_dwordx4 v[8:11], v[38:39], off offset:1024
	global_load_dwordx4 v[4:7], v[38:39], off offset:2048
	s_waitcnt lgkmcnt(0)
	global_load_dwordx4 v[0:3], v[38:39], off offset:3072
	v_lshl_add_u64 v[44:45], s[84:85], 0, v[40:41]
	v_add_co_u32_e64 v44, s[10:11], s30, v44
	s_waitcnt vmcnt(7)
	v_cvt_pk_bf16_f32 v46, v28, v29
	s_nop 0
	v_addc_co_u32_e64 v45, s[10:11], 0, v45, s[10:11]
	v_cvt_pk_bf16_f32 v47, v30, v31
	global_store_dwordx2 v[44:45], v[46:47], off
	s_waitcnt vmcnt(7)
	v_cvt_pk_bf16_f32 v46, v24, v25
	v_cvt_pk_bf16_f32 v47, v26, v27
	global_store_dwordx2 v[44:45], v[46:47], off offset:512
	s_waitcnt vmcnt(7)
	v_cvt_pk_bf16_f32 v46, v20, v21
	v_cvt_pk_bf16_f32 v47, v22, v23
	global_store_dwordx2 v[44:45], v[46:47], off offset:1024
	s_waitcnt vmcnt(7)
	v_cvt_pk_bf16_f32 v46, v16, v17
	v_cvt_pk_bf16_f32 v47, v18, v19
	global_store_dwordx2 v[44:45], v[46:47], off offset:1536
	s_waitcnt vmcnt(7)
	v_cvt_pk_bf16_f32 v46, v12, v13
	v_cvt_pk_bf16_f32 v47, v14, v15
	global_store_dwordx2 v[44:45], v[46:47], off offset:2048
	s_waitcnt vmcnt(7)
	v_cvt_pk_bf16_f32 v46, v8, v9
	v_cvt_pk_bf16_f32 v47, v10, v11
	global_store_dwordx2 v[44:45], v[46:47], off offset:2560
	s_waitcnt vmcnt(7)
	v_cvt_pk_bf16_f32 v46, v4, v5
	v_cvt_pk_bf16_f32 v47, v6, v7
	global_store_dwordx2 v[44:45], v[46:47], off offset:3072
	s_waitcnt vmcnt(7)
	v_cvt_pk_bf16_f32 v46, v0, v1
	v_cvt_pk_bf16_f32 v47, v2, v3
	ds_read_b128 v[130:133], v54
	ds_read_b128 v[134:137], v54 offset:4096
	ds_read_b128 v[138:141], v55
	ds_read_b128 v[142:145], v55 offset:4096
	ds_read_b128 v[146:149], v56
	ds_read_b128 v[150:153], v56 offset:4096
	ds_read_b128 v[154:157], v57
	ds_read_b128 v[160:163], v57 offset:4096
	ds_read_b128 v[164:167], v54 offset:8192
	ds_read_b128 v[168:171], v54 offset:12288
	ds_read_b128 v[172:175], v55 offset:8192
	ds_read_b128 v[176:179], v55 offset:12288
	ds_read_b128 v[180:183], v56 offset:8192
	ds_read_b128 v[184:187], v56 offset:12288
	ds_read_b128 v[188:191], v57 offset:8192
	ds_read_b128 v[192:195], v57 offset:12288
	ds_read_b128 v[196:199], v54 offset:16384
	ds_read_b128 v[200:203], v54 offset:20480
	ds_read_b128 v[204:207], v55 offset:16384
	ds_read_b128 v[208:211], v55 offset:20480
	ds_read_b128 v[212:215], v56 offset:16384
	ds_read_b128 v[216:219], v56 offset:20480
	ds_read_b128 v[220:223], v57 offset:16384
	s_waitcnt lgkmcnt(14)
	v_pk_fma_f32 v[130:131], v[28:29], v[130:131], 0 op_sel_hi:[0,1,0]
	v_pk_fma_f32 v[132:133], v[28:29], v[132:133], 0 op_sel_hi:[0,1,0]
	v_pk_fma_f32 v[130:131], v[28:29], v[134:135], v[130:131] op_sel:[1,0,0]
	v_pk_fma_f32 v[132:133], v[28:29], v[136:137], v[132:133] op_sel:[1,0,0]
	v_mov_b32_e32 v224, v31
	v_pk_fma_f32 v[130:131], v[30:31], v[164:165], v[130:131] op_sel_hi:[0,1,1]
	v_pk_fma_f32 v[132:133], v[30:31], v[166:167], v[132:133] op_sel_hi:[0,1,1]
	v_pk_fma_f32 v[138:139], v[28:29], v[138:139], 0 op_sel_hi:[0,1,0]
	v_pk_fma_f32 v[140:141], v[28:29], v[140:141], 0 op_sel_hi:[0,1,0]
	v_pk_fma_f32 v[146:147], v[28:29], v[146:147], 0 op_sel_hi:[0,1,0]
	v_pk_fma_f32 v[148:149], v[28:29], v[148:149], 0 op_sel_hi:[0,1,0]
	s_waitcnt lgkmcnt(13)
	v_pk_fma_f32 v[130:131], v[224:225], v[168:169], v[130:131] op_sel_hi:[0,1,1]
	v_pk_fma_f32 v[132:133], v[224:225], v[170:171], v[132:133] op_sel_hi:[0,1,1]
	v_pk_fma_f32 v[154:155], v[28:29], v[154:155], 0 op_sel_hi:[0,1,0]
	v_pk_fma_f32 v[156:157], v[28:29], v[156:157], 0 op_sel_hi:[0,1,0]
	v_pk_fma_f32 v[134:135], v[28:29], v[142:143], v[138:139] op_sel:[1,0,0]
	v_pk_fma_f32 v[136:137], v[28:29], v[144:145], v[140:141] op_sel:[1,0,0]
	v_pk_fma_f32 v[138:139], v[28:29], v[150:151], v[146:147] op_sel:[1,0,0]
	v_pk_fma_f32 v[140:141], v[28:29], v[152:153], v[148:149] op_sel:[1,0,0]
	s_waitcnt lgkmcnt(6)
	v_pk_fma_f32 v[146:147], v[24:25], v[196:197], v[130:131] op_sel_hi:[0,1,1]
	v_pk_fma_f32 v[148:149], v[24:25], v[198:199], v[132:133] op_sel_hi:[0,1,1]
	ds_read_b128 v[130:133], v57 offset:20480
	v_pk_fma_f32 v[142:143], v[28:29], v[160:161], v[154:155] op_sel:[1,0,0]
	v_pk_fma_f32 v[144:145], v[28:29], v[162:163], v[156:157] op_sel:[1,0,0]
	v_pk_fma_f32 v[134:135], v[30:31], v[172:173], v[134:135] op_sel_hi:[0,1,1]
	v_pk_fma_f32 v[136:137], v[30:31], v[174:175], v[136:137] op_sel_hi:[0,1,1]
	v_pk_fma_f32 v[138:139], v[30:31], v[180:181], v[138:139] op_sel_hi:[0,1,1]
	v_pk_fma_f32 v[140:141], v[30:31], v[182:183], v[140:141] op_sel_hi:[0,1,1]
	v_pk_fma_f32 v[142:143], v[30:31], v[188:189], v[142:143] op_sel_hi:[0,1,1]
	v_pk_fma_f32 v[144:145], v[30:31], v[190:191], v[144:145] op_sel_hi:[0,1,1]
	v_pk_fma_f32 v[134:135], v[224:225], v[176:177], v[134:135] op_sel_hi:[0,1,1]
	v_pk_fma_f32 v[136:137], v[224:225], v[178:179], v[136:137] op_sel_hi:[0,1,1]
	v_pk_fma_f32 v[138:139], v[224:225], v[184:185], v[138:139] op_sel_hi:[0,1,1]
	v_pk_fma_f32 v[140:141], v[224:225], v[186:187], v[140:141] op_sel_hi:[0,1,1]
	v_pk_fma_f32 v[142:143], v[224:225], v[192:193], v[142:143] op_sel_hi:[0,1,1]
	v_pk_fma_f32 v[144:145], v[224:225], v[194:195], v[144:145] op_sel_hi:[0,1,1]
	s_waitcnt lgkmcnt(5)
	v_pk_fma_f32 v[134:135], v[24:25], v[204:205], v[134:135] op_sel_hi:[0,1,1]
	v_pk_fma_f32 v[136:137], v[24:25], v[206:207], v[136:137] op_sel_hi:[0,1,1]
	s_waitcnt lgkmcnt(3)
	v_pk_fma_f32 v[138:139], v[24:25], v[212:213], v[138:139] op_sel_hi:[0,1,1]
	v_pk_fma_f32 v[140:141], v[24:25], v[214:215], v[140:141] op_sel_hi:[0,1,1]
	s_waitcnt lgkmcnt(1)
	v_pk_fma_f32 v[142:143], v[24:25], v[220:221], v[142:143] op_sel_hi:[0,1,1]
	v_pk_fma_f32 v[144:145], v[24:25], v[222:223], v[144:145] op_sel_hi:[0,1,1]
	v_pk_fma_f32 v[150:151], v[24:25], v[208:209], v[134:135] op_sel:[1,0,0]
	v_pk_fma_f32 v[152:153], v[24:25], v[210:211], v[136:137] op_sel:[1,0,0]
	v_pk_fma_f32 v[154:155], v[24:25], v[216:217], v[138:139] op_sel:[1,0,0]
	v_pk_fma_f32 v[156:157], v[24:25], v[218:219], v[140:141] op_sel:[1,0,0]
	ds_read_b128 v[134:137], v54 offset:24576
	s_waitcnt lgkmcnt(1)
	v_pk_fma_f32 v[160:161], v[24:25], v[130:131], v[142:143] op_sel:[1,0,0]
	v_pk_fma_f32 v[162:163], v[24:25], v[132:133], v[144:145] op_sel:[1,0,0]
	ds_read_b128 v[130:133], v54 offset:28672
	ds_read_b128 v[138:141], v55 offset:24576
	v_pk_fma_f32 v[146:147], v[24:25], v[200:201], v[146:147] op_sel:[1,0,0]
	v_pk_fma_f32 v[148:149], v[24:25], v[202:203], v[148:149] op_sel:[1,0,0]
	s_waitcnt lgkmcnt(2)
	v_pk_fma_f32 v[164:165], v[26:27], v[134:135], v[146:147] op_sel_hi:[0,1,1]
	v_pk_fma_f32 v[166:167], v[26:27], v[136:137], v[148:149] op_sel_hi:[0,1,1]
	ds_read_b128 v[134:137], v55 offset:28672
	ds_read_b128 v[142:145], v56 offset:24576
	s_waitcnt lgkmcnt(2)
	v_pk_fma_f32 v[150:151], v[26:27], v[138:139], v[150:151] op_sel_hi:[0,1,1]
	v_pk_fma_f32 v[152:153], v[26:27], v[140:141], v[152:153] op_sel_hi:[0,1,1]
	ds_read_b128 v[138:141], v57 offset:24576
	ds_read_b128 v[146:149], v56 offset:28672
	v_mul_f32_e32 v168, v17, v17
	s_waitcnt lgkmcnt(2)
	v_pk_fma_f32 v[154:155], v[26:27], v[142:143], v[154:155] op_sel_hi:[0,1,1]
	v_pk_fma_f32 v[156:157], v[26:27], v[144:145], v[156:157] op_sel_hi:[0,1,1]
	s_waitcnt lgkmcnt(1)
	v_pk_fma_f32 v[138:139], v[26:27], v[138:139], v[160:161] op_sel_hi:[0,1,1]
	v_mov_b32_e32 v160, v27
	ds_read_b128 v[142:145], v57 offset:28672
	v_pk_fma_f32 v[140:141], v[26:27], v[140:141], v[162:163] op_sel_hi:[0,1,1]
	v_pk_fma_f32 v[162:163], v[160:161], v[130:131], v[164:165] op_sel_hi:[0,1,1]
	v_pk_fma_f32 v[164:165], v[160:161], v[132:133], v[166:167] op_sel_hi:[0,1,1]
	ds_read_b128 v[130:133], v54 offset:32768
	v_pk_fma_f32 v[150:151], v[160:161], v[134:135], v[150:151] op_sel_hi:[0,1,1]
	v_pk_fma_f32 v[152:153], v[160:161], v[136:137], v[152:153] op_sel_hi:[0,1,1]
	s_waitcnt lgkmcnt(2)
	v_pk_fma_f32 v[154:155], v[160:161], v[146:147], v[154:155] op_sel_hi:[0,1,1]
	v_pk_fma_f32 v[156:157], v[160:161], v[148:149], v[156:157] op_sel_hi:[0,1,1]
	s_waitcnt lgkmcnt(1)
	v_pk_fma_f32 v[166:167], v[160:161], v[142:143], v[138:139] op_sel_hi:[0,1,1]
	v_pk_fma_f32 v[160:161], v[160:161], v[144:145], v[140:141] op_sel_hi:[0,1,1]
	ds_read_b128 v[134:137], v54 offset:36864
	ds_read_b128 v[138:141], v55 offset:32768
	s_waitcnt lgkmcnt(2)
	v_pk_fma_f32 v[162:163], v[20:21], v[130:131], v[162:163] op_sel_hi:[0,1,1]
	v_pk_fma_f32 v[164:165], v[20:21], v[132:133], v[164:165] op_sel_hi:[0,1,1]
	ds_read_b128 v[130:133], v55 offset:36864
	ds_read_b128 v[142:145], v56 offset:32768
	s_waitcnt lgkmcnt(2)
	v_pk_fma_f32 v[150:151], v[20:21], v[138:139], v[150:151] op_sel_hi:[0,1,1]
	v_pk_fma_f32 v[152:153], v[20:21], v[140:141], v[152:153] op_sel_hi:[0,1,1]
	ds_read_b128 v[138:141], v57 offset:32768
	ds_read_b128 v[146:149], v56 offset:36864
	s_waitcnt lgkmcnt(2)
	v_pk_fma_f32 v[154:155], v[20:21], v[142:143], v[154:155] op_sel_hi:[0,1,1]
	v_pk_fma_f32 v[156:157], v[20:21], v[144:145], v[156:157] op_sel_hi:[0,1,1]
	ds_read_b128 v[142:145], v57 offset:36864
	s_waitcnt lgkmcnt(2)
	v_pk_fma_f32 v[138:139], v[20:21], v[138:139], v[166:167] op_sel_hi:[0,1,1]
	v_pk_fma_f32 v[140:141], v[20:21], v[140:141], v[160:161] op_sel_hi:[0,1,1]
	v_pk_fma_f32 v[150:151], v[20:21], v[130:131], v[150:151] op_sel:[1,0,0]
	v_pk_fma_f32 v[152:153], v[20:21], v[132:133], v[152:153] op_sel:[1,0,0]
	ds_read_b128 v[130:133], v54 offset:40960
	v_pk_fma_f32 v[160:161], v[20:21], v[134:135], v[162:163] op_sel:[1,0,0]
	v_pk_fma_f32 v[162:163], v[20:21], v[136:137], v[164:165] op_sel:[1,0,0]
	s_waitcnt lgkmcnt(1)
	v_pk_fma_f32 v[164:165], v[20:21], v[142:143], v[138:139] op_sel:[1,0,0]
	v_pk_fma_f32 v[166:167], v[20:21], v[144:145], v[140:141] op_sel:[1,0,0]
	ds_read_b128 v[134:137], v54 offset:45056
	ds_read_b128 v[138:141], v55 offset:40960
	s_waitcnt lgkmcnt(2)
	v_pk_fma_f32 v[160:161], v[22:23], v[130:131], v[160:161] op_sel_hi:[0,1,1]
	v_pk_fma_f32 v[162:163], v[22:23], v[132:133], v[162:163] op_sel_hi:[0,1,1]
	ds_read_b128 v[130:133], v55 offset:45056
	ds_read_b128 v[142:145], v56 offset:40960
	v_pk_fma_f32 v[154:155], v[20:21], v[146:147], v[154:155] op_sel:[1,0,0]
	v_pk_fma_f32 v[156:157], v[20:21], v[148:149], v[156:157] op_sel:[1,0,0]
	s_waitcnt lgkmcnt(2)
	v_pk_fma_f32 v[150:151], v[22:23], v[138:139], v[150:151] op_sel_hi:[0,1,1]
	v_pk_fma_f32 v[152:153], v[22:23], v[140:141], v[152:153] op_sel_hi:[0,1,1]
	ds_read_b128 v[138:141], v57 offset:40960
	ds_read_b128 v[146:149], v56 offset:45056
	s_waitcnt lgkmcnt(2)
	v_pk_fma_f32 v[154:155], v[22:23], v[142:143], v[154:155] op_sel_hi:[0,1,1]
	v_pk_fma_f32 v[156:157], v[22:23], v[144:145], v[156:157] op_sel_hi:[0,1,1]
	ds_read_b128 v[142:145], v57 offset:45056
	s_waitcnt lgkmcnt(2)
	v_pk_fma_f32 v[138:139], v[22:23], v[138:139], v[164:165] op_sel_hi:[0,1,1]
	v_mov_b32_e32 v164, v23
	v_pk_fma_f32 v[134:135], v[164:165], v[134:135], v[160:161] op_sel_hi:[0,1,1]
	v_pk_fma_f32 v[136:137], v[164:165], v[136:137], v[162:163] op_sel_hi:[0,1,1]
	s_waitcnt lgkmcnt(1)
	v_pk_fma_f32 v[146:147], v[164:165], v[146:147], v[154:155] op_sel_hi:[0,1,1]
	v_pk_fma_f32 v[148:149], v[164:165], v[148:149], v[156:157] op_sel_hi:[0,1,1]
	v_mov_b32_e32 v154, v28
	v_mov_b32_e32 v156, v29
	v_mov_b32_e32 v160, v30
	v_mov_b32_e32 v162, v31
	ds_read_b128 v[28:31], v54 offset:49152
	v_pk_fma_f32 v[140:141], v[22:23], v[140:141], v[166:167] op_sel_hi:[0,1,1]
	v_pk_fma_f32 v[150:151], v[164:165], v[130:131], v[150:151] op_sel_hi:[0,1,1]
	v_pk_fma_f32 v[152:153], v[164:165], v[132:133], v[152:153] op_sel_hi:[0,1,1]
	s_waitcnt lgkmcnt(1)
	v_pk_fma_f32 v[142:143], v[164:165], v[142:143], v[138:139] op_sel_hi:[0,1,1]
	v_pk_fma_f32 v[144:145], v[164:165], v[144:145], v[140:141] op_sel_hi:[0,1,1]
	v_mov_b32_e32 v155, v24
	v_mov_b32_e32 v157, v25
	v_mov_b32_e32 v161, v26
	v_mov_b32_e32 v163, v27
	ds_read_b128 v[24:27], v54 offset:53248
	ds_read_b128 v[130:133], v55 offset:49152
	s_waitcnt lgkmcnt(2)
	v_pk_fma_f32 v[164:165], v[16:17], v[28:29], v[134:135] op_sel_hi:[0,1,1]
	v_pk_fma_f32 v[166:167], v[16:17], v[30:31], v[136:137] op_sel_hi:[0,1,1]
	ds_read_b128 v[28:31], v55 offset:53248
	ds_read_b128 v[134:137], v56 offset:49152
	v_pk_mul_f32 v[156:157], v[156:157], v[156:157]
	s_waitcnt lgkmcnt(2)
	v_pk_fma_f32 v[150:151], v[16:17], v[130:131], v[150:151] op_sel_hi:[0,1,1]
	v_pk_fma_f32 v[152:153], v[16:17], v[132:133], v[152:153] op_sel_hi:[0,1,1]
	ds_read_b128 v[130:133], v57 offset:49152
	ds_read_b128 v[138:141], v56 offset:53248
	s_waitcnt lgkmcnt(2)
	v_pk_fma_f32 v[146:147], v[16:17], v[134:135], v[146:147] op_sel_hi:[0,1,1]
	v_pk_fma_f32 v[148:149], v[16:17], v[136:137], v[148:149] op_sel_hi:[0,1,1]
	ds_read_b128 v[134:137], v57 offset:53248
	v_pk_fma_f32 v[154:155], v[154:155], v[154:155], v[156:157]
	v_pk_mul_f32 v[156:157], v[162:163], v[162:163]
	v_pk_mul_f32 v[22:23], v[22:23], v[22:23]
	v_pk_fma_f32 v[156:157], v[160:161], v[160:161], v[156:157]
	v_pk_mul_f32 v[20:21], v[20:21], v[20:21]
	s_waitcnt lgkmcnt(2)
	v_pk_fma_f32 v[130:131], v[16:17], v[130:131], v[142:143] op_sel_hi:[0,1,1]
	v_pk_fma_f32 v[132:133], v[16:17], v[132:133], v[144:145] op_sel_hi:[0,1,1]
	v_pk_add_f32 v[154:155], v[154:155], v[156:157]
	v_pk_mov_b32 v[156:157], v[20:21], v[22:23] op_sel:[1,0]
	v_mov_b32_e32 v21, v23
	v_pk_fma_f32 v[142:143], v[16:17], v[24:25], v[164:165] op_sel:[1,0,0]
	v_pk_fma_f32 v[144:145], v[16:17], v[26:27], v[166:167] op_sel:[1,0,0]
	v_pk_fma_f32 v[150:151], v[16:17], v[28:29], v[150:151] op_sel:[1,0,0]
	v_pk_fma_f32 v[152:153], v[16:17], v[30:31], v[152:153] op_sel:[1,0,0]
	s_waitcnt lgkmcnt(1)
	v_pk_fma_f32 v[146:147], v[16:17], v[138:139], v[146:147] op_sel:[1,0,0]
	v_pk_fma_f32 v[148:149], v[16:17], v[140:141], v[148:149] op_sel:[1,0,0]
	ds_read_b128 v[24:27], v54 offset:57344
	s_waitcnt lgkmcnt(1)
	v_pk_fma_f32 v[164:165], v[16:17], v[134:135], v[130:131] op_sel:[1,0,0]
	v_pk_fma_f32 v[166:167], v[16:17], v[136:137], v[132:133] op_sel:[1,0,0]
	v_pk_fma_f32 v[16:17], v[16:17], v[16:17], v[168:169] op_sel_hi:[1,1,0]
	v_mul_f32_e32 v168, v19, v19
	v_pk_add_f32 v[20:21], v[156:157], v[20:21]
	v_pk_fma_f32 v[168:169], v[18:19], v[18:19], v[168:169] op_sel_hi:[1,1,0]
	v_pk_add_f32 v[22:23], v[154:155], v[154:155] op_sel:[0,1] op_sel_hi:[1,0]
	v_pk_add_f32 v[20:21], v[20:21], v[20:21] op_sel:[0,1] op_sel_hi:[1,0]
	v_mul_f32_e32 v23, v12, v12
	v_mul_f32_e32 v21, v13, v13
	v_mul_f32_e32 v17, v14, v14
	v_mul_f32_e32 v169, v15, v15
	v_pk_add_f32 v[20:21], v[22:23], v[20:21]
	v_pk_add_f32 v[16:17], v[16:17], v[168:169]
	v_pk_mul_f32 v[22:23], v[8:9], v[8:9]
	v_pk_add_f32 v[16:17], v[20:21], v[16:17]
	v_pk_mul_f32 v[20:21], v[10:11], v[10:11]
	v_pk_add_f32 v[16:17], v[16:17], v[16:17] op_sel:[0,1] op_sel_hi:[1,0]
	v_pk_mov_b32 v[154:155], v[22:23], v[20:21] op_sel:[1,0]
	v_mov_b32_e32 v23, v21
	v_pk_add_f32 v[20:21], v[154:155], v[22:23]
	v_mul_f32_e32 v17, v0, v0
	v_pk_add_f32 v[20:21], v[20:21], v[20:21] op_sel:[0,1] op_sel_hi:[1,0]
	v_mul_f32_e32 v22, v7, v7
	v_mul_f32_e32 v21, v1, v1
	v_pk_add_f32 v[16:17], v[16:17], v[20:21]
	v_mul_f32_e32 v20, v5, v5
	v_pk_fma_f32 v[20:21], v[4:5], v[4:5], v[20:21] op_sel_hi:[1,1,0]
	v_pk_fma_f32 v[22:23], v[6:7], v[6:7], v[22:23] op_sel_hi:[1,1,0]
	v_mul_f32_e32 v21, v2, v2
	v_mul_f32_e32 v23, v3, v3
	v_pk_add_f32 v[20:21], v[20:21], v[22:23]
	ds_read_b128 v[28:31], v55 offset:57344
	ds_read_b128 v[130:133], v54 offset:61440
	v_pk_add_f32 v[16:17], v[16:17], v[20:21]
	s_waitcnt lgkmcnt(2)
	v_pk_fma_f32 v[142:143], v[18:19], v[24:25], v[142:143] op_sel_hi:[0,1,1]
	v_add_f32_e32 v43, v16, v17
	ds_bpermute_b32 v129, v48, v43
	v_pk_fma_f32 v[144:145], v[18:19], v[26:27], v[144:145] op_sel_hi:[0,1,1]
	ds_read_b128 v[24:27], v55 offset:61440
	s_waitcnt lgkmcnt(3)
	v_pk_fma_f32 v[150:151], v[18:19], v[28:29], v[150:151] op_sel_hi:[0,1,1]
	v_pk_fma_f32 v[152:153], v[18:19], v[30:31], v[152:153] op_sel_hi:[0,1,1]
	s_waitcnt lgkmcnt(1)
	v_add_f32_e32 v43, v43, v129
	ds_read_b128 v[28:31], v56 offset:57344
	ds_read_b128 v[134:137], v56 offset:61440
	ds_read_b128 v[138:141], v57 offset:57344
	ds_bpermute_b32 v129, v49, v43
	ds_read_b128 v[20:23], v57 offset:61440
	s_waitcnt lgkmcnt(4)
	v_pk_fma_f32 v[16:17], v[18:19], v[28:29], v[146:147] op_sel_hi:[0,1,1]
	v_pk_fma_f32 v[28:29], v[18:19], v[30:31], v[148:149] op_sel_hi:[0,1,1]
	s_waitcnt lgkmcnt(2)
	v_pk_fma_f32 v[30:31], v[18:19], v[138:139], v[164:165] op_sel_hi:[0,1,1]
	v_pk_fma_f32 v[138:139], v[18:19], v[140:141], v[166:167] op_sel_hi:[0,1,1]
	s_waitcnt lgkmcnt(1)
	v_add_f32_e32 v18, v43, v129
	v_mov_b32_e32 v140, v19
	ds_bpermute_b32 v19, v50, v18
	v_pk_fma_f32 v[130:131], v[140:141], v[130:131], v[142:143] op_sel_hi:[0,1,1]
	v_pk_fma_f32 v[142:143], v[140:141], v[24:25], v[150:151] op_sel_hi:[0,1,1]
	v_pk_fma_f32 v[134:135], v[140:141], v[134:135], v[16:17] op_sel_hi:[0,1,1]
	v_pk_fma_f32 v[28:29], v[140:141], v[136:137], v[28:29] op_sel_hi:[0,1,1]
	s_waitcnt lgkmcnt(0)
	v_add_f32_e32 v24, v18, v19
	ds_bpermute_b32 v25, v51, v24
	ds_read_b128 v[16:19], v58
	v_pk_fma_f32 v[30:31], v[140:141], v[20:21], v[30:31] op_sel_hi:[0,1,1]
	v_pk_fma_f32 v[136:137], v[140:141], v[22:23], v[138:139] op_sel_hi:[0,1,1]
	ds_read_b128 v[20:23], v59
	v_pk_fma_f32 v[132:133], v[140:141], v[132:133], v[144:145] op_sel_hi:[0,1,1]
	v_pk_fma_f32 v[144:145], v[140:141], v[26:27], v[152:153] op_sel_hi:[0,1,1]
	s_waitcnt lgkmcnt(2)
	v_add_f32_e32 v43, v24, v25
	ds_read_b128 v[24:27], v60
	s_waitcnt lgkmcnt(2)
	v_pk_fma_f32 v[130:131], v[12:13], v[16:17], v[130:131] op_sel_hi:[0,1,1]
	v_pk_fma_f32 v[132:133], v[12:13], v[18:19], v[132:133] op_sel_hi:[0,1,1]
	s_waitcnt lgkmcnt(1)
	v_pk_fma_f32 v[138:139], v[12:13], v[20:21], v[142:143] op_sel_hi:[0,1,1]
	ds_read_b128 v[16:19], v61
	v_pk_fma_f32 v[140:141], v[12:13], v[22:23], v[144:145] op_sel_hi:[0,1,1]
	ds_read_b128 v[20:23], v62
	s_waitcnt lgkmcnt(2)
	v_pk_fma_f32 v[134:135], v[12:13], v[24:25], v[134:135] op_sel_hi:[0,1,1]
	v_pk_fma_f32 v[28:29], v[12:13], v[26:27], v[28:29] op_sel_hi:[0,1,1]
	ds_read_b128 v[24:27], v63
	s_waitcnt lgkmcnt(2)
	v_pk_fma_f32 v[30:31], v[12:13], v[16:17], v[30:31] op_sel_hi:[0,1,1]
	v_pk_fma_f32 v[136:137], v[12:13], v[18:19], v[136:137] op_sel_hi:[0,1,1]
	s_waitcnt lgkmcnt(1)
	v_pk_fma_f32 v[130:131], v[12:13], v[20:21], v[130:131] op_sel:[1,0,0]
	ds_read_b128 v[16:19], v66
	v_pk_fma_f32 v[132:133], v[12:13], v[22:23], v[132:133] op_sel:[1,0,0]
	ds_read_b128 v[20:23], v67
	s_waitcnt lgkmcnt(2)
	v_pk_fma_f32 v[138:139], v[12:13], v[24:25], v[138:139] op_sel:[1,0,0]
	v_pk_fma_f32 v[140:141], v[12:13], v[26:27], v[140:141] op_sel:[1,0,0]
	ds_read_b128 v[24:27], v68
	s_waitcnt lgkmcnt(2)
	v_pk_fma_f32 v[134:135], v[12:13], v[16:17], v[134:135] op_sel:[1,0,0]
	v_pk_fma_f32 v[28:29], v[12:13], v[18:19], v[28:29] op_sel:[1,0,0]
	s_waitcnt lgkmcnt(1)
	v_pk_fma_f32 v[30:31], v[12:13], v[20:21], v[30:31] op_sel:[1,0,0]
	ds_read_b128 v[16:19], v69
	v_pk_fma_f32 v[12:13], v[12:13], v[22:23], v[136:137] op_sel:[1,0,0]
	ds_read_b128 v[20:23], v70
	s_waitcnt lgkmcnt(2)
	v_pk_fma_f32 v[130:131], v[14:15], v[24:25], v[130:131] op_sel_hi:[0,1,1]
	v_pk_fma_f32 v[132:133], v[14:15], v[26:27], v[132:133] op_sel_hi:[0,1,1]
	ds_read_b128 v[24:27], v71
	s_waitcnt lgkmcnt(2)
	v_pk_fma_f32 v[136:137], v[14:15], v[16:17], v[138:139] op_sel_hi:[0,1,1]
	v_pk_fma_f32 v[138:139], v[14:15], v[18:19], v[140:141] op_sel_hi:[0,1,1]
	s_waitcnt lgkmcnt(1)
	v_pk_fma_f32 v[134:135], v[14:15], v[20:21], v[134:135] op_sel_hi:[0,1,1]
	v_pk_fma_f32 v[28:29], v[14:15], v[22:23], v[28:29] op_sel_hi:[0,1,1]
	ds_read_b128 v[16:19], v72
	ds_read_b128 v[20:23], v73
	s_waitcnt lgkmcnt(2)
	v_pk_fma_f32 v[24:25], v[14:15], v[24:25], v[30:31] op_sel_hi:[0,1,1]
	v_mov_b32_e32 v30, v15
	v_pk_fma_f32 v[26:27], v[14:15], v[26:27], v[12:13] op_sel_hi:[0,1,1]
	s_waitcnt lgkmcnt(1)
	v_pk_fma_f32 v[130:131], v[30:31], v[16:17], v[130:131] op_sel_hi:[0,1,1]
	v_pk_fma_f32 v[132:133], v[30:31], v[18:19], v[132:133] op_sel_hi:[0,1,1]
	ds_read_b128 v[12:15], v74
	s_waitcnt lgkmcnt(1)
	v_pk_fma_f32 v[136:137], v[30:31], v[20:21], v[136:137] op_sel_hi:[0,1,1]
	ds_read_b128 v[16:19], v75
	ds_bpermute_b32 v20, v52, v43
	v_pk_fma_f32 v[138:139], v[30:31], v[22:23], v[138:139] op_sel_hi:[0,1,1]
	s_waitcnt lgkmcnt(2)
	v_pk_fma_f32 v[134:135], v[30:31], v[12:13], v[134:135] op_sel_hi:[0,1,1]
	v_pk_fma_f32 v[28:29], v[30:31], v[14:15], v[28:29] op_sel_hi:[0,1,1]
	ds_read_b128 v[12:15], v76
	s_waitcnt lgkmcnt(2)
	v_pk_fma_f32 v[24:25], v[30:31], v[16:17], v[24:25] op_sel_hi:[0,1,1]
	v_pk_fma_f32 v[26:27], v[30:31], v[18:19], v[26:27] op_sel_hi:[0,1,1]
	ds_read_b128 v[16:19], v77
	s_waitcnt lgkmcnt(2)
	v_add_f32_e32 v43, v43, v20
	ds_read_b128 v[20:23], v78
	s_waitcnt lgkmcnt(2)
	v_pk_fma_f32 v[30:31], v[8:9], v[12:13], v[130:131] op_sel_hi:[0,1,1]
	v_pk_fma_f32 v[130:131], v[8:9], v[14:15], v[132:133] op_sel_hi:[0,1,1]
	s_waitcnt lgkmcnt(1)
	v_pk_fma_f32 v[132:133], v[8:9], v[16:17], v[136:137] op_sel_hi:[0,1,1]
	ds_read_b128 v[12:15], v79
	v_pk_fma_f32 v[136:137], v[8:9], v[18:19], v[138:139] op_sel_hi:[0,1,1]
	s_waitcnt lgkmcnt(1)
	v_pk_fma_f32 v[134:135], v[8:9], v[20:21], v[134:135] op_sel_hi:[0,1,1]
	ds_read_b128 v[16:19], v80
	v_pk_fma_f32 v[28:29], v[8:9], v[22:23], v[28:29] op_sel_hi:[0,1,1]
	ds_read_b128 v[20:23], v81
	s_waitcnt lgkmcnt(2)
	v_pk_fma_f32 v[24:25], v[8:9], v[12:13], v[24:25] op_sel_hi:[0,1,1]
	v_pk_fma_f32 v[26:27], v[8:9], v[14:15], v[26:27] op_sel_hi:[0,1,1]
	s_waitcnt lgkmcnt(1)
	v_pk_fma_f32 v[30:31], v[8:9], v[16:17], v[30:31] op_sel:[1,0,0]
	ds_read_b128 v[12:15], v82
	v_pk_fma_f32 v[130:131], v[8:9], v[18:19], v[130:131] op_sel:[1,0,0]
	s_waitcnt lgkmcnt(1)
	v_pk_fma_f32 v[132:133], v[8:9], v[20:21], v[132:133] op_sel:[1,0,0]
	ds_read_b128 v[16:19], v83
	v_pk_fma_f32 v[136:137], v[8:9], v[22:23], v[136:137] op_sel:[1,0,0]
	ds_read_b128 v[20:23], v84
	s_waitcnt lgkmcnt(2)
	v_pk_fma_f32 v[134:135], v[8:9], v[12:13], v[134:135] op_sel:[1,0,0]
	v_pk_fma_f32 v[28:29], v[8:9], v[14:15], v[28:29] op_sel:[1,0,0]
	s_waitcnt lgkmcnt(1)
	v_pk_fma_f32 v[24:25], v[8:9], v[16:17], v[24:25] op_sel:[1,0,0]
	ds_read_b128 v[12:15], v85
	v_pk_fma_f32 v[8:9], v[8:9], v[18:19], v[26:27] op_sel:[1,0,0]
	s_waitcnt lgkmcnt(1)
	v_pk_fma_f32 v[26:27], v[10:11], v[20:21], v[30:31] op_sel_hi:[0,1,1]
	ds_read_b128 v[16:19], v86
	v_pk_fma_f32 v[30:31], v[10:11], v[22:23], v[130:131] op_sel_hi:[0,1,1]
	ds_read_b128 v[20:23], v87
	s_waitcnt lgkmcnt(2)
	v_pk_fma_f32 v[130:131], v[10:11], v[12:13], v[132:133] op_sel_hi:[0,1,1]
	v_pk_fma_f32 v[132:133], v[10:11], v[14:15], v[136:137] op_sel_hi:[0,1,1]
	s_waitcnt lgkmcnt(1)
	v_pk_fma_f32 v[134:135], v[10:11], v[16:17], v[134:135] op_sel_hi:[0,1,1]
	v_pk_fma_f32 v[28:29], v[10:11], v[18:19], v[28:29] op_sel_hi:[0,1,1]
	ds_read_b128 v[12:15], v88
	s_waitcnt lgkmcnt(1)
	v_pk_fma_f32 v[20:21], v[10:11], v[20:21], v[24:25] op_sel_hi:[0,1,1]
	v_pk_fma_f32 v[22:23], v[10:11], v[22:23], v[8:9] op_sel_hi:[0,1,1]
	ds_read_b128 v[16:19], v89
	v_mov_b32_e32 v24, v11
	ds_read_b128 v[8:11], v90
	s_waitcnt lgkmcnt(2)
	v_pk_fma_f32 v[26:27], v[24:25], v[12:13], v[26:27] op_sel_hi:[0,1,1]
	v_pk_fma_f32 v[30:31], v[24:25], v[14:15], v[30:31] op_sel_hi:[0,1,1]
	s_waitcnt lgkmcnt(1)
	v_pk_fma_f32 v[130:131], v[24:25], v[16:17], v[130:131] op_sel_hi:[0,1,1]
	ds_read_b128 v[12:15], v91
	v_pk_fma_f32 v[132:133], v[24:25], v[18:19], v[132:133] op_sel_hi:[0,1,1]
	s_waitcnt lgkmcnt(1)
	v_pk_fma_f32 v[134:135], v[24:25], v[8:9], v[134:135] op_sel_hi:[0,1,1]
	ds_read_b128 v[16:19], v92
	v_pk_fma_f32 v[28:29], v[24:25], v[10:11], v[28:29] op_sel_hi:[0,1,1]
	ds_read_b128 v[8:11], v94
	s_waitcnt lgkmcnt(2)
	v_pk_fma_f32 v[20:21], v[24:25], v[12:13], v[20:21] op_sel_hi:[0,1,1]
	v_pk_fma_f32 v[22:23], v[24:25], v[14:15], v[22:23] op_sel_hi:[0,1,1]
	s_waitcnt lgkmcnt(1)
	v_pk_fma_f32 v[24:25], v[4:5], v[16:17], v[26:27] op_sel_hi:[0,1,1]
	ds_read_b128 v[12:15], v95
	v_pk_fma_f32 v[26:27], v[4:5], v[18:19], v[30:31] op_sel_hi:[0,1,1]
	s_waitcnt lgkmcnt(1)
	v_pk_fma_f32 v[30:31], v[4:5], v[8:9], v[130:131] op_sel_hi:[0,1,1]
	ds_read_b128 v[16:19], v96
	v_pk_fma_f32 v[130:131], v[4:5], v[10:11], v[132:133] op_sel_hi:[0,1,1]
	ds_read_b128 v[8:11], v97
	s_waitcnt lgkmcnt(2)
	v_pk_fma_f32 v[132:133], v[4:5], v[12:13], v[134:135] op_sel_hi:[0,1,1]
	v_pk_fma_f32 v[28:29], v[4:5], v[14:15], v[28:29] op_sel_hi:[0,1,1]
	s_waitcnt lgkmcnt(1)
	v_pk_fma_f32 v[20:21], v[4:5], v[16:17], v[20:21] op_sel_hi:[0,1,1]
	ds_read_b128 v[12:15], v98
	v_pk_fma_f32 v[22:23], v[4:5], v[18:19], v[22:23] op_sel_hi:[0,1,1]
	s_waitcnt lgkmcnt(1)
	v_pk_fma_f32 v[24:25], v[4:5], v[8:9], v[24:25] op_sel:[1,0,0]
	ds_read_b128 v[16:19], v99
	v_pk_fma_f32 v[26:27], v[4:5], v[10:11], v[26:27] op_sel:[1,0,0]
	ds_read_b128 v[8:11], v100
	s_waitcnt lgkmcnt(2)
	v_pk_fma_f32 v[30:31], v[4:5], v[12:13], v[30:31] op_sel:[1,0,0]
	v_pk_fma_f32 v[130:131], v[4:5], v[14:15], v[130:131] op_sel:[1,0,0]
	s_waitcnt lgkmcnt(1)
	v_pk_fma_f32 v[132:133], v[4:5], v[16:17], v[132:133] op_sel:[1,0,0]
	ds_read_b128 v[12:15], v101
	v_pk_fma_f32 v[28:29], v[4:5], v[18:19], v[28:29] op_sel:[1,0,0]
	s_waitcnt lgkmcnt(1)
	v_pk_fma_f32 v[20:21], v[4:5], v[8:9], v[20:21] op_sel:[1,0,0]
	ds_read_b128 v[16:19], v102
	v_pk_fma_f32 v[4:5], v[4:5], v[10:11], v[22:23] op_sel:[1,0,0]
	ds_read_b128 v[8:11], v103
	s_waitcnt lgkmcnt(2)
	v_pk_fma_f32 v[22:23], v[6:7], v[12:13], v[24:25] op_sel_hi:[0,1,1]
	v_pk_fma_f32 v[24:25], v[6:7], v[14:15], v[26:27] op_sel_hi:[0,1,1]
	ds_read_b128 v[12:15], v104
	s_waitcnt lgkmcnt(2)
	v_pk_fma_f32 v[18:19], v[6:7], v[18:19], v[130:131] op_sel_hi:[0,1,1]
	s_waitcnt lgkmcnt(1)
	v_pk_fma_f32 v[26:27], v[6:7], v[8:9], v[132:133] op_sel_hi:[0,1,1]
	v_pk_fma_f32 v[28:29], v[6:7], v[10:11], v[28:29] op_sel_hi:[0,1,1]
	ds_read_b128 v[8:11], v105
	v_mov_b32_e32 v130, v7
	v_pk_fma_f32 v[16:17], v[6:7], v[16:17], v[30:31] op_sel_hi:[0,1,1]
	s_waitcnt lgkmcnt(1)
	v_pk_fma_f32 v[20:21], v[6:7], v[12:13], v[20:21] op_sel_hi:[0,1,1]
	v_pk_fma_f32 v[30:31], v[6:7], v[14:15], v[4:5] op_sel_hi:[0,1,1]
	ds_read_b128 v[12:15], v106
	ds_read_b128 v[4:7], v107
	s_waitcnt lgkmcnt(2)
	v_pk_fma_f32 v[22:23], v[130:131], v[8:9], v[22:23] op_sel_hi:[0,1,1]
	v_pk_fma_f32 v[24:25], v[130:131], v[10:11], v[24:25] op_sel_hi:[0,1,1]
	ds_read_b128 v[8:11], v108
	s_waitcnt lgkmcnt(2)
	v_pk_fma_f32 v[16:17], v[130:131], v[12:13], v[16:17] op_sel_hi:[0,1,1]
	v_pk_fma_f32 v[18:19], v[130:131], v[14:15], v[18:19] op_sel_hi:[0,1,1]
	s_waitcnt lgkmcnt(1)
	v_pk_fma_f32 v[26:27], v[130:131], v[4:5], v[26:27] op_sel_hi:[0,1,1]
	ds_read_b128 v[12:15], v109
	v_pk_fma_f32 v[28:29], v[130:131], v[6:7], v[28:29] op_sel_hi:[0,1,1]
	s_waitcnt lgkmcnt(1)
	v_pk_fma_f32 v[20:21], v[130:131], v[8:9], v[20:21] op_sel_hi:[0,1,1]
	ds_read_b128 v[4:7], v110
	v_pk_fma_f32 v[30:31], v[130:131], v[10:11], v[30:31] op_sel_hi:[0,1,1]
	ds_read_b128 v[8:11], v111
	s_waitcnt lgkmcnt(2)
	v_pk_fma_f32 v[22:23], v[0:1], v[12:13], v[22:23] op_sel_hi:[0,1,1]
	v_pk_fma_f32 v[24:25], v[0:1], v[14:15], v[24:25] op_sel_hi:[0,1,1]
	s_waitcnt lgkmcnt(1)
	v_pk_fma_f32 v[16:17], v[0:1], v[4:5], v[16:17] op_sel_hi:[0,1,1]
	ds_read_b128 v[12:15], v112
	v_pk_fma_f32 v[18:19], v[0:1], v[6:7], v[18:19] op_sel_hi:[0,1,1]
	s_waitcnt lgkmcnt(1)
	v_pk_fma_f32 v[26:27], v[0:1], v[8:9], v[26:27] op_sel_hi:[0,1,1]
	ds_read_b128 v[4:7], v113
	v_pk_fma_f32 v[28:29], v[0:1], v[10:11], v[28:29] op_sel_hi:[0,1,1]
	ds_read_b128 v[8:11], v114
	s_waitcnt lgkmcnt(2)
	v_pk_fma_f32 v[20:21], v[0:1], v[12:13], v[20:21] op_sel_hi:[0,1,1]
	v_pk_fma_f32 v[30:31], v[0:1], v[14:15], v[30:31] op_sel_hi:[0,1,1]
	s_waitcnt lgkmcnt(1)
	v_pk_fma_f32 v[22:23], v[0:1], v[4:5], v[22:23] op_sel:[1,0,0]
	ds_read_b128 v[12:15], v115
	v_pk_fma_f32 v[24:25], v[0:1], v[6:7], v[24:25] op_sel:[1,0,0]
	s_waitcnt lgkmcnt(1)
	v_pk_fma_f32 v[16:17], v[0:1], v[8:9], v[16:17] op_sel:[1,0,0]
	ds_read_b128 v[4:7], v116
	v_pk_fma_f32 v[18:19], v[0:1], v[10:11], v[18:19] op_sel:[1,0,0]
	ds_read_b128 v[8:11], v117
	s_waitcnt lgkmcnt(2)
	v_pk_fma_f32 v[26:27], v[0:1], v[12:13], v[26:27] op_sel:[1,0,0]
	v_pk_fma_f32 v[28:29], v[0:1], v[14:15], v[28:29] op_sel:[1,0,0]
	s_waitcnt lgkmcnt(1)
	v_pk_fma_f32 v[20:21], v[0:1], v[4:5], v[20:21] op_sel:[1,0,0]
	ds_read_b128 v[12:15], v118
	v_pk_fma_f32 v[0:1], v[0:1], v[6:7], v[30:31] op_sel:[1,0,0]
	s_waitcnt lgkmcnt(1)
	v_pk_fma_f32 v[22:23], v[2:3], v[8:9], v[22:23] op_sel_hi:[0,1,1]
	ds_read_b128 v[4:7], v119
	v_pk_fma_f32 v[24:25], v[2:3], v[10:11], v[24:25] op_sel_hi:[0,1,1]
	ds_read_b128 v[8:11], v120
	s_waitcnt lgkmcnt(2)
	v_pk_fma_f32 v[12:13], v[2:3], v[12:13], v[16:17] op_sel_hi:[0,1,1]
	v_pk_fma_f32 v[14:15], v[2:3], v[14:15], v[18:19] op_sel_hi:[0,1,1]
	s_waitcnt lgkmcnt(1)
	v_pk_fma_f32 v[16:17], v[2:3], v[4:5], v[26:27] op_sel_hi:[0,1,1]
	v_pk_fma_f32 v[18:19], v[2:3], v[6:7], v[28:29] op_sel_hi:[0,1,1]
	ds_read_b128 v[4:7], v121
	s_waitcnt lgkmcnt(1)
	v_pk_fma_f32 v[20:21], v[2:3], v[8:9], v[20:21] op_sel_hi:[0,1,1]
	v_pk_fma_f32 v[26:27], v[2:3], v[10:11], v[0:1] op_sel_hi:[0,1,1]
	v_mov_b32_e32 v28, v3
	ds_read_b128 v[0:3], v122
	ds_read_b128 v[8:11], v123
	s_waitcnt lgkmcnt(2)
	v_pk_fma_f32 v[22:23], v[28:29], v[4:5], v[22:23] op_sel_hi:[0,1,1]
	v_pk_fma_f32 v[24:25], v[28:29], v[6:7], v[24:25] op_sel_hi:[0,1,1]
	ds_read_b128 v[4:7], v124
	s_waitcnt lgkmcnt(2)
	v_pk_fma_f32 v[0:1], v[28:29], v[0:1], v[12:13] op_sel_hi:[0,1,1]
	s_waitcnt lgkmcnt(1)
	v_pk_fma_f32 v[8:9], v[28:29], v[8:9], v[16:17] op_sel_hi:[0,1,1]
	v_cndmask_b32_e32 v13, v23, v9, vcc
	ds_bpermute_b32 v13, v53, v13
	v_pk_fma_f32 v[10:11], v[28:29], v[10:11], v[18:19] op_sel_hi:[0,1,1]
	s_waitcnt lgkmcnt(1)
	v_pk_fma_f32 v[4:5], v[28:29], v[4:5], v[20:21] op_sel_hi:[0,1,1]
	v_cndmask_b32_e32 v9, v9, v23, vcc
	v_pk_fma_f32 v[2:3], v[28:29], v[2:3], v[14:15] op_sel_hi:[0,1,1]
	v_cndmask_b32_e32 v12, v8, v22, vcc
	v_cndmask_b32_e32 v8, v22, v8, vcc
	v_cndmask_b32_e32 v14, v24, v10, vcc
	s_waitcnt lgkmcnt(0)
	v_add_f32_e32 v9, v9, v13
	v_cndmask_b32_e32 v13, v0, v4, vcc
	ds_bpermute_b32 v8, v53, v8
	ds_bpermute_b32 v14, v53, v14
	ds_bpermute_b32 v13, v53, v13
	v_pk_fma_f32 v[6:7], v[28:29], v[6:7], v[26:27] op_sel_hi:[0,1,1]
	v_cndmask_b32_e32 v10, v10, v24, vcc
	v_cndmask_b32_e32 v0, v4, v0, vcc
	s_waitcnt lgkmcnt(2)
	v_add_f32_e32 v8, v12, v8
	s_waitcnt lgkmcnt(1)
	v_add_f32_e32 v10, v10, v14
	v_cndmask_b32_e32 v12, v11, v25, vcc
	v_cndmask_b32_e32 v11, v25, v11, vcc
	v_cndmask_b32_e32 v14, v1, v5, vcc
	s_waitcnt lgkmcnt(0)
	v_add_f32_e32 v0, v0, v13
	v_cndmask_b32_e32 v1, v5, v1, vcc
	v_cndmask_b32_e32 v4, v6, v2, vcc
	v_cndmask_b32_e32 v2, v2, v6, vcc
	v_cndmask_b32_e32 v5, v3, v7, vcc
	ds_bpermute_b32 v11, v53, v11
	ds_bpermute_b32 v14, v53, v14
	ds_bpermute_b32 v2, v53, v2
	ds_bpermute_b32 v5, v53, v5
	v_cndmask_b32_e64 v6, v8, v0, s[0:1]
	ds_bpermute_b32 v6, v52, v6
	v_cndmask_b32_e32 v3, v7, v3, vcc
	s_waitcnt lgkmcnt(4)
	v_add_f32_e32 v11, v12, v11
	s_waitcnt lgkmcnt(3)
	v_add_f32_e32 v1, v1, v14
	s_waitcnt lgkmcnt(2)
	v_add_f32_e32 v2, v4, v2
	s_waitcnt lgkmcnt(1)
	v_add_f32_e32 v3, v3, v5
	v_cndmask_b32_e64 v0, v0, v8, s[0:1]
	s_waitcnt lgkmcnt(0)
	v_add_f32_e32 v0, v0, v6
	v_cndmask_b32_e64 v4, v1, v9, s[0:1]
	v_cndmask_b32_e64 v1, v9, v1, s[0:1]
	v_cndmask_b32_e64 v5, v10, v2, s[0:1]
	v_cndmask_b32_e64 v6, v11, v3, s[0:1]
	ds_bpermute_b32 v1, v52, v1
	ds_bpermute_b32 v5, v52, v5
	ds_bpermute_b32 v6, v52, v6
	v_cndmask_b32_e64 v2, v2, v10, s[0:1]
	v_cndmask_b32_e64 v3, v3, v11, s[0:1]
	s_waitcnt lgkmcnt(2)
	v_add_f32_e32 v1, v4, v1
	s_waitcnt lgkmcnt(1)
	v_add_f32_e32 v2, v2, v5
	s_waitcnt lgkmcnt(0)
	v_add_f32_e32 v3, v3, v6
	v_cndmask_b32_e64 v4, v0, v2, s[2:3]
	v_cndmask_b32_e64 v5, v1, v3, s[2:3]
	ds_bpermute_b32 v4, v51, v4
	ds_bpermute_b32 v5, v51, v5
	v_cndmask_b32_e64 v0, v2, v0, s[2:3]
	v_cndmask_b32_e64 v1, v3, v1, s[2:3]
	ds_bpermute_b32 v6, v53, v43
	s_waitcnt lgkmcnt(2)
	v_add_f32_e32 v0, v0, v4
	s_waitcnt lgkmcnt(1)
	v_add_f32_e32 v1, v1, v5
	v_cndmask_b32_e64 v2, v0, v1, s[4:5]
	ds_bpermute_b32 v2, v50, v2
	v_cndmask_b32_e64 v0, v1, v0, s[4:5]
	s_waitcnt lgkmcnt(1)
	v_add_f32_e32 v3, v43, v6
	v_fmamk_f32 v3, v3, 0x3a000000, v125
	v_cmp_gt_f32_e64 s[10:11], s13, v3
	s_waitcnt lgkmcnt(0)
	v_add_f32_e32 v0, v0, v2
	ds_bpermute_b32 v1, v49, v0
	v_mul_f32_e32 v2, 0x4b800000, v3
	v_cndmask_b32_e64 v2, v3, v2, s[10:11]
	v_rsq_f32_e32 v4, v2
	global_store_dwordx2 v[44:45], v[46:47], off offset:3584
	s_waitcnt lgkmcnt(0)
	v_add_f32_e32 v2, v0, v1
	ds_bpermute_b32 v3, v48, v2
	v_mul_f32_e32 v0, 0x45800000, v4
	v_cndmask_b32_e64 v0, v4, v0, s[10:11]
	s_and_saveexec_b64 s[26:27], s[6:7]
	s_cbranch_execz .LBB0_203
	global_load_dword v1, v[32:33], off
	s_waitcnt lgkmcnt(0)
	v_add_f32_e32 v2, v2, v3
	s_waitcnt vmcnt(0)
	v_fmac_f32_e32 v1, v0, v2
	v_cmp_nlt_f32_e64 s[10:11], s31, v1
	s_and_saveexec_b64 s[28:29], s[10:11]
	s_cbranch_execz .LBB0_202
	v_mul_f32_e32 v2, 0x3fb8aa3b, v1
	v_rndne_f32_e32 v3, v2
	v_sub_f32_e32 v4, v2, v3
	v_fma_f32 v2, v1, s34, -v2
	v_fmac_f32_e32 v2, 0x32a5705f, v1
	v_add_f32_e32 v2, v4, v2
	v_cvt_i32_f32_e32 v3, v3
	v_exp_f32_e32 v2, v2
	v_cmp_ngt_f32_e64 s[10:11], s35, v1
	v_ldexp_f32 v2, v2, v3
	s_nop 0
	v_cndmask_b32_e64 v2, 0, v2, s[10:11]
	v_cmp_nlt_f32_e64 s[10:11], s36, v1
	s_nop 1
	v_cndmask_b32_e64 v1, v127, v2, s[10:11]
	v_add_f32_e32 v4, 1.0, v1
	v_add_f32_e32 v2, -1.0, v4
	v_sub_f32_e32 v3, v2, v4
	v_add_f32_e32 v3, 1.0, v3
	v_sub_f32_e32 v2, v1, v2
	v_add_f32_e32 v5, v2, v3
	v_frexp_mant_f32_e32 v6, v4
	v_cvt_f64_f32_e32 v[2:3], v4
	v_frexp_exp_i32_f64_e32 v2, v[2:3]
	v_cmp_gt_f32_e64 s[10:11], s38, v6
	s_nop 1
	v_subbrev_co_u32_e64 v10, s[10:11], 0, v2, s[10:11]
	v_sub_u32_e32 v2, 0, v10
	v_ldexp_f32 v3, v4, v2
	v_add_f32_e32 v4, -1.0, v3
	v_add_f32_e32 v6, 1.0, v3
	v_ldexp_f32 v2, v5, v2
	v_add_f32_e32 v5, 1.0, v4
	v_add_f32_e32 v7, -1.0, v6
	v_sub_f32_e32 v5, v3, v5
	v_sub_f32_e32 v3, v3, v7
	v_add_f32_e32 v5, v2, v5
	v_add_f32_e32 v2, v2, v3
	v_add_f32_e32 v11, v6, v2
	v_rcp_f32_e32 v13, v11
	v_sub_f32_e32 v3, v6, v11
	v_add_f32_e32 v12, v2, v3
	v_add_f32_e32 v3, v4, v5
	v_mul_f32_e32 v15, v3, v13
	v_sub_f32_e32 v2, v4, v3
	v_mul_f32_e32 v4, v11, v15
	v_fma_f32 v6, v15, v11, -v4
	v_fmac_f32_e32 v6, v15, v12
	v_add_f32_e32 v14, v5, v2
	v_add_f32_e32 v2, v4, v6
	v_sub_f32_e32 v5, v3, v2
	v_pk_add_f32 v[8:9], v[2:3], v[4:5] neg_lo:[0,1] neg_hi:[0,1]
	v_mov_b32_e32 v7, v2
	v_pk_add_f32 v[2:3], v[8:9], v[6:7] neg_lo:[0,1] neg_hi:[0,1]
	v_cmp_neq_f32_e64 s[10:11], s37, v1
	v_add_f32_e32 v3, v14, v3
	v_add_f32_e32 v2, v2, v3
	v_add_f32_e32 v3, v5, v2
	v_mul_f32_e32 v14, v13, v3
	v_mul_f32_e32 v4, v11, v14
	v_fma_f32 v6, v14, v11, -v4
	v_fmac_f32_e32 v6, v14, v12
	v_sub_f32_e32 v5, v5, v3
	v_add_f32_e32 v11, v2, v5
	v_add_f32_e32 v2, v4, v6
	v_sub_f32_e32 v5, v3, v2
	v_pk_add_f32 v[8:9], v[2:3], v[4:5] neg_lo:[0,1] neg_hi:[0,1]
	v_mov_b32_e32 v7, v2
	v_pk_add_f32 v[2:3], v[8:9], v[6:7] neg_lo:[0,1] neg_hi:[0,1]
	s_nop 0
	v_add_f32_e32 v3, v11, v3
	v_add_f32_e32 v2, v2, v3
	v_add_f32_e32 v3, v15, v14
	v_add_f32_e32 v2, v5, v2
	v_sub_f32_e32 v4, v3, v15
	v_mul_f32_e32 v2, v13, v2
	v_sub_f32_e32 v4, v14, v4
	v_add_f32_e32 v4, v4, v2
	v_add_f32_e32 v6, v3, v4
	v_mul_f32_e32 v7, v6, v6
	v_fmamk_f32 v2, v7, 0x3e9b6dac, v126
	v_fmaak_f32 v43, v7, v2, 0x3f2aaada
	v_cvt_f32_i32_e32 v2, v10
	v_sub_f32_e32 v3, v6, v3
	v_sub_f32_e32 v3, v4, v3
	v_ldexp_f32 v8, v3, 1
	v_mul_f32_e32 v3, v6, v7
	v_ldexp_f32 v5, v6, 1
	v_pk_mul_f32 v[6:7], v[2:3], v[42:43]
	s_nop 0
	v_fma_f32 v4, v2, s39, -v6
	v_fmac_f32_e32 v4, 0xb102e308, v2
	v_pk_add_f32 v[2:3], v[6:7], v[4:5]
	s_nop 0
	v_sub_f32_e32 v5, v3, v5
	v_sub_f32_e32 v5, v7, v5
	v_add_f32_e32 v9, v8, v5
	v_mov_b32_e32 v8, v6
	v_pk_add_f32 v[6:7], v[2:3], v[6:7] neg_lo:[0,1] neg_hi:[0,1]
	v_pk_add_f32 v[10:11], v[2:3], v[8:9]
	v_mov_b32_e32 v5, v2
	v_mov_b32_e32 v7, v11
	v_pk_add_f32 v[12:13], v[4:5], v[6:7] neg_lo:[0,1] neg_hi:[0,1]
	v_pk_add_f32 v[4:5], v[4:5], v[6:7]
	v_mov_b32_e32 v8, v9
	v_pk_add_f32 v[6:7], v[4:5], v[2:3] op_sel:[1,0] op_sel_hi:[0,1] neg_lo:[0,1] neg_hi:[0,1]
	v_pk_add_f32 v[14:15], v[10:11], v[6:7] op_sel_hi:[1,0] neg_lo:[0,1] neg_hi:[0,1]
	v_mov_b32_e32 v10, v11
	v_mov_b32_e32 v11, v5
	v_pk_mov_b32 v[6:7], v[2:3], v[6:7] op_sel:[1,0]
	v_mov_b32_e32 v9, v2
	v_pk_add_f32 v[6:7], v[10:11], v[6:7] neg_lo:[0,1] neg_hi:[0,1]
	v_mov_b32_e32 v14, v12
	v_pk_add_f32 v[2:3], v[8:9], v[6:7] neg_lo:[0,1] neg_hi:[0,1]
	v_mov_b32_e32 v13, v5
	v_pk_add_f32 v[6:7], v[14:15], v[2:3]
	s_nop 0
	v_pk_add_f32 v[8:9], v[6:7], v[6:7] op_sel:[0,1] op_sel_hi:[1,0]
	s_nop 0
	v_pk_add_f32 v[4:5], v[4:5], v[8:9] op_sel:[1,0] op_sel_hi:[0,1]
	v_mov_b32_e32 v7, v4
	v_pk_add_f32 v[10:11], v[6:7], v[12:13] neg_lo:[0,1] neg_hi:[0,1]
	v_mov_b32_e32 v3, v8
	v_sub_f32_e32 v5, v6, v10
	v_pk_add_f32 v[2:3], v[2:3], v[10:11] neg_lo:[0,1] neg_hi:[0,1]
	v_sub_f32_e32 v5, v12, v5
	v_add_f32_e32 v2, v2, v5
	v_add_f32_e32 v2, v2, v3
	v_add_f32_e32 v2, v4, v2
	v_cndmask_b32_e64 v2, v127, v2, s[10:11]
	v_cmp_lt_f32_e64 s[10:11], |v1|, s40
	s_nop 1
	v_cndmask_b32_e64 v1, v2, v1, s[10:11]

.Lmy_partb4:
	s_waitcnt lgkmcnt(0)
	global_load_dword v253, v[32:33], off
	v_lshl_add_u64 v[8:9], v[38:39], 0, s[20:21]
	v_lshl_add_u64 v[10:11], v[8:9], 0, s[20:21]
	v_lshl_add_u64 v[12:13], v[10:11], 0, s[20:21]
	global_load_dwordx4 v[160:163], v[38:39], off offset:-4096
	global_load_dwordx4 v[164:167], v[8:9], off offset:-4096
	global_load_dwordx4 v[168:171], v[10:11], off offset:-4096
	global_load_dwordx4 v[172:175], v[12:13], off offset:-4096
	global_load_dwordx4 v[176:179], v[38:39], off offset:-3072
	global_load_dwordx4 v[180:183], v[8:9], off offset:-3072
	global_load_dwordx4 v[184:187], v[10:11], off offset:-3072
	global_load_dwordx4 v[188:191], v[12:13], off offset:-3072
	global_load_dwordx4 v[192:195], v[38:39], off offset:-2048
	global_load_dwordx4 v[196:199], v[8:9], off offset:-2048
	global_load_dwordx4 v[200:203], v[10:11], off offset:-2048
	global_load_dwordx4 v[204:207], v[12:13], off offset:-2048
	global_load_dwordx4 v[208:211], v[38:39], off offset:-1024
	global_load_dwordx4 v[212:215], v[8:9], off offset:-1024
	global_load_dwordx4 v[216:219], v[10:11], off offset:-1024
	global_load_dwordx4 v[220:223], v[12:13], off offset:-1024
	global_load_dwordx4 v[224:227], v[38:39], off
	global_load_dwordx4 v[228:231], v[8:9], off
	global_load_dwordx4 v[0:3], v[10:11], off
	global_load_dwordx4 v[4:7], v[12:13], off
	v_lshl_add_u64 v[14:15], s[84:85], 0, v[40:41]
	v_add_co_u32_e64 v14, s[10:11], s30, v14
	s_nop 1
	v_addc_co_u32_e64 v15, s[10:11], 0, v15, s[10:11]
	v_lshl_add_u64 v[16:17], v[14:15], 0, s[22:23]
	v_lshl_add_u64 v[18:19], v[16:17], 0, s[22:23]
	v_lshl_add_u64 v[20:21], v[18:19], 0, s[22:23]
	v_mov_b32_e32 v240, 0
	v_mov_b32_e32 v241, 0
	v_mov_b32_e32 v242, 0
	v_mov_b32_e32 v243, 0
	v_mov_b32_e32 v66, 0
	v_mov_b32_e32 v67, 0
	v_mov_b32_e32 v68, 0
	v_mov_b32_e32 v69, 0
	v_mov_b32_e32 v70, 0
	v_mov_b32_e32 v71, 0
	v_mov_b32_e32 v72, 0
	v_mov_b32_e32 v73, 0
	v_mov_b32_e32 v74, 0
	v_mov_b32_e32 v75, 0
	v_mov_b32_e32 v76, 0
	v_mov_b32_e32 v77, 0
	v_mov_b32_e32 v78, 0
	v_mov_b32_e32 v79, 0
	v_mov_b32_e32 v80, 0
	v_mov_b32_e32 v81, 0
	v_mov_b32_e32 v82, 0
	v_mov_b32_e32 v83, 0
	v_mov_b32_e32 v84, 0
	v_mov_b32_e32 v85, 0
	v_mov_b32_e32 v86, 0
	v_mov_b32_e32 v87, 0
	v_mov_b32_e32 v88, 0
	v_mov_b32_e32 v89, 0
	v_mov_b32_e32 v90, 0
	v_mov_b32_e32 v91, 0
	v_mov_b32_e32 v94, 0
	v_mov_b32_e32 v95, 0
	v_mov_b32_e32 v96, 0
	v_mov_b32_e32 v97, 0
	v_mov_b32_e32 v98, 0
	v_mov_b32_e32 v99, 0
	v_mov_b32_e32 v100, 0
	v_mov_b32_e32 v101, 0
	v_mov_b32_e32 v102, 0
	v_mov_b32_e32 v103, 0
	v_mov_b32_e32 v104, 0
	v_mov_b32_e32 v105, 0
	v_mov_b32_e32 v106, 0
	v_mov_b32_e32 v107, 0
	v_mov_b32_e32 v108, 0
	v_mov_b32_e32 v109, 0
	v_mov_b32_e32 v110, 0
	v_mov_b32_e32 v111, 0
	v_mov_b32_e32 v112, 0
	v_mov_b32_e32 v113, 0
	v_mov_b32_e32 v114, 0
	v_mov_b32_e32 v115, 0
	v_mov_b32_e32 v116, 0
	v_mov_b32_e32 v117, 0
	v_mov_b32_e32 v118, 0
	v_mov_b32_e32 v119, 0
	v_mov_b32_e32 v120, 0
	v_mov_b32_e32 v121, 0
	v_mov_b32_e32 v122, 0
	v_mov_b32_e32 v123, 0
	v_mov_b32_e32 v24, 0
	v_mov_b32_e32 v25, 0
	v_mov_b32_e32 v26, 0
	v_mov_b32_e32 v27, 0
	v_mov_b32_e32 v28, 0
	v_mov_b32_e32 v29, 0
	v_mov_b32_e32 v30, 0
	v_mov_b32_e32 v31, 0
	ds_read_b128 v[130:133], v54
	ds_read_b128 v[134:137], v55
	ds_read_b128 v[138:141], v56
	ds_read_b128 v[142:145], v57
	ds_read_b128 v[146:149], v54 offset:4096
	ds_read_b128 v[150:153], v55 offset:4096
	ds_read_b128 v[154:157], v56 offset:4096
	ds_read_b128 v[44:47], v57 offset:4096
	s_waitcnt vmcnt(19)
	v_cvt_pk_bf16_f32 v244, v160, v161
	v_cvt_pk_bf16_f32 v245, v162, v163
	global_store_dwordx2 v[14:15], v[244:245], off
	v_pk_mul_f32 v[22:23], v[160:161], v[160:161]
	v_pk_fma_f32 v[22:23], v[162:163], v[162:163], v[22:23]
	v_add_f32_e32 v22, v22, v23
	v_add_f32_e32 v240, v240, v22
	s_waitcnt vmcnt(19)
	v_cvt_pk_bf16_f32 v246, v164, v165
	v_cvt_pk_bf16_f32 v247, v166, v167
	global_store_dwordx2 v[16:17], v[246:247], off
	v_pk_mul_f32 v[22:23], v[164:165], v[164:165]
	v_pk_fma_f32 v[22:23], v[166:167], v[166:167], v[22:23]
	v_add_f32_e32 v22, v22, v23
	v_add_f32_e32 v241, v241, v22
	s_waitcnt vmcnt(19)
	v_cvt_pk_bf16_f32 v248, v168, v169
	v_cvt_pk_bf16_f32 v249, v170, v171
	global_store_dwordx2 v[18:19], v[248:249], off
	v_pk_mul_f32 v[22:23], v[168:169], v[168:169]
	v_pk_fma_f32 v[22:23], v[170:171], v[170:171], v[22:23]
	v_add_f32_e32 v22, v22, v23
	v_add_f32_e32 v242, v242, v22
	s_waitcnt vmcnt(19)
	v_cvt_pk_bf16_f32 v232, v172, v173
	v_cvt_pk_bf16_f32 v233, v174, v175
	global_store_dwordx2 v[20:21], v[232:233], off
	v_pk_mul_f32 v[22:23], v[172:173], v[172:173]
	v_pk_fma_f32 v[22:23], v[174:175], v[174:175], v[22:23]
	v_add_f32_e32 v22, v22, v23
	v_add_f32_e32 v243, v243, v22
	s_waitcnt lgkmcnt(7)
	v_pk_fma_f32 v[66:67], v[160:161], v[130:131], v[66:67] op_sel_hi:[0,1,1]
	v_pk_fma_f32 v[82:83], v[164:165], v[130:131], v[82:83] op_sel_hi:[0,1,1]
	v_pk_fma_f32 v[100:101], v[168:169], v[130:131], v[100:101] op_sel_hi:[0,1,1]
	v_pk_fma_f32 v[116:117], v[172:173], v[130:131], v[116:117] op_sel_hi:[0,1,1]
	v_pk_fma_f32 v[68:69], v[160:161], v[132:133], v[68:69] op_sel_hi:[0,1,1]
	v_pk_fma_f32 v[84:85], v[164:165], v[132:133], v[84:85] op_sel_hi:[0,1,1]
	v_pk_fma_f32 v[102:103], v[168:169], v[132:133], v[102:103] op_sel_hi:[0,1,1]
	v_pk_fma_f32 v[118:119], v[172:173], v[132:133], v[118:119] op_sel_hi:[0,1,1]
	ds_read_b128 v[130:133], v54 offset:8192
	s_waitcnt lgkmcnt(7)
	v_pk_fma_f32 v[70:71], v[160:161], v[134:135], v[70:71] op_sel_hi:[0,1,1]
	v_pk_fma_f32 v[86:87], v[164:165], v[134:135], v[86:87] op_sel_hi:[0,1,1]
	v_pk_fma_f32 v[104:105], v[168:169], v[134:135], v[104:105] op_sel_hi:[0,1,1]
	v_pk_fma_f32 v[120:121], v[172:173], v[134:135], v[120:121] op_sel_hi:[0,1,1]
	v_pk_fma_f32 v[72:73], v[160:161], v[136:137], v[72:73] op_sel_hi:[0,1,1]
	v_pk_fma_f32 v[88:89], v[164:165], v[136:137], v[88:89] op_sel_hi:[0,1,1]
	v_pk_fma_f32 v[106:107], v[168:169], v[136:137], v[106:107] op_sel_hi:[0,1,1]
	v_pk_fma_f32 v[122:123], v[172:173], v[136:137], v[122:123] op_sel_hi:[0,1,1]
	ds_read_b128 v[134:137], v55 offset:8192
	s_waitcnt lgkmcnt(7)
	v_pk_fma_f32 v[74:75], v[160:161], v[138:139], v[74:75] op_sel_hi:[0,1,1]
	v_pk_fma_f32 v[90:91], v[164:165], v[138:139], v[90:91] op_sel_hi:[0,1,1]
	v_pk_fma_f32 v[108:109], v[168:169], v[138:139], v[108:109] op_sel_hi:[0,1,1]
	v_pk_fma_f32 v[24:25], v[172:173], v[138:139], v[24:25] op_sel_hi:[0,1,1]
	v_pk_fma_f32 v[76:77], v[160:161], v[140:141], v[76:77] op_sel_hi:[0,1,1]
	v_pk_fma_f32 v[94:95], v[164:165], v[140:141], v[94:95] op_sel_hi:[0,1,1]
	v_pk_fma_f32 v[110:111], v[168:169], v[140:141], v[110:111] op_sel_hi:[0,1,1]
	v_pk_fma_f32 v[26:27], v[172:173], v[140:141], v[26:27] op_sel_hi:[0,1,1]
	ds_read_b128 v[138:141], v56 offset:8192
	s_waitcnt lgkmcnt(7)
	v_pk_fma_f32 v[78:79], v[160:161], v[142:143], v[78:79] op_sel_hi:[0,1,1]
	v_pk_fma_f32 v[96:97], v[164:165], v[142:143], v[96:97] op_sel_hi:[0,1,1]
	v_pk_fma_f32 v[112:113], v[168:169], v[142:143], v[112:113] op_sel_hi:[0,1,1]
	v_pk_fma_f32 v[28:29], v[172:173], v[142:143], v[28:29] op_sel_hi:[0,1,1]
	v_pk_fma_f32 v[80:81], v[160:161], v[144:145], v[80:81] op_sel_hi:[0,1,1]
	v_pk_fma_f32 v[98:99], v[164:165], v[144:145], v[98:99] op_sel_hi:[0,1,1]
	v_pk_fma_f32 v[114:115], v[168:169], v[144:145], v[114:115] op_sel_hi:[0,1,1]
	v_pk_fma_f32 v[30:31], v[172:173], v[144:145], v[30:31] op_sel_hi:[0,1,1]
	ds_read_b128 v[142:145], v57 offset:8192
	s_waitcnt lgkmcnt(7)
	v_pk_fma_f32 v[66:67], v[160:161], v[146:147], v[66:67] op_sel:[1,0,0]
	v_pk_fma_f32 v[82:83], v[164:165], v[146:147], v[82:83] op_sel:[1,0,0]
	v_pk_fma_f32 v[100:101], v[168:169], v[146:147], v[100:101] op_sel:[1,0,0]
	v_pk_fma_f32 v[116:117], v[172:173], v[146:147], v[116:117] op_sel:[1,0,0]
	v_pk_fma_f32 v[68:69], v[160:161], v[148:149], v[68:69] op_sel:[1,0,0]
	v_pk_fma_f32 v[84:85], v[164:165], v[148:149], v[84:85] op_sel:[1,0,0]
	v_pk_fma_f32 v[102:103], v[168:169], v[148:149], v[102:103] op_sel:[1,0,0]
	v_pk_fma_f32 v[118:119], v[172:173], v[148:149], v[118:119] op_sel:[1,0,0]
	ds_read_b128 v[146:149], v54 offset:12288
	s_waitcnt lgkmcnt(7)
	v_pk_fma_f32 v[70:71], v[160:161], v[150:151], v[70:71] op_sel:[1,0,0]
	v_pk_fma_f32 v[86:87], v[164:165], v[150:151], v[86:87] op_sel:[1,0,0]
	v_pk_fma_f32 v[104:105], v[168:169], v[150:151], v[104:105] op_sel:[1,0,0]
	v_pk_fma_f32 v[120:121], v[172:173], v[150:151], v[120:121] op_sel:[1,0,0]
	v_pk_fma_f32 v[72:73], v[160:161], v[152:153], v[72:73] op_sel:[1,0,0]
	v_pk_fma_f32 v[88:89], v[164:165], v[152:153], v[88:89] op_sel:[1,0,0]
	v_pk_fma_f32 v[106:107], v[168:169], v[152:153], v[106:107] op_sel:[1,0,0]
	v_pk_fma_f32 v[122:123], v[172:173], v[152:153], v[122:123] op_sel:[1,0,0]
	ds_read_b128 v[150:153], v55 offset:12288
	s_waitcnt lgkmcnt(7)
	v_pk_fma_f32 v[74:75], v[160:161], v[154:155], v[74:75] op_sel:[1,0,0]
	v_pk_fma_f32 v[90:91], v[164:165], v[154:155], v[90:91] op_sel:[1,0,0]
	v_pk_fma_f32 v[108:109], v[168:169], v[154:155], v[108:109] op_sel:[1,0,0]
	v_pk_fma_f32 v[24:25], v[172:173], v[154:155], v[24:25] op_sel:[1,0,0]
	v_pk_fma_f32 v[76:77], v[160:161], v[156:157], v[76:77] op_sel:[1,0,0]
	v_pk_fma_f32 v[94:95], v[164:165], v[156:157], v[94:95] op_sel:[1,0,0]
	v_pk_fma_f32 v[110:111], v[168:169], v[156:157], v[110:111] op_sel:[1,0,0]
	v_pk_fma_f32 v[26:27], v[172:173], v[156:157], v[26:27] op_sel:[1,0,0]
	ds_read_b128 v[154:157], v56 offset:12288
	s_waitcnt lgkmcnt(7)
	v_pk_fma_f32 v[78:79], v[160:161], v[44:45], v[78:79] op_sel:[1,0,0]
	v_pk_fma_f32 v[96:97], v[164:165], v[44:45], v[96:97] op_sel:[1,0,0]
	v_pk_fma_f32 v[112:113], v[168:169], v[44:45], v[112:113] op_sel:[1,0,0]
	v_pk_fma_f32 v[28:29], v[172:173], v[44:45], v[28:29] op_sel:[1,0,0]
	v_pk_fma_f32 v[80:81], v[160:161], v[46:47], v[80:81] op_sel:[1,0,0]
	v_pk_fma_f32 v[98:99], v[164:165], v[46:47], v[98:99] op_sel:[1,0,0]
	v_pk_fma_f32 v[114:115], v[168:169], v[46:47], v[114:115] op_sel:[1,0,0]
	v_pk_fma_f32 v[30:31], v[172:173], v[46:47], v[30:31] op_sel:[1,0,0]
	ds_read_b128 v[44:47], v57 offset:12288
	s_waitcnt lgkmcnt(7)
	v_pk_fma_f32 v[66:67], v[162:163], v[130:131], v[66:67] op_sel_hi:[0,1,1]
	v_pk_fma_f32 v[82:83], v[166:167], v[130:131], v[82:83] op_sel_hi:[0,1,1]
	v_pk_fma_f32 v[100:101], v[170:171], v[130:131], v[100:101] op_sel_hi:[0,1,1]
	v_pk_fma_f32 v[116:117], v[174:175], v[130:131], v[116:117] op_sel_hi:[0,1,1]
	v_pk_fma_f32 v[68:69], v[162:163], v[132:133], v[68:69] op_sel_hi:[0,1,1]
	v_pk_fma_f32 v[84:85], v[166:167], v[132:133], v[84:85] op_sel_hi:[0,1,1]
	v_pk_fma_f32 v[102:103], v[170:171], v[132:133], v[102:103] op_sel_hi:[0,1,1]
	v_pk_fma_f32 v[118:119], v[174:175], v[132:133], v[118:119] op_sel_hi:[0,1,1]
	ds_read_b128 v[130:133], v54 offset:16384
	s_waitcnt lgkmcnt(7)
	v_pk_fma_f32 v[70:71], v[162:163], v[134:135], v[70:71] op_sel_hi:[0,1,1]
	v_pk_fma_f32 v[86:87], v[166:167], v[134:135], v[86:87] op_sel_hi:[0,1,1]
	v_pk_fma_f32 v[104:105], v[170:171], v[134:135], v[104:105] op_sel_hi:[0,1,1]
	v_pk_fma_f32 v[120:121], v[174:175], v[134:135], v[120:121] op_sel_hi:[0,1,1]
	v_pk_fma_f32 v[72:73], v[162:163], v[136:137], v[72:73] op_sel_hi:[0,1,1]
	v_pk_fma_f32 v[88:89], v[166:167], v[136:137], v[88:89] op_sel_hi:[0,1,1]
	v_pk_fma_f32 v[106:107], v[170:171], v[136:137], v[106:107] op_sel_hi:[0,1,1]
	v_pk_fma_f32 v[122:123], v[174:175], v[136:137], v[122:123] op_sel_hi:[0,1,1]
	ds_read_b128 v[134:137], v55 offset:16384
	s_waitcnt lgkmcnt(7)
	v_pk_fma_f32 v[74:75], v[162:163], v[138:139], v[74:75] op_sel_hi:[0,1,1]
	v_pk_fma_f32 v[90:91], v[166:167], v[138:139], v[90:91] op_sel_hi:[0,1,1]
	v_pk_fma_f32 v[108:109], v[170:171], v[138:139], v[108:109] op_sel_hi:[0,1,1]
	v_pk_fma_f32 v[24:25], v[174:175], v[138:139], v[24:25] op_sel_hi:[0,1,1]
	v_pk_fma_f32 v[76:77], v[162:163], v[140:141], v[76:77] op_sel_hi:[0,1,1]
	v_pk_fma_f32 v[94:95], v[166:167], v[140:141], v[94:95] op_sel_hi:[0,1,1]
	v_pk_fma_f32 v[110:111], v[170:171], v[140:141], v[110:111] op_sel_hi:[0,1,1]
	v_pk_fma_f32 v[26:27], v[174:175], v[140:141], v[26:27] op_sel_hi:[0,1,1]
	ds_read_b128 v[138:141], v56 offset:16384
	s_waitcnt lgkmcnt(7)
	v_pk_fma_f32 v[78:79], v[162:163], v[142:143], v[78:79] op_sel_hi:[0,1,1]
	v_pk_fma_f32 v[96:97], v[166:167], v[142:143], v[96:97] op_sel_hi:[0,1,1]
	v_pk_fma_f32 v[112:113], v[170:171], v[142:143], v[112:113] op_sel_hi:[0,1,1]
	v_pk_fma_f32 v[28:29], v[174:175], v[142:143], v[28:29] op_sel_hi:[0,1,1]
	v_pk_fma_f32 v[80:81], v[162:163], v[144:145], v[80:81] op_sel_hi:[0,1,1]
	v_pk_fma_f32 v[98:99], v[166:167], v[144:145], v[98:99] op_sel_hi:[0,1,1]
	v_pk_fma_f32 v[114:115], v[170:171], v[144:145], v[114:115] op_sel_hi:[0,1,1]
	v_pk_fma_f32 v[30:31], v[174:175], v[144:145], v[30:31] op_sel_hi:[0,1,1]
	ds_read_b128 v[142:145], v57 offset:16384
	s_waitcnt lgkmcnt(7)
	v_pk_fma_f32 v[66:67], v[162:163], v[146:147], v[66:67] op_sel:[1,0,0]
	v_pk_fma_f32 v[82:83], v[166:167], v[146:147], v[82:83] op_sel:[1,0,0]
	v_pk_fma_f32 v[100:101], v[170:171], v[146:147], v[100:101] op_sel:[1,0,0]
	v_pk_fma_f32 v[116:117], v[174:175], v[146:147], v[116:117] op_sel:[1,0,0]
	v_pk_fma_f32 v[68:69], v[162:163], v[148:149], v[68:69] op_sel:[1,0,0]
	v_pk_fma_f32 v[84:85], v[166:167], v[148:149], v[84:85] op_sel:[1,0,0]
	v_pk_fma_f32 v[102:103], v[170:171], v[148:149], v[102:103] op_sel:[1,0,0]
	v_pk_fma_f32 v[118:119], v[174:175], v[148:149], v[118:119] op_sel:[1,0,0]
	ds_read_b128 v[146:149], v54 offset:20480
	s_waitcnt lgkmcnt(7)
	v_pk_fma_f32 v[70:71], v[162:163], v[150:151], v[70:71] op_sel:[1,0,0]
	v_pk_fma_f32 v[86:87], v[166:167], v[150:151], v[86:87] op_sel:[1,0,0]
	v_pk_fma_f32 v[104:105], v[170:171], v[150:151], v[104:105] op_sel:[1,0,0]
	v_pk_fma_f32 v[120:121], v[174:175], v[150:151], v[120:121] op_sel:[1,0,0]
	v_pk_fma_f32 v[72:73], v[162:163], v[152:153], v[72:73] op_sel:[1,0,0]
	v_pk_fma_f32 v[88:89], v[166:167], v[152:153], v[88:89] op_sel:[1,0,0]
	v_pk_fma_f32 v[106:107], v[170:171], v[152:153], v[106:107] op_sel:[1,0,0]
	v_pk_fma_f32 v[122:123], v[174:175], v[152:153], v[122:123] op_sel:[1,0,0]
	ds_read_b128 v[150:153], v55 offset:20480
	s_waitcnt lgkmcnt(7)
	v_pk_fma_f32 v[74:75], v[162:163], v[154:155], v[74:75] op_sel:[1,0,0]
	v_pk_fma_f32 v[90:91], v[166:167], v[154:155], v[90:91] op_sel:[1,0,0]
	v_pk_fma_f32 v[108:109], v[170:171], v[154:155], v[108:109] op_sel:[1,0,0]
	v_pk_fma_f32 v[24:25], v[174:175], v[154:155], v[24:25] op_sel:[1,0,0]
	v_pk_fma_f32 v[76:77], v[162:163], v[156:157], v[76:77] op_sel:[1,0,0]
	v_pk_fma_f32 v[94:95], v[166:167], v[156:157], v[94:95] op_sel:[1,0,0]
	v_pk_fma_f32 v[110:111], v[170:171], v[156:157], v[110:111] op_sel:[1,0,0]
	v_pk_fma_f32 v[26:27], v[174:175], v[156:157], v[26:27] op_sel:[1,0,0]
	ds_read_b128 v[154:157], v56 offset:20480
	s_waitcnt lgkmcnt(7)
	v_pk_fma_f32 v[78:79], v[162:163], v[44:45], v[78:79] op_sel:[1,0,0]
	v_pk_fma_f32 v[96:97], v[166:167], v[44:45], v[96:97] op_sel:[1,0,0]
	v_pk_fma_f32 v[112:113], v[170:171], v[44:45], v[112:113] op_sel:[1,0,0]
	v_pk_fma_f32 v[28:29], v[174:175], v[44:45], v[28:29] op_sel:[1,0,0]
	v_pk_fma_f32 v[80:81], v[162:163], v[46:47], v[80:81] op_sel:[1,0,0]
	v_pk_fma_f32 v[98:99], v[166:167], v[46:47], v[98:99] op_sel:[1,0,0]
	v_pk_fma_f32 v[114:115], v[170:171], v[46:47], v[114:115] op_sel:[1,0,0]
	v_pk_fma_f32 v[30:31], v[174:175], v[46:47], v[30:31] op_sel:[1,0,0]
	ds_read_b128 v[44:47], v57 offset:20480
	global_load_dwordx4 v[160:163], v[38:39], off offset:1024
	global_load_dwordx4 v[164:167], v[8:9], off offset:1024
	global_load_dwordx4 v[168:171], v[10:11], off offset:1024
	global_load_dwordx4 v[172:175], v[12:13], off offset:1024
	s_waitcnt vmcnt(23)
	v_cvt_pk_bf16_f32 v244, v176, v177
	v_cvt_pk_bf16_f32 v245, v178, v179
	global_store_dwordx2 v[14:15], v[244:245], off offset:512
	v_pk_mul_f32 v[22:23], v[176:177], v[176:177]
	v_pk_fma_f32 v[22:23], v[178:179], v[178:179], v[22:23]
	v_add_f32_e32 v22, v22, v23
	v_add_f32_e32 v240, v240, v22
	s_waitcnt vmcnt(23)
	v_cvt_pk_bf16_f32 v246, v180, v181
	v_cvt_pk_bf16_f32 v247, v182, v183
	global_store_dwordx2 v[16:17], v[246:247], off offset:512
	v_pk_mul_f32 v[22:23], v[180:181], v[180:181]
	v_pk_fma_f32 v[22:23], v[182:183], v[182:183], v[22:23]
	v_add_f32_e32 v22, v22, v23
	v_add_f32_e32 v241, v241, v22
	s_waitcnt vmcnt(23)
	v_cvt_pk_bf16_f32 v248, v184, v185
	v_cvt_pk_bf16_f32 v249, v186, v187
	global_store_dwordx2 v[18:19], v[248:249], off offset:512
	v_pk_mul_f32 v[22:23], v[184:185], v[184:185]
	v_pk_fma_f32 v[22:23], v[186:187], v[186:187], v[22:23]
	v_add_f32_e32 v22, v22, v23
	v_add_f32_e32 v242, v242, v22
	s_waitcnt vmcnt(23)
	v_cvt_pk_bf16_f32 v232, v188, v189
	v_cvt_pk_bf16_f32 v233, v190, v191
	global_store_dwordx2 v[20:21], v[232:233], off offset:512
	v_pk_mul_f32 v[22:23], v[188:189], v[188:189]
	v_pk_fma_f32 v[22:23], v[190:191], v[190:191], v[22:23]
	v_add_f32_e32 v22, v22, v23
	v_add_f32_e32 v243, v243, v22
	s_waitcnt lgkmcnt(7)
	v_pk_fma_f32 v[66:67], v[176:177], v[130:131], v[66:67] op_sel_hi:[0,1,1]
	v_pk_fma_f32 v[82:83], v[180:181], v[130:131], v[82:83] op_sel_hi:[0,1,1]
	v_pk_fma_f32 v[100:101], v[184:185], v[130:131], v[100:101] op_sel_hi:[0,1,1]
	v_pk_fma_f32 v[116:117], v[188:189], v[130:131], v[116:117] op_sel_hi:[0,1,1]
	v_pk_fma_f32 v[68:69], v[176:177], v[132:133], v[68:69] op_sel_hi:[0,1,1]
	v_pk_fma_f32 v[84:85], v[180:181], v[132:133], v[84:85] op_sel_hi:[0,1,1]
	v_pk_fma_f32 v[102:103], v[184:185], v[132:133], v[102:103] op_sel_hi:[0,1,1]
	v_pk_fma_f32 v[118:119], v[188:189], v[132:133], v[118:119] op_sel_hi:[0,1,1]
	ds_read_b128 v[130:133], v54 offset:24576
	s_waitcnt lgkmcnt(7)
	v_pk_fma_f32 v[70:71], v[176:177], v[134:135], v[70:71] op_sel_hi:[0,1,1]
	v_pk_fma_f32 v[86:87], v[180:181], v[134:135], v[86:87] op_sel_hi:[0,1,1]
	v_pk_fma_f32 v[104:105], v[184:185], v[134:135], v[104:105] op_sel_hi:[0,1,1]
	v_pk_fma_f32 v[120:121], v[188:189], v[134:135], v[120:121] op_sel_hi:[0,1,1]
	v_pk_fma_f32 v[72:73], v[176:177], v[136:137], v[72:73] op_sel_hi:[0,1,1]
	v_pk_fma_f32 v[88:89], v[180:181], v[136:137], v[88:89] op_sel_hi:[0,1,1]
	v_pk_fma_f32 v[106:107], v[184:185], v[136:137], v[106:107] op_sel_hi:[0,1,1]
	v_pk_fma_f32 v[122:123], v[188:189], v[136:137], v[122:123] op_sel_hi:[0,1,1]
	ds_read_b128 v[134:137], v55 offset:24576
	s_waitcnt lgkmcnt(7)
	v_pk_fma_f32 v[74:75], v[176:177], v[138:139], v[74:75] op_sel_hi:[0,1,1]
	v_pk_fma_f32 v[90:91], v[180:181], v[138:139], v[90:91] op_sel_hi:[0,1,1]
	v_pk_fma_f32 v[108:109], v[184:185], v[138:139], v[108:109] op_sel_hi:[0,1,1]
	v_pk_fma_f32 v[24:25], v[188:189], v[138:139], v[24:25] op_sel_hi:[0,1,1]
	v_pk_fma_f32 v[76:77], v[176:177], v[140:141], v[76:77] op_sel_hi:[0,1,1]
	v_pk_fma_f32 v[94:95], v[180:181], v[140:141], v[94:95] op_sel_hi:[0,1,1]
	v_pk_fma_f32 v[110:111], v[184:185], v[140:141], v[110:111] op_sel_hi:[0,1,1]
	v_pk_fma_f32 v[26:27], v[188:189], v[140:141], v[26:27] op_sel_hi:[0,1,1]
	ds_read_b128 v[138:141], v56 offset:24576
	s_waitcnt lgkmcnt(7)
	v_pk_fma_f32 v[78:79], v[176:177], v[142:143], v[78:79] op_sel_hi:[0,1,1]
	v_pk_fma_f32 v[96:97], v[180:181], v[142:143], v[96:97] op_sel_hi:[0,1,1]
	v_pk_fma_f32 v[112:113], v[184:185], v[142:143], v[112:113] op_sel_hi:[0,1,1]
	v_pk_fma_f32 v[28:29], v[188:189], v[142:143], v[28:29] op_sel_hi:[0,1,1]
	v_pk_fma_f32 v[80:81], v[176:177], v[144:145], v[80:81] op_sel_hi:[0,1,1]
	v_pk_fma_f32 v[98:99], v[180:181], v[144:145], v[98:99] op_sel_hi:[0,1,1]
	v_pk_fma_f32 v[114:115], v[184:185], v[144:145], v[114:115] op_sel_hi:[0,1,1]
	v_pk_fma_f32 v[30:31], v[188:189], v[144:145], v[30:31] op_sel_hi:[0,1,1]
	ds_read_b128 v[142:145], v57 offset:24576
	s_waitcnt lgkmcnt(7)
	v_pk_fma_f32 v[66:67], v[176:177], v[146:147], v[66:67] op_sel:[1,0,0]
	v_pk_fma_f32 v[82:83], v[180:181], v[146:147], v[82:83] op_sel:[1,0,0]
	v_pk_fma_f32 v[100:101], v[184:185], v[146:147], v[100:101] op_sel:[1,0,0]
	v_pk_fma_f32 v[116:117], v[188:189], v[146:147], v[116:117] op_sel:[1,0,0]
	v_pk_fma_f32 v[68:69], v[176:177], v[148:149], v[68:69] op_sel:[1,0,0]
	v_pk_fma_f32 v[84:85], v[180:181], v[148:149], v[84:85] op_sel:[1,0,0]
	v_pk_fma_f32 v[102:103], v[184:185], v[148:149], v[102:103] op_sel:[1,0,0]
	v_pk_fma_f32 v[118:119], v[188:189], v[148:149], v[118:119] op_sel:[1,0,0]
	ds_read_b128 v[146:149], v54 offset:28672
	s_waitcnt lgkmcnt(7)
	v_pk_fma_f32 v[70:71], v[176:177], v[150:151], v[70:71] op_sel:[1,0,0]
	v_pk_fma_f32 v[86:87], v[180:181], v[150:151], v[86:87] op_sel:[1,0,0]
	v_pk_fma_f32 v[104:105], v[184:185], v[150:151], v[104:105] op_sel:[1,0,0]
	v_pk_fma_f32 v[120:121], v[188:189], v[150:151], v[120:121] op_sel:[1,0,0]
	v_pk_fma_f32 v[72:73], v[176:177], v[152:153], v[72:73] op_sel:[1,0,0]
	v_pk_fma_f32 v[88:89], v[180:181], v[152:153], v[88:89] op_sel:[1,0,0]
	v_pk_fma_f32 v[106:107], v[184:185], v[152:153], v[106:107] op_sel:[1,0,0]
	v_pk_fma_f32 v[122:123], v[188:189], v[152:153], v[122:123] op_sel:[1,0,0]
	ds_read_b128 v[150:153], v55 offset:28672
	s_waitcnt lgkmcnt(7)
	v_pk_fma_f32 v[74:75], v[176:177], v[154:155], v[74:75] op_sel:[1,0,0]
	v_pk_fma_f32 v[90:91], v[180:181], v[154:155], v[90:91] op_sel:[1,0,0]
	v_pk_fma_f32 v[108:109], v[184:185], v[154:155], v[108:109] op_sel:[1,0,0]
	v_pk_fma_f32 v[24:25], v[188:189], v[154:155], v[24:25] op_sel:[1,0,0]
	v_pk_fma_f32 v[76:77], v[176:177], v[156:157], v[76:77] op_sel:[1,0,0]
	v_pk_fma_f32 v[94:95], v[180:181], v[156:157], v[94:95] op_sel:[1,0,0]
	v_pk_fma_f32 v[110:111], v[184:185], v[156:157], v[110:111] op_sel:[1,0,0]
	v_pk_fma_f32 v[26:27], v[188:189], v[156:157], v[26:27] op_sel:[1,0,0]
	ds_read_b128 v[154:157], v56 offset:28672
	s_waitcnt lgkmcnt(7)
	v_pk_fma_f32 v[78:79], v[176:177], v[44:45], v[78:79] op_sel:[1,0,0]
	v_pk_fma_f32 v[96:97], v[180:181], v[44:45], v[96:97] op_sel:[1,0,0]
	v_pk_fma_f32 v[112:113], v[184:185], v[44:45], v[112:113] op_sel:[1,0,0]
	v_pk_fma_f32 v[28:29], v[188:189], v[44:45], v[28:29] op_sel:[1,0,0]
	v_pk_fma_f32 v[80:81], v[176:177], v[46:47], v[80:81] op_sel:[1,0,0]
	v_pk_fma_f32 v[98:99], v[180:181], v[46:47], v[98:99] op_sel:[1,0,0]
	v_pk_fma_f32 v[114:115], v[184:185], v[46:47], v[114:115] op_sel:[1,0,0]
	v_pk_fma_f32 v[30:31], v[188:189], v[46:47], v[30:31] op_sel:[1,0,0]
	ds_read_b128 v[44:47], v57 offset:28672
	s_waitcnt lgkmcnt(7)
	v_pk_fma_f32 v[66:67], v[178:179], v[130:131], v[66:67] op_sel_hi:[0,1,1]
	v_pk_fma_f32 v[82:83], v[182:183], v[130:131], v[82:83] op_sel_hi:[0,1,1]
	v_pk_fma_f32 v[100:101], v[186:187], v[130:131], v[100:101] op_sel_hi:[0,1,1]
	v_pk_fma_f32 v[116:117], v[190:191], v[130:131], v[116:117] op_sel_hi:[0,1,1]
	v_pk_fma_f32 v[68:69], v[178:179], v[132:133], v[68:69] op_sel_hi:[0,1,1]
	v_pk_fma_f32 v[84:85], v[182:183], v[132:133], v[84:85] op_sel_hi:[0,1,1]
	v_pk_fma_f32 v[102:103], v[186:187], v[132:133], v[102:103] op_sel_hi:[0,1,1]
	v_pk_fma_f32 v[118:119], v[190:191], v[132:133], v[118:119] op_sel_hi:[0,1,1]
	ds_read_b128 v[130:133], v54 offset:32768
	s_waitcnt lgkmcnt(7)
	v_pk_fma_f32 v[70:71], v[178:179], v[134:135], v[70:71] op_sel_hi:[0,1,1]
	v_pk_fma_f32 v[86:87], v[182:183], v[134:135], v[86:87] op_sel_hi:[0,1,1]
	v_pk_fma_f32 v[104:105], v[186:187], v[134:135], v[104:105] op_sel_hi:[0,1,1]
	v_pk_fma_f32 v[120:121], v[190:191], v[134:135], v[120:121] op_sel_hi:[0,1,1]
	v_pk_fma_f32 v[72:73], v[178:179], v[136:137], v[72:73] op_sel_hi:[0,1,1]
	v_pk_fma_f32 v[88:89], v[182:183], v[136:137], v[88:89] op_sel_hi:[0,1,1]
	v_pk_fma_f32 v[106:107], v[186:187], v[136:137], v[106:107] op_sel_hi:[0,1,1]
	v_pk_fma_f32 v[122:123], v[190:191], v[136:137], v[122:123] op_sel_hi:[0,1,1]
	ds_read_b128 v[134:137], v55 offset:32768
	s_waitcnt lgkmcnt(7)
	v_pk_fma_f32 v[74:75], v[178:179], v[138:139], v[74:75] op_sel_hi:[0,1,1]
	v_pk_fma_f32 v[90:91], v[182:183], v[138:139], v[90:91] op_sel_hi:[0,1,1]
	v_pk_fma_f32 v[108:109], v[186:187], v[138:139], v[108:109] op_sel_hi:[0,1,1]
	v_pk_fma_f32 v[24:25], v[190:191], v[138:139], v[24:25] op_sel_hi:[0,1,1]
	v_pk_fma_f32 v[76:77], v[178:179], v[140:141], v[76:77] op_sel_hi:[0,1,1]
	v_pk_fma_f32 v[94:95], v[182:183], v[140:141], v[94:95] op_sel_hi:[0,1,1]
	v_pk_fma_f32 v[110:111], v[186:187], v[140:141], v[110:111] op_sel_hi:[0,1,1]
	v_pk_fma_f32 v[26:27], v[190:191], v[140:141], v[26:27] op_sel_hi:[0,1,1]
	ds_read_b128 v[138:141], v56 offset:32768
	s_waitcnt lgkmcnt(7)
	v_pk_fma_f32 v[78:79], v[178:179], v[142:143], v[78:79] op_sel_hi:[0,1,1]
	v_pk_fma_f32 v[96:97], v[182:183], v[142:143], v[96:97] op_sel_hi:[0,1,1]
	v_pk_fma_f32 v[112:113], v[186:187], v[142:143], v[112:113] op_sel_hi:[0,1,1]
	v_pk_fma_f32 v[28:29], v[190:191], v[142:143], v[28:29] op_sel_hi:[0,1,1]
	v_pk_fma_f32 v[80:81], v[178:179], v[144:145], v[80:81] op_sel_hi:[0,1,1]
	v_pk_fma_f32 v[98:99], v[182:183], v[144:145], v[98:99] op_sel_hi:[0,1,1]
	v_pk_fma_f32 v[114:115], v[186:187], v[144:145], v[114:115] op_sel_hi:[0,1,1]
	v_pk_fma_f32 v[30:31], v[190:191], v[144:145], v[30:31] op_sel_hi:[0,1,1]
	ds_read_b128 v[142:145], v57 offset:32768
	s_waitcnt lgkmcnt(7)
	v_pk_fma_f32 v[66:67], v[178:179], v[146:147], v[66:67] op_sel:[1,0,0]
	v_pk_fma_f32 v[82:83], v[182:183], v[146:147], v[82:83] op_sel:[1,0,0]
	v_pk_fma_f32 v[100:101], v[186:187], v[146:147], v[100:101] op_sel:[1,0,0]
	v_pk_fma_f32 v[116:117], v[190:191], v[146:147], v[116:117] op_sel:[1,0,0]
	v_pk_fma_f32 v[68:69], v[178:179], v[148:149], v[68:69] op_sel:[1,0,0]
	v_pk_fma_f32 v[84:85], v[182:183], v[148:149], v[84:85] op_sel:[1,0,0]
	v_pk_fma_f32 v[102:103], v[186:187], v[148:149], v[102:103] op_sel:[1,0,0]
	v_pk_fma_f32 v[118:119], v[190:191], v[148:149], v[118:119] op_sel:[1,0,0]
	ds_read_b128 v[146:149], v54 offset:36864
	s_waitcnt lgkmcnt(7)
	v_pk_fma_f32 v[70:71], v[178:179], v[150:151], v[70:71] op_sel:[1,0,0]
	v_pk_fma_f32 v[86:87], v[182:183], v[150:151], v[86:87] op_sel:[1,0,0]
	v_pk_fma_f32 v[104:105], v[186:187], v[150:151], v[104:105] op_sel:[1,0,0]
	v_pk_fma_f32 v[120:121], v[190:191], v[150:151], v[120:121] op_sel:[1,0,0]
	v_pk_fma_f32 v[72:73], v[178:179], v[152:153], v[72:73] op_sel:[1,0,0]
	v_pk_fma_f32 v[88:89], v[182:183], v[152:153], v[88:89] op_sel:[1,0,0]
	v_pk_fma_f32 v[106:107], v[186:187], v[152:153], v[106:107] op_sel:[1,0,0]
	v_pk_fma_f32 v[122:123], v[190:191], v[152:153], v[122:123] op_sel:[1,0,0]
	ds_read_b128 v[150:153], v55 offset:36864
	s_waitcnt lgkmcnt(7)
	v_pk_fma_f32 v[74:75], v[178:179], v[154:155], v[74:75] op_sel:[1,0,0]
	v_pk_fma_f32 v[90:91], v[182:183], v[154:155], v[90:91] op_sel:[1,0,0]
	v_pk_fma_f32 v[108:109], v[186:187], v[154:155], v[108:109] op_sel:[1,0,0]
	v_pk_fma_f32 v[24:25], v[190:191], v[154:155], v[24:25] op_sel:[1,0,0]
	v_pk_fma_f32 v[76:77], v[178:179], v[156:157], v[76:77] op_sel:[1,0,0]
	v_pk_fma_f32 v[94:95], v[182:183], v[156:157], v[94:95] op_sel:[1,0,0]
	v_pk_fma_f32 v[110:111], v[186:187], v[156:157], v[110:111] op_sel:[1,0,0]
	v_pk_fma_f32 v[26:27], v[190:191], v[156:157], v[26:27] op_sel:[1,0,0]
	ds_read_b128 v[154:157], v56 offset:36864
	s_waitcnt lgkmcnt(7)
	v_pk_fma_f32 v[78:79], v[178:179], v[44:45], v[78:79] op_sel:[1,0,0]
	v_pk_fma_f32 v[96:97], v[182:183], v[44:45], v[96:97] op_sel:[1,0,0]
	v_pk_fma_f32 v[112:113], v[186:187], v[44:45], v[112:113] op_sel:[1,0,0]
	v_pk_fma_f32 v[28:29], v[190:191], v[44:45], v[28:29] op_sel:[1,0,0]
	v_pk_fma_f32 v[80:81], v[178:179], v[46:47], v[80:81] op_sel:[1,0,0]
	v_pk_fma_f32 v[98:99], v[182:183], v[46:47], v[98:99] op_sel:[1,0,0]
	v_pk_fma_f32 v[114:115], v[186:187], v[46:47], v[114:115] op_sel:[1,0,0]
	v_pk_fma_f32 v[30:31], v[190:191], v[46:47], v[30:31] op_sel:[1,0,0]
	ds_read_b128 v[44:47], v57 offset:36864
	global_load_dwordx4 v[176:179], v[38:39], off offset:2048
	global_load_dwordx4 v[180:183], v[8:9], off offset:2048
	global_load_dwordx4 v[184:187], v[10:11], off offset:2048
	global_load_dwordx4 v[188:191], v[12:13], off offset:2048
	s_waitcnt vmcnt(27)
	v_cvt_pk_bf16_f32 v244, v192, v193
	v_cvt_pk_bf16_f32 v245, v194, v195
	global_store_dwordx2 v[14:15], v[244:245], off offset:1024
	v_pk_mul_f32 v[22:23], v[192:193], v[192:193]
	v_pk_fma_f32 v[22:23], v[194:195], v[194:195], v[22:23]
	v_add_f32_e32 v22, v22, v23
	v_add_f32_e32 v240, v240, v22
	s_waitcnt vmcnt(27)
	v_cvt_pk_bf16_f32 v246, v196, v197
	v_cvt_pk_bf16_f32 v247, v198, v199
	global_store_dwordx2 v[16:17], v[246:247], off offset:1024
	v_pk_mul_f32 v[22:23], v[196:197], v[196:197]
	v_pk_fma_f32 v[22:23], v[198:199], v[198:199], v[22:23]
	v_add_f32_e32 v22, v22, v23
	v_add_f32_e32 v241, v241, v22
	s_waitcnt vmcnt(27)
	v_cvt_pk_bf16_f32 v248, v200, v201
	v_cvt_pk_bf16_f32 v249, v202, v203
	global_store_dwordx2 v[18:19], v[248:249], off offset:1024
	v_pk_mul_f32 v[22:23], v[200:201], v[200:201]
	v_pk_fma_f32 v[22:23], v[202:203], v[202:203], v[22:23]
	v_add_f32_e32 v22, v22, v23
	v_add_f32_e32 v242, v242, v22
	s_waitcnt vmcnt(27)
	v_cvt_pk_bf16_f32 v232, v204, v205
	v_cvt_pk_bf16_f32 v233, v206, v207
	global_store_dwordx2 v[20:21], v[232:233], off offset:1024
	v_pk_mul_f32 v[22:23], v[204:205], v[204:205]
	v_pk_fma_f32 v[22:23], v[206:207], v[206:207], v[22:23]
	v_add_f32_e32 v22, v22, v23
	v_add_f32_e32 v243, v243, v22
	s_waitcnt lgkmcnt(7)
	v_pk_fma_f32 v[66:67], v[192:193], v[130:131], v[66:67] op_sel_hi:[0,1,1]
	v_pk_fma_f32 v[82:83], v[196:197], v[130:131], v[82:83] op_sel_hi:[0,1,1]
	v_pk_fma_f32 v[100:101], v[200:201], v[130:131], v[100:101] op_sel_hi:[0,1,1]
	v_pk_fma_f32 v[116:117], v[204:205], v[130:131], v[116:117] op_sel_hi:[0,1,1]
	v_pk_fma_f32 v[68:69], v[192:193], v[132:133], v[68:69] op_sel_hi:[0,1,1]
	v_pk_fma_f32 v[84:85], v[196:197], v[132:133], v[84:85] op_sel_hi:[0,1,1]
	v_pk_fma_f32 v[102:103], v[200:201], v[132:133], v[102:103] op_sel_hi:[0,1,1]
	v_pk_fma_f32 v[118:119], v[204:205], v[132:133], v[118:119] op_sel_hi:[0,1,1]
	ds_read_b128 v[130:133], v54 offset:40960
	s_waitcnt lgkmcnt(7)
	v_pk_fma_f32 v[70:71], v[192:193], v[134:135], v[70:71] op_sel_hi:[0,1,1]
	v_pk_fma_f32 v[86:87], v[196:197], v[134:135], v[86:87] op_sel_hi:[0,1,1]
	v_pk_fma_f32 v[104:105], v[200:201], v[134:135], v[104:105] op_sel_hi:[0,1,1]
	v_pk_fma_f32 v[120:121], v[204:205], v[134:135], v[120:121] op_sel_hi:[0,1,1]
	v_pk_fma_f32 v[72:73], v[192:193], v[136:137], v[72:73] op_sel_hi:[0,1,1]
	v_pk_fma_f32 v[88:89], v[196:197], v[136:137], v[88:89] op_sel_hi:[0,1,1]
	v_pk_fma_f32 v[106:107], v[200:201], v[136:137], v[106:107] op_sel_hi:[0,1,1]
	v_pk_fma_f32 v[122:123], v[204:205], v[136:137], v[122:123] op_sel_hi:[0,1,1]
	ds_read_b128 v[134:137], v55 offset:40960
	s_waitcnt lgkmcnt(7)
	v_pk_fma_f32 v[74:75], v[192:193], v[138:139], v[74:75] op_sel_hi:[0,1,1]
	v_pk_fma_f32 v[90:91], v[196:197], v[138:139], v[90:91] op_sel_hi:[0,1,1]
	v_pk_fma_f32 v[108:109], v[200:201], v[138:139], v[108:109] op_sel_hi:[0,1,1]
	v_pk_fma_f32 v[24:25], v[204:205], v[138:139], v[24:25] op_sel_hi:[0,1,1]
	v_pk_fma_f32 v[76:77], v[192:193], v[140:141], v[76:77] op_sel_hi:[0,1,1]
	v_pk_fma_f32 v[94:95], v[196:197], v[140:141], v[94:95] op_sel_hi:[0,1,1]
	v_pk_fma_f32 v[110:111], v[200:201], v[140:141], v[110:111] op_sel_hi:[0,1,1]
	v_pk_fma_f32 v[26:27], v[204:205], v[140:141], v[26:27] op_sel_hi:[0,1,1]
	ds_read_b128 v[138:141], v56 offset:40960
	s_waitcnt lgkmcnt(7)
	v_pk_fma_f32 v[78:79], v[192:193], v[142:143], v[78:79] op_sel_hi:[0,1,1]
	v_pk_fma_f32 v[96:97], v[196:197], v[142:143], v[96:97] op_sel_hi:[0,1,1]
	v_pk_fma_f32 v[112:113], v[200:201], v[142:143], v[112:113] op_sel_hi:[0,1,1]
	v_pk_fma_f32 v[28:29], v[204:205], v[142:143], v[28:29] op_sel_hi:[0,1,1]
	v_pk_fma_f32 v[80:81], v[192:193], v[144:145], v[80:81] op_sel_hi:[0,1,1]
	v_pk_fma_f32 v[98:99], v[196:197], v[144:145], v[98:99] op_sel_hi:[0,1,1]
	v_pk_fma_f32 v[114:115], v[200:201], v[144:145], v[114:115] op_sel_hi:[0,1,1]
	v_pk_fma_f32 v[30:31], v[204:205], v[144:145], v[30:31] op_sel_hi:[0,1,1]
	ds_read_b128 v[142:145], v57 offset:40960
	s_waitcnt lgkmcnt(7)
	v_pk_fma_f32 v[66:67], v[192:193], v[146:147], v[66:67] op_sel:[1,0,0]
	v_pk_fma_f32 v[82:83], v[196:197], v[146:147], v[82:83] op_sel:[1,0,0]
	v_pk_fma_f32 v[100:101], v[200:201], v[146:147], v[100:101] op_sel:[1,0,0]
	v_pk_fma_f32 v[116:117], v[204:205], v[146:147], v[116:117] op_sel:[1,0,0]
	v_pk_fma_f32 v[68:69], v[192:193], v[148:149], v[68:69] op_sel:[1,0,0]
	v_pk_fma_f32 v[84:85], v[196:197], v[148:149], v[84:85] op_sel:[1,0,0]
	v_pk_fma_f32 v[102:103], v[200:201], v[148:149], v[102:103] op_sel:[1,0,0]
	v_pk_fma_f32 v[118:119], v[204:205], v[148:149], v[118:119] op_sel:[1,0,0]
	ds_read_b128 v[146:149], v54 offset:45056
	s_waitcnt lgkmcnt(7)
	v_pk_fma_f32 v[70:71], v[192:193], v[150:151], v[70:71] op_sel:[1,0,0]
	v_pk_fma_f32 v[86:87], v[196:197], v[150:151], v[86:87] op_sel:[1,0,0]
	v_pk_fma_f32 v[104:105], v[200:201], v[150:151], v[104:105] op_sel:[1,0,0]
	v_pk_fma_f32 v[120:121], v[204:205], v[150:151], v[120:121] op_sel:[1,0,0]
	v_pk_fma_f32 v[72:73], v[192:193], v[152:153], v[72:73] op_sel:[1,0,0]
	v_pk_fma_f32 v[88:89], v[196:197], v[152:153], v[88:89] op_sel:[1,0,0]
	v_pk_fma_f32 v[106:107], v[200:201], v[152:153], v[106:107] op_sel:[1,0,0]
	v_pk_fma_f32 v[122:123], v[204:205], v[152:153], v[122:123] op_sel:[1,0,0]
	ds_read_b128 v[150:153], v55 offset:45056
	s_waitcnt lgkmcnt(7)
	v_pk_fma_f32 v[74:75], v[192:193], v[154:155], v[74:75] op_sel:[1,0,0]
	v_pk_fma_f32 v[90:91], v[196:197], v[154:155], v[90:91] op_sel:[1,0,0]
	v_pk_fma_f32 v[108:109], v[200:201], v[154:155], v[108:109] op_sel:[1,0,0]
	v_pk_fma_f32 v[24:25], v[204:205], v[154:155], v[24:25] op_sel:[1,0,0]
	v_pk_fma_f32 v[76:77], v[192:193], v[156:157], v[76:77] op_sel:[1,0,0]
	v_pk_fma_f32 v[94:95], v[196:197], v[156:157], v[94:95] op_sel:[1,0,0]
	v_pk_fma_f32 v[110:111], v[200:201], v[156:157], v[110:111] op_sel:[1,0,0]
	v_pk_fma_f32 v[26:27], v[204:205], v[156:157], v[26:27] op_sel:[1,0,0]
	ds_read_b128 v[154:157], v56 offset:45056
	s_waitcnt lgkmcnt(7)
	v_pk_fma_f32 v[78:79], v[192:193], v[44:45], v[78:79] op_sel:[1,0,0]
	v_pk_fma_f32 v[96:97], v[196:197], v[44:45], v[96:97] op_sel:[1,0,0]
	v_pk_fma_f32 v[112:113], v[200:201], v[44:45], v[112:113] op_sel:[1,0,0]
	v_pk_fma_f32 v[28:29], v[204:205], v[44:45], v[28:29] op_sel:[1,0,0]
	v_pk_fma_f32 v[80:81], v[192:193], v[46:47], v[80:81] op_sel:[1,0,0]
	v_pk_fma_f32 v[98:99], v[196:197], v[46:47], v[98:99] op_sel:[1,0,0]
	v_pk_fma_f32 v[114:115], v[200:201], v[46:47], v[114:115] op_sel:[1,0,0]
	v_pk_fma_f32 v[30:31], v[204:205], v[46:47], v[30:31] op_sel:[1,0,0]
	ds_read_b128 v[44:47], v57 offset:45056
	s_waitcnt lgkmcnt(7)
	v_pk_fma_f32 v[66:67], v[194:195], v[130:131], v[66:67] op_sel_hi:[0,1,1]
	v_pk_fma_f32 v[82:83], v[198:199], v[130:131], v[82:83] op_sel_hi:[0,1,1]
	v_pk_fma_f32 v[100:101], v[202:203], v[130:131], v[100:101] op_sel_hi:[0,1,1]
	v_pk_fma_f32 v[116:117], v[206:207], v[130:131], v[116:117] op_sel_hi:[0,1,1]
	v_pk_fma_f32 v[68:69], v[194:195], v[132:133], v[68:69] op_sel_hi:[0,1,1]
	v_pk_fma_f32 v[84:85], v[198:199], v[132:133], v[84:85] op_sel_hi:[0,1,1]
	v_pk_fma_f32 v[102:103], v[202:203], v[132:133], v[102:103] op_sel_hi:[0,1,1]
	v_pk_fma_f32 v[118:119], v[206:207], v[132:133], v[118:119] op_sel_hi:[0,1,1]
	ds_read_b128 v[130:133], v54 offset:49152
	s_waitcnt lgkmcnt(7)
	v_pk_fma_f32 v[70:71], v[194:195], v[134:135], v[70:71] op_sel_hi:[0,1,1]
	v_pk_fma_f32 v[86:87], v[198:199], v[134:135], v[86:87] op_sel_hi:[0,1,1]
	v_pk_fma_f32 v[104:105], v[202:203], v[134:135], v[104:105] op_sel_hi:[0,1,1]
	v_pk_fma_f32 v[120:121], v[206:207], v[134:135], v[120:121] op_sel_hi:[0,1,1]
	v_pk_fma_f32 v[72:73], v[194:195], v[136:137], v[72:73] op_sel_hi:[0,1,1]
	v_pk_fma_f32 v[88:89], v[198:199], v[136:137], v[88:89] op_sel_hi:[0,1,1]
	v_pk_fma_f32 v[106:107], v[202:203], v[136:137], v[106:107] op_sel_hi:[0,1,1]
	v_pk_fma_f32 v[122:123], v[206:207], v[136:137], v[122:123] op_sel_hi:[0,1,1]
	ds_read_b128 v[134:137], v55 offset:49152
	s_waitcnt lgkmcnt(7)
	v_pk_fma_f32 v[74:75], v[194:195], v[138:139], v[74:75] op_sel_hi:[0,1,1]
	v_pk_fma_f32 v[90:91], v[198:199], v[138:139], v[90:91] op_sel_hi:[0,1,1]
	v_pk_fma_f32 v[108:109], v[202:203], v[138:139], v[108:109] op_sel_hi:[0,1,1]
	v_pk_fma_f32 v[24:25], v[206:207], v[138:139], v[24:25] op_sel_hi:[0,1,1]
	v_pk_fma_f32 v[76:77], v[194:195], v[140:141], v[76:77] op_sel_hi:[0,1,1]
	v_pk_fma_f32 v[94:95], v[198:199], v[140:141], v[94:95] op_sel_hi:[0,1,1]
	v_pk_fma_f32 v[110:111], v[202:203], v[140:141], v[110:111] op_sel_hi:[0,1,1]
	v_pk_fma_f32 v[26:27], v[206:207], v[140:141], v[26:27] op_sel_hi:[0,1,1]
	ds_read_b128 v[138:141], v56 offset:49152
	s_waitcnt lgkmcnt(7)
	v_pk_fma_f32 v[78:79], v[194:195], v[142:143], v[78:79] op_sel_hi:[0,1,1]
	v_pk_fma_f32 v[96:97], v[198:199], v[142:143], v[96:97] op_sel_hi:[0,1,1]
	v_pk_fma_f32 v[112:113], v[202:203], v[142:143], v[112:113] op_sel_hi:[0,1,1]
	v_pk_fma_f32 v[28:29], v[206:207], v[142:143], v[28:29] op_sel_hi:[0,1,1]
	v_pk_fma_f32 v[80:81], v[194:195], v[144:145], v[80:81] op_sel_hi:[0,1,1]
	v_pk_fma_f32 v[98:99], v[198:199], v[144:145], v[98:99] op_sel_hi:[0,1,1]
	v_pk_fma_f32 v[114:115], v[202:203], v[144:145], v[114:115] op_sel_hi:[0,1,1]
	v_pk_fma_f32 v[30:31], v[206:207], v[144:145], v[30:31] op_sel_hi:[0,1,1]
	ds_read_b128 v[142:145], v57 offset:49152
	s_waitcnt lgkmcnt(7)
	v_pk_fma_f32 v[66:67], v[194:195], v[146:147], v[66:67] op_sel:[1,0,0]
	v_pk_fma_f32 v[82:83], v[198:199], v[146:147], v[82:83] op_sel:[1,0,0]
	v_pk_fma_f32 v[100:101], v[202:203], v[146:147], v[100:101] op_sel:[1,0,0]
	v_pk_fma_f32 v[116:117], v[206:207], v[146:147], v[116:117] op_sel:[1,0,0]
	v_pk_fma_f32 v[68:69], v[194:195], v[148:149], v[68:69] op_sel:[1,0,0]
	v_pk_fma_f32 v[84:85], v[198:199], v[148:149], v[84:85] op_sel:[1,0,0]
	v_pk_fma_f32 v[102:103], v[202:203], v[148:149], v[102:103] op_sel:[1,0,0]
	v_pk_fma_f32 v[118:119], v[206:207], v[148:149], v[118:119] op_sel:[1,0,0]
	ds_read_b128 v[146:149], v54 offset:53248
	s_waitcnt lgkmcnt(7)
	v_pk_fma_f32 v[70:71], v[194:195], v[150:151], v[70:71] op_sel:[1,0,0]
	v_pk_fma_f32 v[86:87], v[198:199], v[150:151], v[86:87] op_sel:[1,0,0]
	v_pk_fma_f32 v[104:105], v[202:203], v[150:151], v[104:105] op_sel:[1,0,0]
	v_pk_fma_f32 v[120:121], v[206:207], v[150:151], v[120:121] op_sel:[1,0,0]
	v_pk_fma_f32 v[72:73], v[194:195], v[152:153], v[72:73] op_sel:[1,0,0]
	v_pk_fma_f32 v[88:89], v[198:199], v[152:153], v[88:89] op_sel:[1,0,0]
	v_pk_fma_f32 v[106:107], v[202:203], v[152:153], v[106:107] op_sel:[1,0,0]
	v_pk_fma_f32 v[122:123], v[206:207], v[152:153], v[122:123] op_sel:[1,0,0]
	ds_read_b128 v[150:153], v55 offset:53248
	s_waitcnt lgkmcnt(7)
	v_pk_fma_f32 v[74:75], v[194:195], v[154:155], v[74:75] op_sel:[1,0,0]
	v_pk_fma_f32 v[90:91], v[198:199], v[154:155], v[90:91] op_sel:[1,0,0]
	v_pk_fma_f32 v[108:109], v[202:203], v[154:155], v[108:109] op_sel:[1,0,0]
	v_pk_fma_f32 v[24:25], v[206:207], v[154:155], v[24:25] op_sel:[1,0,0]
	v_pk_fma_f32 v[76:77], v[194:195], v[156:157], v[76:77] op_sel:[1,0,0]
	v_pk_fma_f32 v[94:95], v[198:199], v[156:157], v[94:95] op_sel:[1,0,0]
	v_pk_fma_f32 v[110:111], v[202:203], v[156:157], v[110:111] op_sel:[1,0,0]
	v_pk_fma_f32 v[26:27], v[206:207], v[156:157], v[26:27] op_sel:[1,0,0]
	ds_read_b128 v[154:157], v56 offset:53248
	s_waitcnt lgkmcnt(7)
	v_pk_fma_f32 v[78:79], v[194:195], v[44:45], v[78:79] op_sel:[1,0,0]
	v_pk_fma_f32 v[96:97], v[198:199], v[44:45], v[96:97] op_sel:[1,0,0]
	v_pk_fma_f32 v[112:113], v[202:203], v[44:45], v[112:113] op_sel:[1,0,0]
	v_pk_fma_f32 v[28:29], v[206:207], v[44:45], v[28:29] op_sel:[1,0,0]
	v_pk_fma_f32 v[80:81], v[194:195], v[46:47], v[80:81] op_sel:[1,0,0]
	v_pk_fma_f32 v[98:99], v[198:199], v[46:47], v[98:99] op_sel:[1,0,0]
	v_pk_fma_f32 v[114:115], v[202:203], v[46:47], v[114:115] op_sel:[1,0,0]
	v_pk_fma_f32 v[30:31], v[206:207], v[46:47], v[30:31] op_sel:[1,0,0]
	ds_read_b128 v[44:47], v57 offset:53248
	global_load_dwordx4 v[192:195], v[38:39], off offset:3072
	global_load_dwordx4 v[196:199], v[8:9], off offset:3072
	global_load_dwordx4 v[200:203], v[10:11], off offset:3072
	global_load_dwordx4 v[204:207], v[12:13], off offset:3072
	s_waitcnt vmcnt(31)
	v_cvt_pk_bf16_f32 v244, v208, v209
	v_cvt_pk_bf16_f32 v245, v210, v211
	global_store_dwordx2 v[14:15], v[244:245], off offset:1536
	v_pk_mul_f32 v[22:23], v[208:209], v[208:209]
	v_pk_fma_f32 v[22:23], v[210:211], v[210:211], v[22:23]
	v_add_f32_e32 v22, v22, v23
	v_add_f32_e32 v240, v240, v22
	s_waitcnt vmcnt(31)
	v_cvt_pk_bf16_f32 v246, v212, v213
	v_cvt_pk_bf16_f32 v247, v214, v215
	global_store_dwordx2 v[16:17], v[246:247], off offset:1536
	v_pk_mul_f32 v[22:23], v[212:213], v[212:213]
	v_pk_fma_f32 v[22:23], v[214:215], v[214:215], v[22:23]
	v_add_f32_e32 v22, v22, v23
	v_add_f32_e32 v241, v241, v22
	s_waitcnt vmcnt(31)
	v_cvt_pk_bf16_f32 v248, v216, v217
	v_cvt_pk_bf16_f32 v249, v218, v219
	global_store_dwordx2 v[18:19], v[248:249], off offset:1536
	v_pk_mul_f32 v[22:23], v[216:217], v[216:217]
	v_pk_fma_f32 v[22:23], v[218:219], v[218:219], v[22:23]
	v_add_f32_e32 v22, v22, v23
	v_add_f32_e32 v242, v242, v22
	s_waitcnt vmcnt(31)
	v_cvt_pk_bf16_f32 v232, v220, v221
	v_cvt_pk_bf16_f32 v233, v222, v223
	global_store_dwordx2 v[20:21], v[232:233], off offset:1536
	v_pk_mul_f32 v[22:23], v[220:221], v[220:221]
	v_pk_fma_f32 v[22:23], v[222:223], v[222:223], v[22:23]
	v_add_f32_e32 v22, v22, v23
	v_add_f32_e32 v243, v243, v22
	s_waitcnt lgkmcnt(7)
	v_pk_fma_f32 v[66:67], v[208:209], v[130:131], v[66:67] op_sel_hi:[0,1,1]
	v_pk_fma_f32 v[82:83], v[212:213], v[130:131], v[82:83] op_sel_hi:[0,1,1]
	v_pk_fma_f32 v[100:101], v[216:217], v[130:131], v[100:101] op_sel_hi:[0,1,1]
	v_pk_fma_f32 v[116:117], v[220:221], v[130:131], v[116:117] op_sel_hi:[0,1,1]
	v_pk_fma_f32 v[68:69], v[208:209], v[132:133], v[68:69] op_sel_hi:[0,1,1]
	v_pk_fma_f32 v[84:85], v[212:213], v[132:133], v[84:85] op_sel_hi:[0,1,1]
	v_pk_fma_f32 v[102:103], v[216:217], v[132:133], v[102:103] op_sel_hi:[0,1,1]
	v_pk_fma_f32 v[118:119], v[220:221], v[132:133], v[118:119] op_sel_hi:[0,1,1]
	ds_read_b128 v[130:133], v54 offset:57344
	s_waitcnt lgkmcnt(7)
	v_pk_fma_f32 v[70:71], v[208:209], v[134:135], v[70:71] op_sel_hi:[0,1,1]
	v_pk_fma_f32 v[86:87], v[212:213], v[134:135], v[86:87] op_sel_hi:[0,1,1]
	v_pk_fma_f32 v[104:105], v[216:217], v[134:135], v[104:105] op_sel_hi:[0,1,1]
	v_pk_fma_f32 v[120:121], v[220:221], v[134:135], v[120:121] op_sel_hi:[0,1,1]
	v_pk_fma_f32 v[72:73], v[208:209], v[136:137], v[72:73] op_sel_hi:[0,1,1]
	v_pk_fma_f32 v[88:89], v[212:213], v[136:137], v[88:89] op_sel_hi:[0,1,1]
	v_pk_fma_f32 v[106:107], v[216:217], v[136:137], v[106:107] op_sel_hi:[0,1,1]
	v_pk_fma_f32 v[122:123], v[220:221], v[136:137], v[122:123] op_sel_hi:[0,1,1]
	ds_read_b128 v[134:137], v55 offset:57344
	s_waitcnt lgkmcnt(7)
	v_pk_fma_f32 v[74:75], v[208:209], v[138:139], v[74:75] op_sel_hi:[0,1,1]
	v_pk_fma_f32 v[90:91], v[212:213], v[138:139], v[90:91] op_sel_hi:[0,1,1]
	v_pk_fma_f32 v[108:109], v[216:217], v[138:139], v[108:109] op_sel_hi:[0,1,1]
	v_pk_fma_f32 v[24:25], v[220:221], v[138:139], v[24:25] op_sel_hi:[0,1,1]
	v_pk_fma_f32 v[76:77], v[208:209], v[140:141], v[76:77] op_sel_hi:[0,1,1]
	v_pk_fma_f32 v[94:95], v[212:213], v[140:141], v[94:95] op_sel_hi:[0,1,1]
	v_pk_fma_f32 v[110:111], v[216:217], v[140:141], v[110:111] op_sel_hi:[0,1,1]
	v_pk_fma_f32 v[26:27], v[220:221], v[140:141], v[26:27] op_sel_hi:[0,1,1]
	ds_read_b128 v[138:141], v56 offset:57344
	s_waitcnt lgkmcnt(7)
	v_pk_fma_f32 v[78:79], v[208:209], v[142:143], v[78:79] op_sel_hi:[0,1,1]
	v_pk_fma_f32 v[96:97], v[212:213], v[142:143], v[96:97] op_sel_hi:[0,1,1]
	v_pk_fma_f32 v[112:113], v[216:217], v[142:143], v[112:113] op_sel_hi:[0,1,1]
	v_pk_fma_f32 v[28:29], v[220:221], v[142:143], v[28:29] op_sel_hi:[0,1,1]
	v_pk_fma_f32 v[80:81], v[208:209], v[144:145], v[80:81] op_sel_hi:[0,1,1]
	v_pk_fma_f32 v[98:99], v[212:213], v[144:145], v[98:99] op_sel_hi:[0,1,1]
	v_pk_fma_f32 v[114:115], v[216:217], v[144:145], v[114:115] op_sel_hi:[0,1,1]
	v_pk_fma_f32 v[30:31], v[220:221], v[144:145], v[30:31] op_sel_hi:[0,1,1]
	ds_read_b128 v[142:145], v57 offset:57344
	s_waitcnt lgkmcnt(7)
	v_pk_fma_f32 v[66:67], v[208:209], v[146:147], v[66:67] op_sel:[1,0,0]
	v_pk_fma_f32 v[82:83], v[212:213], v[146:147], v[82:83] op_sel:[1,0,0]
	v_pk_fma_f32 v[100:101], v[216:217], v[146:147], v[100:101] op_sel:[1,0,0]
	v_pk_fma_f32 v[116:117], v[220:221], v[146:147], v[116:117] op_sel:[1,0,0]
	v_pk_fma_f32 v[68:69], v[208:209], v[148:149], v[68:69] op_sel:[1,0,0]
	v_pk_fma_f32 v[84:85], v[212:213], v[148:149], v[84:85] op_sel:[1,0,0]
	v_pk_fma_f32 v[102:103], v[216:217], v[148:149], v[102:103] op_sel:[1,0,0]
	v_pk_fma_f32 v[118:119], v[220:221], v[148:149], v[118:119] op_sel:[1,0,0]
	ds_read_b128 v[146:149], v54 offset:61440
	s_waitcnt lgkmcnt(7)
	v_pk_fma_f32 v[70:71], v[208:209], v[150:151], v[70:71] op_sel:[1,0,0]
	v_pk_fma_f32 v[86:87], v[212:213], v[150:151], v[86:87] op_sel:[1,0,0]
	v_pk_fma_f32 v[104:105], v[216:217], v[150:151], v[104:105] op_sel:[1,0,0]
	v_pk_fma_f32 v[120:121], v[220:221], v[150:151], v[120:121] op_sel:[1,0,0]
	v_pk_fma_f32 v[72:73], v[208:209], v[152:153], v[72:73] op_sel:[1,0,0]
	v_pk_fma_f32 v[88:89], v[212:213], v[152:153], v[88:89] op_sel:[1,0,0]
	v_pk_fma_f32 v[106:107], v[216:217], v[152:153], v[106:107] op_sel:[1,0,0]
	v_pk_fma_f32 v[122:123], v[220:221], v[152:153], v[122:123] op_sel:[1,0,0]
	ds_read_b128 v[150:153], v55 offset:61440
	s_waitcnt lgkmcnt(7)
	v_pk_fma_f32 v[74:75], v[208:209], v[154:155], v[74:75] op_sel:[1,0,0]
	v_pk_fma_f32 v[90:91], v[212:213], v[154:155], v[90:91] op_sel:[1,0,0]
	v_pk_fma_f32 v[108:109], v[216:217], v[154:155], v[108:109] op_sel:[1,0,0]
	v_pk_fma_f32 v[24:25], v[220:221], v[154:155], v[24:25] op_sel:[1,0,0]
	v_pk_fma_f32 v[76:77], v[208:209], v[156:157], v[76:77] op_sel:[1,0,0]
	v_pk_fma_f32 v[94:95], v[212:213], v[156:157], v[94:95] op_sel:[1,0,0]
	v_pk_fma_f32 v[110:111], v[216:217], v[156:157], v[110:111] op_sel:[1,0,0]
	v_pk_fma_f32 v[26:27], v[220:221], v[156:157], v[26:27] op_sel:[1,0,0]
	ds_read_b128 v[154:157], v56 offset:61440
	s_waitcnt lgkmcnt(7)
	v_pk_fma_f32 v[78:79], v[208:209], v[44:45], v[78:79] op_sel:[1,0,0]
	v_pk_fma_f32 v[96:97], v[212:213], v[44:45], v[96:97] op_sel:[1,0,0]
	v_pk_fma_f32 v[112:113], v[216:217], v[44:45], v[112:113] op_sel:[1,0,0]
	v_pk_fma_f32 v[28:29], v[220:221], v[44:45], v[28:29] op_sel:[1,0,0]
	v_pk_fma_f32 v[80:81], v[208:209], v[46:47], v[80:81] op_sel:[1,0,0]
	v_pk_fma_f32 v[98:99], v[212:213], v[46:47], v[98:99] op_sel:[1,0,0]
	v_pk_fma_f32 v[114:115], v[216:217], v[46:47], v[114:115] op_sel:[1,0,0]
	v_pk_fma_f32 v[30:31], v[220:221], v[46:47], v[30:31] op_sel:[1,0,0]
	ds_read_b128 v[44:47], v57 offset:61440
	s_waitcnt lgkmcnt(7)
	v_pk_fma_f32 v[66:67], v[210:211], v[130:131], v[66:67] op_sel_hi:[0,1,1]
	v_pk_fma_f32 v[82:83], v[214:215], v[130:131], v[82:83] op_sel_hi:[0,1,1]
	v_pk_fma_f32 v[100:101], v[218:219], v[130:131], v[100:101] op_sel_hi:[0,1,1]
	v_pk_fma_f32 v[116:117], v[222:223], v[130:131], v[116:117] op_sel_hi:[0,1,1]
	v_pk_fma_f32 v[68:69], v[210:211], v[132:133], v[68:69] op_sel_hi:[0,1,1]
	v_pk_fma_f32 v[84:85], v[214:215], v[132:133], v[84:85] op_sel_hi:[0,1,1]
	v_pk_fma_f32 v[102:103], v[218:219], v[132:133], v[102:103] op_sel_hi:[0,1,1]
	v_pk_fma_f32 v[118:119], v[222:223], v[132:133], v[118:119] op_sel_hi:[0,1,1]
	ds_read_b128 v[130:133], v58
	s_waitcnt lgkmcnt(7)
	v_pk_fma_f32 v[70:71], v[210:211], v[134:135], v[70:71] op_sel_hi:[0,1,1]
	v_pk_fma_f32 v[86:87], v[214:215], v[134:135], v[86:87] op_sel_hi:[0,1,1]
	v_pk_fma_f32 v[104:105], v[218:219], v[134:135], v[104:105] op_sel_hi:[0,1,1]
	v_pk_fma_f32 v[120:121], v[222:223], v[134:135], v[120:121] op_sel_hi:[0,1,1]
	v_pk_fma_f32 v[72:73], v[210:211], v[136:137], v[72:73] op_sel_hi:[0,1,1]
	v_pk_fma_f32 v[88:89], v[214:215], v[136:137], v[88:89] op_sel_hi:[0,1,1]
	v_pk_fma_f32 v[106:107], v[218:219], v[136:137], v[106:107] op_sel_hi:[0,1,1]
	v_pk_fma_f32 v[122:123], v[222:223], v[136:137], v[122:123] op_sel_hi:[0,1,1]
	ds_read_b128 v[134:137], v59
	s_waitcnt lgkmcnt(7)
	v_pk_fma_f32 v[74:75], v[210:211], v[138:139], v[74:75] op_sel_hi:[0,1,1]
	v_pk_fma_f32 v[90:91], v[214:215], v[138:139], v[90:91] op_sel_hi:[0,1,1]
	v_pk_fma_f32 v[108:109], v[218:219], v[138:139], v[108:109] op_sel_hi:[0,1,1]
	v_pk_fma_f32 v[24:25], v[222:223], v[138:139], v[24:25] op_sel_hi:[0,1,1]
	v_pk_fma_f32 v[76:77], v[210:211], v[140:141], v[76:77] op_sel_hi:[0,1,1]
	v_pk_fma_f32 v[94:95], v[214:215], v[140:141], v[94:95] op_sel_hi:[0,1,1]
	v_pk_fma_f32 v[110:111], v[218:219], v[140:141], v[110:111] op_sel_hi:[0,1,1]
	v_pk_fma_f32 v[26:27], v[222:223], v[140:141], v[26:27] op_sel_hi:[0,1,1]
	ds_read_b128 v[138:141], v60
	s_waitcnt lgkmcnt(7)
	v_pk_fma_f32 v[78:79], v[210:211], v[142:143], v[78:79] op_sel_hi:[0,1,1]
	v_pk_fma_f32 v[96:97], v[214:215], v[142:143], v[96:97] op_sel_hi:[0,1,1]
	v_pk_fma_f32 v[112:113], v[218:219], v[142:143], v[112:113] op_sel_hi:[0,1,1]
	v_pk_fma_f32 v[28:29], v[222:223], v[142:143], v[28:29] op_sel_hi:[0,1,1]
	v_pk_fma_f32 v[80:81], v[210:211], v[144:145], v[80:81] op_sel_hi:[0,1,1]
	v_pk_fma_f32 v[98:99], v[214:215], v[144:145], v[98:99] op_sel_hi:[0,1,1]
	v_pk_fma_f32 v[114:115], v[218:219], v[144:145], v[114:115] op_sel_hi:[0,1,1]
	v_pk_fma_f32 v[30:31], v[222:223], v[144:145], v[30:31] op_sel_hi:[0,1,1]
	ds_read_b128 v[142:145], v61
	s_waitcnt lgkmcnt(7)
	v_pk_fma_f32 v[66:67], v[210:211], v[146:147], v[66:67] op_sel:[1,0,0]
	v_pk_fma_f32 v[82:83], v[214:215], v[146:147], v[82:83] op_sel:[1,0,0]
	v_pk_fma_f32 v[100:101], v[218:219], v[146:147], v[100:101] op_sel:[1,0,0]
	v_pk_fma_f32 v[116:117], v[222:223], v[146:147], v[116:117] op_sel:[1,0,0]
	v_pk_fma_f32 v[68:69], v[210:211], v[148:149], v[68:69] op_sel:[1,0,0]
	v_pk_fma_f32 v[84:85], v[214:215], v[148:149], v[84:85] op_sel:[1,0,0]
	v_pk_fma_f32 v[102:103], v[218:219], v[148:149], v[102:103] op_sel:[1,0,0]
	v_pk_fma_f32 v[118:119], v[222:223], v[148:149], v[118:119] op_sel:[1,0,0]
	ds_read_b128 v[146:149], v58 offset:4096
	s_waitcnt lgkmcnt(7)
	v_pk_fma_f32 v[70:71], v[210:211], v[150:151], v[70:71] op_sel:[1,0,0]
	v_pk_fma_f32 v[86:87], v[214:215], v[150:151], v[86:87] op_sel:[1,0,0]
	v_pk_fma_f32 v[104:105], v[218:219], v[150:151], v[104:105] op_sel:[1,0,0]
	v_pk_fma_f32 v[120:121], v[222:223], v[150:151], v[120:121] op_sel:[1,0,0]
	v_pk_fma_f32 v[72:73], v[210:211], v[152:153], v[72:73] op_sel:[1,0,0]
	v_pk_fma_f32 v[88:89], v[214:215], v[152:153], v[88:89] op_sel:[1,0,0]
	v_pk_fma_f32 v[106:107], v[218:219], v[152:153], v[106:107] op_sel:[1,0,0]
	v_pk_fma_f32 v[122:123], v[222:223], v[152:153], v[122:123] op_sel:[1,0,0]
	ds_read_b128 v[150:153], v59 offset:4096
	s_waitcnt lgkmcnt(7)
	v_pk_fma_f32 v[74:75], v[210:211], v[154:155], v[74:75] op_sel:[1,0,0]
	v_pk_fma_f32 v[90:91], v[214:215], v[154:155], v[90:91] op_sel:[1,0,0]
	v_pk_fma_f32 v[108:109], v[218:219], v[154:155], v[108:109] op_sel:[1,0,0]
	v_pk_fma_f32 v[24:25], v[222:223], v[154:155], v[24:25] op_sel:[1,0,0]
	v_pk_fma_f32 v[76:77], v[210:211], v[156:157], v[76:77] op_sel:[1,0,0]
	v_pk_fma_f32 v[94:95], v[214:215], v[156:157], v[94:95] op_sel:[1,0,0]
	v_pk_fma_f32 v[110:111], v[218:219], v[156:157], v[110:111] op_sel:[1,0,0]
	v_pk_fma_f32 v[26:27], v[222:223], v[156:157], v[26:27] op_sel:[1,0,0]
	ds_read_b128 v[154:157], v60 offset:4096
	s_waitcnt lgkmcnt(7)
	v_pk_fma_f32 v[78:79], v[210:211], v[44:45], v[78:79] op_sel:[1,0,0]
	v_pk_fma_f32 v[96:97], v[214:215], v[44:45], v[96:97] op_sel:[1,0,0]
	v_pk_fma_f32 v[112:113], v[218:219], v[44:45], v[112:113] op_sel:[1,0,0]
	v_pk_fma_f32 v[28:29], v[222:223], v[44:45], v[28:29] op_sel:[1,0,0]
	v_pk_fma_f32 v[80:81], v[210:211], v[46:47], v[80:81] op_sel:[1,0,0]
	v_pk_fma_f32 v[98:99], v[214:215], v[46:47], v[98:99] op_sel:[1,0,0]
	v_pk_fma_f32 v[114:115], v[218:219], v[46:47], v[114:115] op_sel:[1,0,0]
	v_pk_fma_f32 v[30:31], v[222:223], v[46:47], v[30:31] op_sel:[1,0,0]
	ds_read_b128 v[44:47], v61 offset:4096
	s_waitcnt vmcnt(31)
	v_cvt_pk_bf16_f32 v244, v224, v225
	v_cvt_pk_bf16_f32 v245, v226, v227
	global_store_dwordx2 v[14:15], v[244:245], off offset:2048
	v_pk_mul_f32 v[22:23], v[224:225], v[224:225]
	v_pk_fma_f32 v[22:23], v[226:227], v[226:227], v[22:23]
	v_add_f32_e32 v22, v22, v23
	v_add_f32_e32 v240, v240, v22
	s_waitcnt vmcnt(31)
	v_cvt_pk_bf16_f32 v246, v228, v229
	v_cvt_pk_bf16_f32 v247, v230, v231
	global_store_dwordx2 v[16:17], v[246:247], off offset:2048
	v_pk_mul_f32 v[22:23], v[228:229], v[228:229]
	v_pk_fma_f32 v[22:23], v[230:231], v[230:231], v[22:23]
	v_add_f32_e32 v22, v22, v23
	v_add_f32_e32 v241, v241, v22
	s_waitcnt vmcnt(31)
	v_cvt_pk_bf16_f32 v248, v0, v1
	v_cvt_pk_bf16_f32 v249, v2, v3
	global_store_dwordx2 v[18:19], v[248:249], off offset:2048
	v_pk_mul_f32 v[22:23], v[0:1], v[0:1]
	v_pk_fma_f32 v[22:23], v[2:3], v[2:3], v[22:23]
	v_add_f32_e32 v22, v22, v23
	v_add_f32_e32 v242, v242, v22
	s_waitcnt vmcnt(31)
	v_cvt_pk_bf16_f32 v232, v4, v5
	v_cvt_pk_bf16_f32 v233, v6, v7
	global_store_dwordx2 v[20:21], v[232:233], off offset:2048
	v_pk_mul_f32 v[22:23], v[4:5], v[4:5]
	v_pk_fma_f32 v[22:23], v[6:7], v[6:7], v[22:23]
	v_add_f32_e32 v22, v22, v23
	v_add_f32_e32 v243, v243, v22
	s_waitcnt lgkmcnt(7)
	v_pk_fma_f32 v[66:67], v[224:225], v[130:131], v[66:67] op_sel_hi:[0,1,1]
	v_pk_fma_f32 v[82:83], v[228:229], v[130:131], v[82:83] op_sel_hi:[0,1,1]
	v_pk_fma_f32 v[100:101], v[0:1], v[130:131], v[100:101] op_sel_hi:[0,1,1]
	v_pk_fma_f32 v[116:117], v[4:5], v[130:131], v[116:117] op_sel_hi:[0,1,1]
	v_pk_fma_f32 v[68:69], v[224:225], v[132:133], v[68:69] op_sel_hi:[0,1,1]
	v_pk_fma_f32 v[84:85], v[228:229], v[132:133], v[84:85] op_sel_hi:[0,1,1]
	v_pk_fma_f32 v[102:103], v[0:1], v[132:133], v[102:103] op_sel_hi:[0,1,1]
	v_pk_fma_f32 v[118:119], v[4:5], v[132:133], v[118:119] op_sel_hi:[0,1,1]
	ds_read_b128 v[130:133], v58 offset:8192
	s_waitcnt lgkmcnt(7)
	v_pk_fma_f32 v[70:71], v[224:225], v[134:135], v[70:71] op_sel_hi:[0,1,1]
	v_pk_fma_f32 v[86:87], v[228:229], v[134:135], v[86:87] op_sel_hi:[0,1,1]
	v_pk_fma_f32 v[104:105], v[0:1], v[134:135], v[104:105] op_sel_hi:[0,1,1]
	v_pk_fma_f32 v[120:121], v[4:5], v[134:135], v[120:121] op_sel_hi:[0,1,1]
	v_pk_fma_f32 v[72:73], v[224:225], v[136:137], v[72:73] op_sel_hi:[0,1,1]
	v_pk_fma_f32 v[88:89], v[228:229], v[136:137], v[88:89] op_sel_hi:[0,1,1]
	v_pk_fma_f32 v[106:107], v[0:1], v[136:137], v[106:107] op_sel_hi:[0,1,1]
	v_pk_fma_f32 v[122:123], v[4:5], v[136:137], v[122:123] op_sel_hi:[0,1,1]
	ds_read_b128 v[134:137], v59 offset:8192
	s_waitcnt lgkmcnt(7)
	v_pk_fma_f32 v[74:75], v[224:225], v[138:139], v[74:75] op_sel_hi:[0,1,1]
	v_pk_fma_f32 v[90:91], v[228:229], v[138:139], v[90:91] op_sel_hi:[0,1,1]
	v_pk_fma_f32 v[108:109], v[0:1], v[138:139], v[108:109] op_sel_hi:[0,1,1]
	v_pk_fma_f32 v[24:25], v[4:5], v[138:139], v[24:25] op_sel_hi:[0,1,1]
	v_pk_fma_f32 v[76:77], v[224:225], v[140:141], v[76:77] op_sel_hi:[0,1,1]
	v_pk_fma_f32 v[94:95], v[228:229], v[140:141], v[94:95] op_sel_hi:[0,1,1]
	v_pk_fma_f32 v[110:111], v[0:1], v[140:141], v[110:111] op_sel_hi:[0,1,1]
	v_pk_fma_f32 v[26:27], v[4:5], v[140:141], v[26:27] op_sel_hi:[0,1,1]
	ds_read_b128 v[138:141], v60 offset:8192
	s_waitcnt lgkmcnt(7)
	v_pk_fma_f32 v[78:79], v[224:225], v[142:143], v[78:79] op_sel_hi:[0,1,1]
	v_pk_fma_f32 v[96:97], v[228:229], v[142:143], v[96:97] op_sel_hi:[0,1,1]
	v_pk_fma_f32 v[112:113], v[0:1], v[142:143], v[112:113] op_sel_hi:[0,1,1]
	v_pk_fma_f32 v[28:29], v[4:5], v[142:143], v[28:29] op_sel_hi:[0,1,1]
	v_pk_fma_f32 v[80:81], v[224:225], v[144:145], v[80:81] op_sel_hi:[0,1,1]
	v_pk_fma_f32 v[98:99], v[228:229], v[144:145], v[98:99] op_sel_hi:[0,1,1]
	v_pk_fma_f32 v[114:115], v[0:1], v[144:145], v[114:115] op_sel_hi:[0,1,1]
	v_pk_fma_f32 v[30:31], v[4:5], v[144:145], v[30:31] op_sel_hi:[0,1,1]
	ds_read_b128 v[142:145], v61 offset:8192
	s_waitcnt lgkmcnt(7)
	v_pk_fma_f32 v[66:67], v[224:225], v[146:147], v[66:67] op_sel:[1,0,0]
	v_pk_fma_f32 v[82:83], v[228:229], v[146:147], v[82:83] op_sel:[1,0,0]
	v_pk_fma_f32 v[100:101], v[0:1], v[146:147], v[100:101] op_sel:[1,0,0]
	v_pk_fma_f32 v[116:117], v[4:5], v[146:147], v[116:117] op_sel:[1,0,0]
	v_pk_fma_f32 v[68:69], v[224:225], v[148:149], v[68:69] op_sel:[1,0,0]
	v_pk_fma_f32 v[84:85], v[228:229], v[148:149], v[84:85] op_sel:[1,0,0]
	v_pk_fma_f32 v[102:103], v[0:1], v[148:149], v[102:103] op_sel:[1,0,0]
	v_pk_fma_f32 v[118:119], v[4:5], v[148:149], v[118:119] op_sel:[1,0,0]
	ds_read_b128 v[146:149], v58 offset:12288
	s_waitcnt lgkmcnt(7)
	v_pk_fma_f32 v[70:71], v[224:225], v[150:151], v[70:71] op_sel:[1,0,0]
	v_pk_fma_f32 v[86:87], v[228:229], v[150:151], v[86:87] op_sel:[1,0,0]
	v_pk_fma_f32 v[104:105], v[0:1], v[150:151], v[104:105] op_sel:[1,0,0]
	v_pk_fma_f32 v[120:121], v[4:5], v[150:151], v[120:121] op_sel:[1,0,0]
	v_pk_fma_f32 v[72:73], v[224:225], v[152:153], v[72:73] op_sel:[1,0,0]
	v_pk_fma_f32 v[88:89], v[228:229], v[152:153], v[88:89] op_sel:[1,0,0]
	v_pk_fma_f32 v[106:107], v[0:1], v[152:153], v[106:107] op_sel:[1,0,0]
	v_pk_fma_f32 v[122:123], v[4:5], v[152:153], v[122:123] op_sel:[1,0,0]
	ds_read_b128 v[150:153], v59 offset:12288
	s_waitcnt lgkmcnt(7)
	v_pk_fma_f32 v[74:75], v[224:225], v[154:155], v[74:75] op_sel:[1,0,0]
	v_pk_fma_f32 v[90:91], v[228:229], v[154:155], v[90:91] op_sel:[1,0,0]
	v_pk_fma_f32 v[108:109], v[0:1], v[154:155], v[108:109] op_sel:[1,0,0]
	v_pk_fma_f32 v[24:25], v[4:5], v[154:155], v[24:25] op_sel:[1,0,0]
	v_pk_fma_f32 v[76:77], v[224:225], v[156:157], v[76:77] op_sel:[1,0,0]
	v_pk_fma_f32 v[94:95], v[228:229], v[156:157], v[94:95] op_sel:[1,0,0]
	v_pk_fma_f32 v[110:111], v[0:1], v[156:157], v[110:111] op_sel:[1,0,0]
	v_pk_fma_f32 v[26:27], v[4:5], v[156:157], v[26:27] op_sel:[1,0,0]
	ds_read_b128 v[154:157], v60 offset:12288
	s_waitcnt lgkmcnt(7)
	v_pk_fma_f32 v[78:79], v[224:225], v[44:45], v[78:79] op_sel:[1,0,0]
	v_pk_fma_f32 v[96:97], v[228:229], v[44:45], v[96:97] op_sel:[1,0,0]
	v_pk_fma_f32 v[112:113], v[0:1], v[44:45], v[112:113] op_sel:[1,0,0]
	v_pk_fma_f32 v[28:29], v[4:5], v[44:45], v[28:29] op_sel:[1,0,0]
	v_pk_fma_f32 v[80:81], v[224:225], v[46:47], v[80:81] op_sel:[1,0,0]
	v_pk_fma_f32 v[98:99], v[228:229], v[46:47], v[98:99] op_sel:[1,0,0]
	v_pk_fma_f32 v[114:115], v[0:1], v[46:47], v[114:115] op_sel:[1,0,0]
	v_pk_fma_f32 v[30:31], v[4:5], v[46:47], v[30:31] op_sel:[1,0,0]
	ds_read_b128 v[44:47], v61 offset:12288
	s_waitcnt lgkmcnt(7)
	v_pk_fma_f32 v[66:67], v[226:227], v[130:131], v[66:67] op_sel_hi:[0,1,1]
	v_pk_fma_f32 v[82:83], v[230:231], v[130:131], v[82:83] op_sel_hi:[0,1,1]
	v_pk_fma_f32 v[100:101], v[2:3], v[130:131], v[100:101] op_sel_hi:[0,1,1]
	v_pk_fma_f32 v[116:117], v[6:7], v[130:131], v[116:117] op_sel_hi:[0,1,1]
	v_pk_fma_f32 v[68:69], v[226:227], v[132:133], v[68:69] op_sel_hi:[0,1,1]
	v_pk_fma_f32 v[84:85], v[230:231], v[132:133], v[84:85] op_sel_hi:[0,1,1]
	v_pk_fma_f32 v[102:103], v[2:3], v[132:133], v[102:103] op_sel_hi:[0,1,1]
	v_pk_fma_f32 v[118:119], v[6:7], v[132:133], v[118:119] op_sel_hi:[0,1,1]
	ds_read_b128 v[130:133], v58 offset:16384
	s_waitcnt lgkmcnt(7)
	v_pk_fma_f32 v[70:71], v[226:227], v[134:135], v[70:71] op_sel_hi:[0,1,1]
	v_pk_fma_f32 v[86:87], v[230:231], v[134:135], v[86:87] op_sel_hi:[0,1,1]
	v_pk_fma_f32 v[104:105], v[2:3], v[134:135], v[104:105] op_sel_hi:[0,1,1]
	v_pk_fma_f32 v[120:121], v[6:7], v[134:135], v[120:121] op_sel_hi:[0,1,1]
	v_pk_fma_f32 v[72:73], v[226:227], v[136:137], v[72:73] op_sel_hi:[0,1,1]
	v_pk_fma_f32 v[88:89], v[230:231], v[136:137], v[88:89] op_sel_hi:[0,1,1]
	v_pk_fma_f32 v[106:107], v[2:3], v[136:137], v[106:107] op_sel_hi:[0,1,1]
	v_pk_fma_f32 v[122:123], v[6:7], v[136:137], v[122:123] op_sel_hi:[0,1,1]
	ds_read_b128 v[134:137], v59 offset:16384
	s_waitcnt lgkmcnt(7)
	v_pk_fma_f32 v[74:75], v[226:227], v[138:139], v[74:75] op_sel_hi:[0,1,1]
	v_pk_fma_f32 v[90:91], v[230:231], v[138:139], v[90:91] op_sel_hi:[0,1,1]
	v_pk_fma_f32 v[108:109], v[2:3], v[138:139], v[108:109] op_sel_hi:[0,1,1]
	v_pk_fma_f32 v[24:25], v[6:7], v[138:139], v[24:25] op_sel_hi:[0,1,1]
	v_pk_fma_f32 v[76:77], v[226:227], v[140:141], v[76:77] op_sel_hi:[0,1,1]
	v_pk_fma_f32 v[94:95], v[230:231], v[140:141], v[94:95] op_sel_hi:[0,1,1]
	v_pk_fma_f32 v[110:111], v[2:3], v[140:141], v[110:111] op_sel_hi:[0,1,1]
	v_pk_fma_f32 v[26:27], v[6:7], v[140:141], v[26:27] op_sel_hi:[0,1,1]
	ds_read_b128 v[138:141], v60 offset:16384
	s_waitcnt lgkmcnt(7)
	v_pk_fma_f32 v[78:79], v[226:227], v[142:143], v[78:79] op_sel_hi:[0,1,1]
	v_pk_fma_f32 v[96:97], v[230:231], v[142:143], v[96:97] op_sel_hi:[0,1,1]
	v_pk_fma_f32 v[112:113], v[2:3], v[142:143], v[112:113] op_sel_hi:[0,1,1]
	v_pk_fma_f32 v[28:29], v[6:7], v[142:143], v[28:29] op_sel_hi:[0,1,1]
	v_pk_fma_f32 v[80:81], v[226:227], v[144:145], v[80:81] op_sel_hi:[0,1,1]
	v_pk_fma_f32 v[98:99], v[230:231], v[144:145], v[98:99] op_sel_hi:[0,1,1]
	v_pk_fma_f32 v[114:115], v[2:3], v[144:145], v[114:115] op_sel_hi:[0,1,1]
	v_pk_fma_f32 v[30:31], v[6:7], v[144:145], v[30:31] op_sel_hi:[0,1,1]
	ds_read_b128 v[142:145], v61 offset:16384
	s_waitcnt lgkmcnt(7)
	v_pk_fma_f32 v[66:67], v[226:227], v[146:147], v[66:67] op_sel:[1,0,0]
	v_pk_fma_f32 v[82:83], v[230:231], v[146:147], v[82:83] op_sel:[1,0,0]
	v_pk_fma_f32 v[100:101], v[2:3], v[146:147], v[100:101] op_sel:[1,0,0]
	v_pk_fma_f32 v[116:117], v[6:7], v[146:147], v[116:117] op_sel:[1,0,0]
	v_pk_fma_f32 v[68:69], v[226:227], v[148:149], v[68:69] op_sel:[1,0,0]
	v_pk_fma_f32 v[84:85], v[230:231], v[148:149], v[84:85] op_sel:[1,0,0]
	v_pk_fma_f32 v[102:103], v[2:3], v[148:149], v[102:103] op_sel:[1,0,0]
	v_pk_fma_f32 v[118:119], v[6:7], v[148:149], v[118:119] op_sel:[1,0,0]
	ds_read_b128 v[146:149], v58 offset:20480
	s_waitcnt lgkmcnt(7)
	v_pk_fma_f32 v[70:71], v[226:227], v[150:151], v[70:71] op_sel:[1,0,0]
	v_pk_fma_f32 v[86:87], v[230:231], v[150:151], v[86:87] op_sel:[1,0,0]
	v_pk_fma_f32 v[104:105], v[2:3], v[150:151], v[104:105] op_sel:[1,0,0]
	v_pk_fma_f32 v[120:121], v[6:7], v[150:151], v[120:121] op_sel:[1,0,0]
	v_pk_fma_f32 v[72:73], v[226:227], v[152:153], v[72:73] op_sel:[1,0,0]
	v_pk_fma_f32 v[88:89], v[230:231], v[152:153], v[88:89] op_sel:[1,0,0]
	v_pk_fma_f32 v[106:107], v[2:3], v[152:153], v[106:107] op_sel:[1,0,0]
	v_pk_fma_f32 v[122:123], v[6:7], v[152:153], v[122:123] op_sel:[1,0,0]
	ds_read_b128 v[150:153], v59 offset:20480
	s_waitcnt lgkmcnt(7)
	v_pk_fma_f32 v[74:75], v[226:227], v[154:155], v[74:75] op_sel:[1,0,0]
	v_pk_fma_f32 v[90:91], v[230:231], v[154:155], v[90:91] op_sel:[1,0,0]
	v_pk_fma_f32 v[108:109], v[2:3], v[154:155], v[108:109] op_sel:[1,0,0]
	v_pk_fma_f32 v[24:25], v[6:7], v[154:155], v[24:25] op_sel:[1,0,0]
	v_pk_fma_f32 v[76:77], v[226:227], v[156:157], v[76:77] op_sel:[1,0,0]
	v_pk_fma_f32 v[94:95], v[230:231], v[156:157], v[94:95] op_sel:[1,0,0]
	v_pk_fma_f32 v[110:111], v[2:3], v[156:157], v[110:111] op_sel:[1,0,0]
	v_pk_fma_f32 v[26:27], v[6:7], v[156:157], v[26:27] op_sel:[1,0,0]
	ds_read_b128 v[154:157], v60 offset:20480
	s_waitcnt lgkmcnt(7)
	v_pk_fma_f32 v[78:79], v[226:227], v[44:45], v[78:79] op_sel:[1,0,0]
	v_pk_fma_f32 v[96:97], v[230:231], v[44:45], v[96:97] op_sel:[1,0,0]
	v_pk_fma_f32 v[112:113], v[2:3], v[44:45], v[112:113] op_sel:[1,0,0]
	v_pk_fma_f32 v[28:29], v[6:7], v[44:45], v[28:29] op_sel:[1,0,0]
	v_pk_fma_f32 v[80:81], v[226:227], v[46:47], v[80:81] op_sel:[1,0,0]
	v_pk_fma_f32 v[98:99], v[230:231], v[46:47], v[98:99] op_sel:[1,0,0]
	v_pk_fma_f32 v[114:115], v[2:3], v[46:47], v[114:115] op_sel:[1,0,0]
	v_pk_fma_f32 v[30:31], v[6:7], v[46:47], v[30:31] op_sel:[1,0,0]
	ds_read_b128 v[44:47], v61 offset:20480
	s_waitcnt vmcnt(27)
	v_cvt_pk_bf16_f32 v244, v160, v161
	v_cvt_pk_bf16_f32 v245, v162, v163
	global_store_dwordx2 v[14:15], v[244:245], off offset:2560
	v_pk_mul_f32 v[22:23], v[160:161], v[160:161]
	v_pk_fma_f32 v[22:23], v[162:163], v[162:163], v[22:23]
	v_add_f32_e32 v22, v22, v23
	v_add_f32_e32 v240, v240, v22
	s_waitcnt vmcnt(27)
	v_cvt_pk_bf16_f32 v246, v164, v165
	v_cvt_pk_bf16_f32 v247, v166, v167
	global_store_dwordx2 v[16:17], v[246:247], off offset:2560
	v_pk_mul_f32 v[22:23], v[164:165], v[164:165]
	v_pk_fma_f32 v[22:23], v[166:167], v[166:167], v[22:23]
	v_add_f32_e32 v22, v22, v23
	v_add_f32_e32 v241, v241, v22
	s_waitcnt vmcnt(27)
	v_cvt_pk_bf16_f32 v248, v168, v169
	v_cvt_pk_bf16_f32 v249, v170, v171
	global_store_dwordx2 v[18:19], v[248:249], off offset:2560
	v_pk_mul_f32 v[22:23], v[168:169], v[168:169]
	v_pk_fma_f32 v[22:23], v[170:171], v[170:171], v[22:23]
	v_add_f32_e32 v22, v22, v23
	v_add_f32_e32 v242, v242, v22
	s_waitcnt vmcnt(27)
	v_cvt_pk_bf16_f32 v232, v172, v173
	v_cvt_pk_bf16_f32 v233, v174, v175
	global_store_dwordx2 v[20:21], v[232:233], off offset:2560
	v_pk_mul_f32 v[22:23], v[172:173], v[172:173]
	v_pk_fma_f32 v[22:23], v[174:175], v[174:175], v[22:23]
	v_add_f32_e32 v22, v22, v23
	v_add_f32_e32 v243, v243, v22
	s_waitcnt lgkmcnt(7)
	v_pk_fma_f32 v[66:67], v[160:161], v[130:131], v[66:67] op_sel_hi:[0,1,1]
	v_pk_fma_f32 v[82:83], v[164:165], v[130:131], v[82:83] op_sel_hi:[0,1,1]
	v_pk_fma_f32 v[100:101], v[168:169], v[130:131], v[100:101] op_sel_hi:[0,1,1]
	v_pk_fma_f32 v[116:117], v[172:173], v[130:131], v[116:117] op_sel_hi:[0,1,1]
	v_pk_fma_f32 v[68:69], v[160:161], v[132:133], v[68:69] op_sel_hi:[0,1,1]
	v_pk_fma_f32 v[84:85], v[164:165], v[132:133], v[84:85] op_sel_hi:[0,1,1]
	v_pk_fma_f32 v[102:103], v[168:169], v[132:133], v[102:103] op_sel_hi:[0,1,1]
	v_pk_fma_f32 v[118:119], v[172:173], v[132:133], v[118:119] op_sel_hi:[0,1,1]
	ds_read_b128 v[130:133], v58 offset:24576
	s_waitcnt lgkmcnt(7)
	v_pk_fma_f32 v[70:71], v[160:161], v[134:135], v[70:71] op_sel_hi:[0,1,1]
	v_pk_fma_f32 v[86:87], v[164:165], v[134:135], v[86:87] op_sel_hi:[0,1,1]
	v_pk_fma_f32 v[104:105], v[168:169], v[134:135], v[104:105] op_sel_hi:[0,1,1]
	v_pk_fma_f32 v[120:121], v[172:173], v[134:135], v[120:121] op_sel_hi:[0,1,1]
	v_pk_fma_f32 v[72:73], v[160:161], v[136:137], v[72:73] op_sel_hi:[0,1,1]
	v_pk_fma_f32 v[88:89], v[164:165], v[136:137], v[88:89] op_sel_hi:[0,1,1]
	v_pk_fma_f32 v[106:107], v[168:169], v[136:137], v[106:107] op_sel_hi:[0,1,1]
	v_pk_fma_f32 v[122:123], v[172:173], v[136:137], v[122:123] op_sel_hi:[0,1,1]
	ds_read_b128 v[134:137], v59 offset:24576
	s_waitcnt lgkmcnt(7)
	v_pk_fma_f32 v[74:75], v[160:161], v[138:139], v[74:75] op_sel_hi:[0,1,1]
	v_pk_fma_f32 v[90:91], v[164:165], v[138:139], v[90:91] op_sel_hi:[0,1,1]
	v_pk_fma_f32 v[108:109], v[168:169], v[138:139], v[108:109] op_sel_hi:[0,1,1]
	v_pk_fma_f32 v[24:25], v[172:173], v[138:139], v[24:25] op_sel_hi:[0,1,1]
	v_pk_fma_f32 v[76:77], v[160:161], v[140:141], v[76:77] op_sel_hi:[0,1,1]
	v_pk_fma_f32 v[94:95], v[164:165], v[140:141], v[94:95] op_sel_hi:[0,1,1]
	v_pk_fma_f32 v[110:111], v[168:169], v[140:141], v[110:111] op_sel_hi:[0,1,1]
	v_pk_fma_f32 v[26:27], v[172:173], v[140:141], v[26:27] op_sel_hi:[0,1,1]
	ds_read_b128 v[138:141], v60 offset:24576
	s_waitcnt lgkmcnt(7)
	v_pk_fma_f32 v[78:79], v[160:161], v[142:143], v[78:79] op_sel_hi:[0,1,1]
	v_pk_fma_f32 v[96:97], v[164:165], v[142:143], v[96:97] op_sel_hi:[0,1,1]
	v_pk_fma_f32 v[112:113], v[168:169], v[142:143], v[112:113] op_sel_hi:[0,1,1]
	v_pk_fma_f32 v[28:29], v[172:173], v[142:143], v[28:29] op_sel_hi:[0,1,1]
	v_pk_fma_f32 v[80:81], v[160:161], v[144:145], v[80:81] op_sel_hi:[0,1,1]
	v_pk_fma_f32 v[98:99], v[164:165], v[144:145], v[98:99] op_sel_hi:[0,1,1]
	v_pk_fma_f32 v[114:115], v[168:169], v[144:145], v[114:115] op_sel_hi:[0,1,1]
	v_pk_fma_f32 v[30:31], v[172:173], v[144:145], v[30:31] op_sel_hi:[0,1,1]
	ds_read_b128 v[142:145], v61 offset:24576
	s_waitcnt lgkmcnt(7)
	v_pk_fma_f32 v[66:67], v[160:161], v[146:147], v[66:67] op_sel:[1,0,0]
	v_pk_fma_f32 v[82:83], v[164:165], v[146:147], v[82:83] op_sel:[1,0,0]
	v_pk_fma_f32 v[100:101], v[168:169], v[146:147], v[100:101] op_sel:[1,0,0]
	v_pk_fma_f32 v[116:117], v[172:173], v[146:147], v[116:117] op_sel:[1,0,0]
	v_pk_fma_f32 v[68:69], v[160:161], v[148:149], v[68:69] op_sel:[1,0,0]
	v_pk_fma_f32 v[84:85], v[164:165], v[148:149], v[84:85] op_sel:[1,0,0]
	v_pk_fma_f32 v[102:103], v[168:169], v[148:149], v[102:103] op_sel:[1,0,0]
	v_pk_fma_f32 v[118:119], v[172:173], v[148:149], v[118:119] op_sel:[1,0,0]
	ds_read_b128 v[146:149], v58 offset:28672
	s_waitcnt lgkmcnt(7)
	v_pk_fma_f32 v[70:71], v[160:161], v[150:151], v[70:71] op_sel:[1,0,0]
	v_pk_fma_f32 v[86:87], v[164:165], v[150:151], v[86:87] op_sel:[1,0,0]
	v_pk_fma_f32 v[104:105], v[168:169], v[150:151], v[104:105] op_sel:[1,0,0]
	v_pk_fma_f32 v[120:121], v[172:173], v[150:151], v[120:121] op_sel:[1,0,0]
	v_pk_fma_f32 v[72:73], v[160:161], v[152:153], v[72:73] op_sel:[1,0,0]
	v_pk_fma_f32 v[88:89], v[164:165], v[152:153], v[88:89] op_sel:[1,0,0]
	v_pk_fma_f32 v[106:107], v[168:169], v[152:153], v[106:107] op_sel:[1,0,0]
	v_pk_fma_f32 v[122:123], v[172:173], v[152:153], v[122:123] op_sel:[1,0,0]
	ds_read_b128 v[150:153], v59 offset:28672
	s_waitcnt lgkmcnt(7)
	v_pk_fma_f32 v[74:75], v[160:161], v[154:155], v[74:75] op_sel:[1,0,0]
	v_pk_fma_f32 v[90:91], v[164:165], v[154:155], v[90:91] op_sel:[1,0,0]
	v_pk_fma_f32 v[108:109], v[168:169], v[154:155], v[108:109] op_sel:[1,0,0]
	v_pk_fma_f32 v[24:25], v[172:173], v[154:155], v[24:25] op_sel:[1,0,0]
	v_pk_fma_f32 v[76:77], v[160:161], v[156:157], v[76:77] op_sel:[1,0,0]
	v_pk_fma_f32 v[94:95], v[164:165], v[156:157], v[94:95] op_sel:[1,0,0]
	v_pk_fma_f32 v[110:111], v[168:169], v[156:157], v[110:111] op_sel:[1,0,0]
	v_pk_fma_f32 v[26:27], v[172:173], v[156:157], v[26:27] op_sel:[1,0,0]
	ds_read_b128 v[154:157], v60 offset:28672
	s_waitcnt lgkmcnt(7)
	v_pk_fma_f32 v[78:79], v[160:161], v[44:45], v[78:79] op_sel:[1,0,0]
	v_pk_fma_f32 v[96:97], v[164:165], v[44:45], v[96:97] op_sel:[1,0,0]
	v_pk_fma_f32 v[112:113], v[168:169], v[44:45], v[112:113] op_sel:[1,0,0]
	v_pk_fma_f32 v[28:29], v[172:173], v[44:45], v[28:29] op_sel:[1,0,0]
	v_pk_fma_f32 v[80:81], v[160:161], v[46:47], v[80:81] op_sel:[1,0,0]
	v_pk_fma_f32 v[98:99], v[164:165], v[46:47], v[98:99] op_sel:[1,0,0]
	v_pk_fma_f32 v[114:115], v[168:169], v[46:47], v[114:115] op_sel:[1,0,0]
	v_pk_fma_f32 v[30:31], v[172:173], v[46:47], v[30:31] op_sel:[1,0,0]
	ds_read_b128 v[44:47], v61 offset:28672
	s_waitcnt lgkmcnt(7)
	v_pk_fma_f32 v[66:67], v[162:163], v[130:131], v[66:67] op_sel_hi:[0,1,1]
	v_pk_fma_f32 v[82:83], v[166:167], v[130:131], v[82:83] op_sel_hi:[0,1,1]
	v_pk_fma_f32 v[100:101], v[170:171], v[130:131], v[100:101] op_sel_hi:[0,1,1]
	v_pk_fma_f32 v[116:117], v[174:175], v[130:131], v[116:117] op_sel_hi:[0,1,1]
	v_pk_fma_f32 v[68:69], v[162:163], v[132:133], v[68:69] op_sel_hi:[0,1,1]
	v_pk_fma_f32 v[84:85], v[166:167], v[132:133], v[84:85] op_sel_hi:[0,1,1]
	v_pk_fma_f32 v[102:103], v[170:171], v[132:133], v[102:103] op_sel_hi:[0,1,1]
	v_pk_fma_f32 v[118:119], v[174:175], v[132:133], v[118:119] op_sel_hi:[0,1,1]
	ds_read_b128 v[130:133], v58 offset:32768
	s_waitcnt lgkmcnt(7)
	v_pk_fma_f32 v[70:71], v[162:163], v[134:135], v[70:71] op_sel_hi:[0,1,1]
	v_pk_fma_f32 v[86:87], v[166:167], v[134:135], v[86:87] op_sel_hi:[0,1,1]
	v_pk_fma_f32 v[104:105], v[170:171], v[134:135], v[104:105] op_sel_hi:[0,1,1]
	v_pk_fma_f32 v[120:121], v[174:175], v[134:135], v[120:121] op_sel_hi:[0,1,1]
	v_pk_fma_f32 v[72:73], v[162:163], v[136:137], v[72:73] op_sel_hi:[0,1,1]
	v_pk_fma_f32 v[88:89], v[166:167], v[136:137], v[88:89] op_sel_hi:[0,1,1]
	v_pk_fma_f32 v[106:107], v[170:171], v[136:137], v[106:107] op_sel_hi:[0,1,1]
	v_pk_fma_f32 v[122:123], v[174:175], v[136:137], v[122:123] op_sel_hi:[0,1,1]
	ds_read_b128 v[134:137], v59 offset:32768
	s_waitcnt lgkmcnt(7)
	v_pk_fma_f32 v[74:75], v[162:163], v[138:139], v[74:75] op_sel_hi:[0,1,1]
	v_pk_fma_f32 v[90:91], v[166:167], v[138:139], v[90:91] op_sel_hi:[0,1,1]
	v_pk_fma_f32 v[108:109], v[170:171], v[138:139], v[108:109] op_sel_hi:[0,1,1]
	v_pk_fma_f32 v[24:25], v[174:175], v[138:139], v[24:25] op_sel_hi:[0,1,1]
	v_pk_fma_f32 v[76:77], v[162:163], v[140:141], v[76:77] op_sel_hi:[0,1,1]
	v_pk_fma_f32 v[94:95], v[166:167], v[140:141], v[94:95] op_sel_hi:[0,1,1]
	v_pk_fma_f32 v[110:111], v[170:171], v[140:141], v[110:111] op_sel_hi:[0,1,1]
	v_pk_fma_f32 v[26:27], v[174:175], v[140:141], v[26:27] op_sel_hi:[0,1,1]
	ds_read_b128 v[138:141], v60 offset:32768
	s_waitcnt lgkmcnt(7)
	v_pk_fma_f32 v[78:79], v[162:163], v[142:143], v[78:79] op_sel_hi:[0,1,1]
	v_pk_fma_f32 v[96:97], v[166:167], v[142:143], v[96:97] op_sel_hi:[0,1,1]
	v_pk_fma_f32 v[112:113], v[170:171], v[142:143], v[112:113] op_sel_hi:[0,1,1]
	v_pk_fma_f32 v[28:29], v[174:175], v[142:143], v[28:29] op_sel_hi:[0,1,1]
	v_pk_fma_f32 v[80:81], v[162:163], v[144:145], v[80:81] op_sel_hi:[0,1,1]
	v_pk_fma_f32 v[98:99], v[166:167], v[144:145], v[98:99] op_sel_hi:[0,1,1]
	v_pk_fma_f32 v[114:115], v[170:171], v[144:145], v[114:115] op_sel_hi:[0,1,1]
	v_pk_fma_f32 v[30:31], v[174:175], v[144:145], v[30:31] op_sel_hi:[0,1,1]
	ds_read_b128 v[142:145], v61 offset:32768
	s_waitcnt lgkmcnt(7)
	v_pk_fma_f32 v[66:67], v[162:163], v[146:147], v[66:67] op_sel:[1,0,0]
	v_pk_fma_f32 v[82:83], v[166:167], v[146:147], v[82:83] op_sel:[1,0,0]
	v_pk_fma_f32 v[100:101], v[170:171], v[146:147], v[100:101] op_sel:[1,0,0]
	v_pk_fma_f32 v[116:117], v[174:175], v[146:147], v[116:117] op_sel:[1,0,0]
	v_pk_fma_f32 v[68:69], v[162:163], v[148:149], v[68:69] op_sel:[1,0,0]
	v_pk_fma_f32 v[84:85], v[166:167], v[148:149], v[84:85] op_sel:[1,0,0]
	v_pk_fma_f32 v[102:103], v[170:171], v[148:149], v[102:103] op_sel:[1,0,0]
	v_pk_fma_f32 v[118:119], v[174:175], v[148:149], v[118:119] op_sel:[1,0,0]
	ds_read_b128 v[146:149], v58 offset:36864
	s_waitcnt lgkmcnt(7)
	v_pk_fma_f32 v[70:71], v[162:163], v[150:151], v[70:71] op_sel:[1,0,0]
	v_pk_fma_f32 v[86:87], v[166:167], v[150:151], v[86:87] op_sel:[1,0,0]
	v_pk_fma_f32 v[104:105], v[170:171], v[150:151], v[104:105] op_sel:[1,0,0]
	v_pk_fma_f32 v[120:121], v[174:175], v[150:151], v[120:121] op_sel:[1,0,0]
	v_pk_fma_f32 v[72:73], v[162:163], v[152:153], v[72:73] op_sel:[1,0,0]
	v_pk_fma_f32 v[88:89], v[166:167], v[152:153], v[88:89] op_sel:[1,0,0]
	v_pk_fma_f32 v[106:107], v[170:171], v[152:153], v[106:107] op_sel:[1,0,0]
	v_pk_fma_f32 v[122:123], v[174:175], v[152:153], v[122:123] op_sel:[1,0,0]
	ds_read_b128 v[150:153], v59 offset:36864
	s_waitcnt lgkmcnt(7)
	v_pk_fma_f32 v[74:75], v[162:163], v[154:155], v[74:75] op_sel:[1,0,0]
	v_pk_fma_f32 v[90:91], v[166:167], v[154:155], v[90:91] op_sel:[1,0,0]
	v_pk_fma_f32 v[108:109], v[170:171], v[154:155], v[108:109] op_sel:[1,0,0]
	v_pk_fma_f32 v[24:25], v[174:175], v[154:155], v[24:25] op_sel:[1,0,0]
	v_pk_fma_f32 v[76:77], v[162:163], v[156:157], v[76:77] op_sel:[1,0,0]
	v_pk_fma_f32 v[94:95], v[166:167], v[156:157], v[94:95] op_sel:[1,0,0]
	v_pk_fma_f32 v[110:111], v[170:171], v[156:157], v[110:111] op_sel:[1,0,0]
	v_pk_fma_f32 v[26:27], v[174:175], v[156:157], v[26:27] op_sel:[1,0,0]
	ds_read_b128 v[154:157], v60 offset:36864
	s_waitcnt lgkmcnt(7)
	v_pk_fma_f32 v[78:79], v[162:163], v[44:45], v[78:79] op_sel:[1,0,0]
	v_pk_fma_f32 v[96:97], v[166:167], v[44:45], v[96:97] op_sel:[1,0,0]
	v_pk_fma_f32 v[112:113], v[170:171], v[44:45], v[112:113] op_sel:[1,0,0]
	v_pk_fma_f32 v[28:29], v[174:175], v[44:45], v[28:29] op_sel:[1,0,0]
	v_pk_fma_f32 v[80:81], v[162:163], v[46:47], v[80:81] op_sel:[1,0,0]
	v_pk_fma_f32 v[98:99], v[166:167], v[46:47], v[98:99] op_sel:[1,0,0]
	v_pk_fma_f32 v[114:115], v[170:171], v[46:47], v[114:115] op_sel:[1,0,0]
	v_pk_fma_f32 v[30:31], v[174:175], v[46:47], v[30:31] op_sel:[1,0,0]
	ds_read_b128 v[44:47], v61 offset:36864
	s_waitcnt vmcnt(23)
	v_cvt_pk_bf16_f32 v244, v176, v177
	v_cvt_pk_bf16_f32 v245, v178, v179
	global_store_dwordx2 v[14:15], v[244:245], off offset:3072
	v_pk_mul_f32 v[22:23], v[176:177], v[176:177]
	v_pk_fma_f32 v[22:23], v[178:179], v[178:179], v[22:23]
	v_add_f32_e32 v22, v22, v23
	v_add_f32_e32 v240, v240, v22
	s_waitcnt vmcnt(23)
	v_cvt_pk_bf16_f32 v246, v180, v181
	v_cvt_pk_bf16_f32 v247, v182, v183
	global_store_dwordx2 v[16:17], v[246:247], off offset:3072
	v_pk_mul_f32 v[22:23], v[180:181], v[180:181]
	v_pk_fma_f32 v[22:23], v[182:183], v[182:183], v[22:23]
	v_add_f32_e32 v22, v22, v23
	v_add_f32_e32 v241, v241, v22
	s_waitcnt vmcnt(23)
	v_cvt_pk_bf16_f32 v248, v184, v185
	v_cvt_pk_bf16_f32 v249, v186, v187
	global_store_dwordx2 v[18:19], v[248:249], off offset:3072
	v_pk_mul_f32 v[22:23], v[184:185], v[184:185]
	v_pk_fma_f32 v[22:23], v[186:187], v[186:187], v[22:23]
	v_add_f32_e32 v22, v22, v23
	v_add_f32_e32 v242, v242, v22
	s_waitcnt vmcnt(23)
	v_cvt_pk_bf16_f32 v232, v188, v189
	v_cvt_pk_bf16_f32 v233, v190, v191
	global_store_dwordx2 v[20:21], v[232:233], off offset:3072
	v_pk_mul_f32 v[22:23], v[188:189], v[188:189]
	v_pk_fma_f32 v[22:23], v[190:191], v[190:191], v[22:23]
	v_add_f32_e32 v22, v22, v23
	v_add_f32_e32 v243, v243, v22
	s_waitcnt lgkmcnt(7)
	v_pk_fma_f32 v[66:67], v[176:177], v[130:131], v[66:67] op_sel_hi:[0,1,1]
	v_pk_fma_f32 v[82:83], v[180:181], v[130:131], v[82:83] op_sel_hi:[0,1,1]
	v_pk_fma_f32 v[100:101], v[184:185], v[130:131], v[100:101] op_sel_hi:[0,1,1]
	v_pk_fma_f32 v[116:117], v[188:189], v[130:131], v[116:117] op_sel_hi:[0,1,1]
	v_pk_fma_f32 v[68:69], v[176:177], v[132:133], v[68:69] op_sel_hi:[0,1,1]
	v_pk_fma_f32 v[84:85], v[180:181], v[132:133], v[84:85] op_sel_hi:[0,1,1]
	v_pk_fma_f32 v[102:103], v[184:185], v[132:133], v[102:103] op_sel_hi:[0,1,1]
	v_pk_fma_f32 v[118:119], v[188:189], v[132:133], v[118:119] op_sel_hi:[0,1,1]
	ds_read_b128 v[130:133], v58 offset:40960
	s_waitcnt lgkmcnt(7)
	v_pk_fma_f32 v[70:71], v[176:177], v[134:135], v[70:71] op_sel_hi:[0,1,1]
	v_pk_fma_f32 v[86:87], v[180:181], v[134:135], v[86:87] op_sel_hi:[0,1,1]
	v_pk_fma_f32 v[104:105], v[184:185], v[134:135], v[104:105] op_sel_hi:[0,1,1]
	v_pk_fma_f32 v[120:121], v[188:189], v[134:135], v[120:121] op_sel_hi:[0,1,1]
	v_pk_fma_f32 v[72:73], v[176:177], v[136:137], v[72:73] op_sel_hi:[0,1,1]
	v_pk_fma_f32 v[88:89], v[180:181], v[136:137], v[88:89] op_sel_hi:[0,1,1]
	v_pk_fma_f32 v[106:107], v[184:185], v[136:137], v[106:107] op_sel_hi:[0,1,1]
	v_pk_fma_f32 v[122:123], v[188:189], v[136:137], v[122:123] op_sel_hi:[0,1,1]
	ds_read_b128 v[134:137], v59 offset:40960
	s_waitcnt lgkmcnt(7)
	v_pk_fma_f32 v[74:75], v[176:177], v[138:139], v[74:75] op_sel_hi:[0,1,1]
	v_pk_fma_f32 v[90:91], v[180:181], v[138:139], v[90:91] op_sel_hi:[0,1,1]
	v_pk_fma_f32 v[108:109], v[184:185], v[138:139], v[108:109] op_sel_hi:[0,1,1]
	v_pk_fma_f32 v[24:25], v[188:189], v[138:139], v[24:25] op_sel_hi:[0,1,1]
	v_pk_fma_f32 v[76:77], v[176:177], v[140:141], v[76:77] op_sel_hi:[0,1,1]
	v_pk_fma_f32 v[94:95], v[180:181], v[140:141], v[94:95] op_sel_hi:[0,1,1]
	v_pk_fma_f32 v[110:111], v[184:185], v[140:141], v[110:111] op_sel_hi:[0,1,1]
	v_pk_fma_f32 v[26:27], v[188:189], v[140:141], v[26:27] op_sel_hi:[0,1,1]
	ds_read_b128 v[138:141], v60 offset:40960
	s_waitcnt lgkmcnt(7)
	v_pk_fma_f32 v[78:79], v[176:177], v[142:143], v[78:79] op_sel_hi:[0,1,1]
	v_pk_fma_f32 v[96:97], v[180:181], v[142:143], v[96:97] op_sel_hi:[0,1,1]
	v_pk_fma_f32 v[112:113], v[184:185], v[142:143], v[112:113] op_sel_hi:[0,1,1]
	v_pk_fma_f32 v[28:29], v[188:189], v[142:143], v[28:29] op_sel_hi:[0,1,1]
	v_pk_fma_f32 v[80:81], v[176:177], v[144:145], v[80:81] op_sel_hi:[0,1,1]
	v_pk_fma_f32 v[98:99], v[180:181], v[144:145], v[98:99] op_sel_hi:[0,1,1]
	v_pk_fma_f32 v[114:115], v[184:185], v[144:145], v[114:115] op_sel_hi:[0,1,1]
	v_pk_fma_f32 v[30:31], v[188:189], v[144:145], v[30:31] op_sel_hi:[0,1,1]
	ds_read_b128 v[142:145], v61 offset:40960
	s_waitcnt lgkmcnt(7)
	v_pk_fma_f32 v[66:67], v[176:177], v[146:147], v[66:67] op_sel:[1,0,0]
	v_pk_fma_f32 v[82:83], v[180:181], v[146:147], v[82:83] op_sel:[1,0,0]
	v_pk_fma_f32 v[100:101], v[184:185], v[146:147], v[100:101] op_sel:[1,0,0]
	v_pk_fma_f32 v[116:117], v[188:189], v[146:147], v[116:117] op_sel:[1,0,0]
	v_pk_fma_f32 v[68:69], v[176:177], v[148:149], v[68:69] op_sel:[1,0,0]
	v_pk_fma_f32 v[84:85], v[180:181], v[148:149], v[84:85] op_sel:[1,0,0]
	v_pk_fma_f32 v[102:103], v[184:185], v[148:149], v[102:103] op_sel:[1,0,0]
	v_pk_fma_f32 v[118:119], v[188:189], v[148:149], v[118:119] op_sel:[1,0,0]
	ds_read_b128 v[146:149], v58 offset:45056
	s_waitcnt lgkmcnt(7)
	v_pk_fma_f32 v[70:71], v[176:177], v[150:151], v[70:71] op_sel:[1,0,0]
	v_pk_fma_f32 v[86:87], v[180:181], v[150:151], v[86:87] op_sel:[1,0,0]
	v_pk_fma_f32 v[104:105], v[184:185], v[150:151], v[104:105] op_sel:[1,0,0]
	v_pk_fma_f32 v[120:121], v[188:189], v[150:151], v[120:121] op_sel:[1,0,0]
	v_pk_fma_f32 v[72:73], v[176:177], v[152:153], v[72:73] op_sel:[1,0,0]
	v_pk_fma_f32 v[88:89], v[180:181], v[152:153], v[88:89] op_sel:[1,0,0]
	v_pk_fma_f32 v[106:107], v[184:185], v[152:153], v[106:107] op_sel:[1,0,0]
	v_pk_fma_f32 v[122:123], v[188:189], v[152:153], v[122:123] op_sel:[1,0,0]
	ds_read_b128 v[150:153], v59 offset:45056
	s_waitcnt lgkmcnt(7)
	v_pk_fma_f32 v[74:75], v[176:177], v[154:155], v[74:75] op_sel:[1,0,0]
	v_pk_fma_f32 v[90:91], v[180:181], v[154:155], v[90:91] op_sel:[1,0,0]
	v_pk_fma_f32 v[108:109], v[184:185], v[154:155], v[108:109] op_sel:[1,0,0]
	v_pk_fma_f32 v[24:25], v[188:189], v[154:155], v[24:25] op_sel:[1,0,0]
	v_pk_fma_f32 v[76:77], v[176:177], v[156:157], v[76:77] op_sel:[1,0,0]
	v_pk_fma_f32 v[94:95], v[180:181], v[156:157], v[94:95] op_sel:[1,0,0]
	v_pk_fma_f32 v[110:111], v[184:185], v[156:157], v[110:111] op_sel:[1,0,0]
	v_pk_fma_f32 v[26:27], v[188:189], v[156:157], v[26:27] op_sel:[1,0,0]
	ds_read_b128 v[154:157], v60 offset:45056
	s_waitcnt lgkmcnt(7)
	v_pk_fma_f32 v[78:79], v[176:177], v[44:45], v[78:79] op_sel:[1,0,0]
	v_pk_fma_f32 v[96:97], v[180:181], v[44:45], v[96:97] op_sel:[1,0,0]
	v_pk_fma_f32 v[112:113], v[184:185], v[44:45], v[112:113] op_sel:[1,0,0]
	v_pk_fma_f32 v[28:29], v[188:189], v[44:45], v[28:29] op_sel:[1,0,0]
	v_pk_fma_f32 v[80:81], v[176:177], v[46:47], v[80:81] op_sel:[1,0,0]
	v_pk_fma_f32 v[98:99], v[180:181], v[46:47], v[98:99] op_sel:[1,0,0]
	v_pk_fma_f32 v[114:115], v[184:185], v[46:47], v[114:115] op_sel:[1,0,0]
	v_pk_fma_f32 v[30:31], v[188:189], v[46:47], v[30:31] op_sel:[1,0,0]
	ds_read_b128 v[44:47], v61 offset:45056
	s_waitcnt lgkmcnt(7)
	v_pk_fma_f32 v[66:67], v[178:179], v[130:131], v[66:67] op_sel_hi:[0,1,1]
	v_pk_fma_f32 v[82:83], v[182:183], v[130:131], v[82:83] op_sel_hi:[0,1,1]
	v_pk_fma_f32 v[100:101], v[186:187], v[130:131], v[100:101] op_sel_hi:[0,1,1]
	v_pk_fma_f32 v[116:117], v[190:191], v[130:131], v[116:117] op_sel_hi:[0,1,1]
	v_pk_fma_f32 v[68:69], v[178:179], v[132:133], v[68:69] op_sel_hi:[0,1,1]
	v_pk_fma_f32 v[84:85], v[182:183], v[132:133], v[84:85] op_sel_hi:[0,1,1]
	v_pk_fma_f32 v[102:103], v[186:187], v[132:133], v[102:103] op_sel_hi:[0,1,1]
	v_pk_fma_f32 v[118:119], v[190:191], v[132:133], v[118:119] op_sel_hi:[0,1,1]
	ds_read_b128 v[130:133], v58 offset:49152
	s_waitcnt lgkmcnt(7)
	v_pk_fma_f32 v[70:71], v[178:179], v[134:135], v[70:71] op_sel_hi:[0,1,1]
	v_pk_fma_f32 v[86:87], v[182:183], v[134:135], v[86:87] op_sel_hi:[0,1,1]
	v_pk_fma_f32 v[104:105], v[186:187], v[134:135], v[104:105] op_sel_hi:[0,1,1]
	v_pk_fma_f32 v[120:121], v[190:191], v[134:135], v[120:121] op_sel_hi:[0,1,1]
	v_pk_fma_f32 v[72:73], v[178:179], v[136:137], v[72:73] op_sel_hi:[0,1,1]
	v_pk_fma_f32 v[88:89], v[182:183], v[136:137], v[88:89] op_sel_hi:[0,1,1]
	v_pk_fma_f32 v[106:107], v[186:187], v[136:137], v[106:107] op_sel_hi:[0,1,1]
	v_pk_fma_f32 v[122:123], v[190:191], v[136:137], v[122:123] op_sel_hi:[0,1,1]
	ds_read_b128 v[134:137], v59 offset:49152
	s_waitcnt lgkmcnt(7)
	v_pk_fma_f32 v[74:75], v[178:179], v[138:139], v[74:75] op_sel_hi:[0,1,1]
	v_pk_fma_f32 v[90:91], v[182:183], v[138:139], v[90:91] op_sel_hi:[0,1,1]
	v_pk_fma_f32 v[108:109], v[186:187], v[138:139], v[108:109] op_sel_hi:[0,1,1]
	v_pk_fma_f32 v[24:25], v[190:191], v[138:139], v[24:25] op_sel_hi:[0,1,1]
	v_pk_fma_f32 v[76:77], v[178:179], v[140:141], v[76:77] op_sel_hi:[0,1,1]
	v_pk_fma_f32 v[94:95], v[182:183], v[140:141], v[94:95] op_sel_hi:[0,1,1]
	v_pk_fma_f32 v[110:111], v[186:187], v[140:141], v[110:111] op_sel_hi:[0,1,1]
	v_pk_fma_f32 v[26:27], v[190:191], v[140:141], v[26:27] op_sel_hi:[0,1,1]
	ds_read_b128 v[138:141], v60 offset:49152
	s_waitcnt lgkmcnt(7)
	v_pk_fma_f32 v[78:79], v[178:179], v[142:143], v[78:79] op_sel_hi:[0,1,1]
	v_pk_fma_f32 v[96:97], v[182:183], v[142:143], v[96:97] op_sel_hi:[0,1,1]
	v_pk_fma_f32 v[112:113], v[186:187], v[142:143], v[112:113] op_sel_hi:[0,1,1]
	v_pk_fma_f32 v[28:29], v[190:191], v[142:143], v[28:29] op_sel_hi:[0,1,1]
	v_pk_fma_f32 v[80:81], v[178:179], v[144:145], v[80:81] op_sel_hi:[0,1,1]
	v_pk_fma_f32 v[98:99], v[182:183], v[144:145], v[98:99] op_sel_hi:[0,1,1]
	v_pk_fma_f32 v[114:115], v[186:187], v[144:145], v[114:115] op_sel_hi:[0,1,1]
	v_pk_fma_f32 v[30:31], v[190:191], v[144:145], v[30:31] op_sel_hi:[0,1,1]
	ds_read_b128 v[142:145], v61 offset:49152
	s_waitcnt lgkmcnt(7)
	v_pk_fma_f32 v[66:67], v[178:179], v[146:147], v[66:67] op_sel:[1,0,0]
	v_pk_fma_f32 v[82:83], v[182:183], v[146:147], v[82:83] op_sel:[1,0,0]
	v_pk_fma_f32 v[100:101], v[186:187], v[146:147], v[100:101] op_sel:[1,0,0]
	v_pk_fma_f32 v[116:117], v[190:191], v[146:147], v[116:117] op_sel:[1,0,0]
	v_pk_fma_f32 v[68:69], v[178:179], v[148:149], v[68:69] op_sel:[1,0,0]
	v_pk_fma_f32 v[84:85], v[182:183], v[148:149], v[84:85] op_sel:[1,0,0]
	v_pk_fma_f32 v[102:103], v[186:187], v[148:149], v[102:103] op_sel:[1,0,0]
	v_pk_fma_f32 v[118:119], v[190:191], v[148:149], v[118:119] op_sel:[1,0,0]
	ds_read_b128 v[146:149], v58 offset:53248
	s_waitcnt lgkmcnt(7)
	v_pk_fma_f32 v[70:71], v[178:179], v[150:151], v[70:71] op_sel:[1,0,0]
	v_pk_fma_f32 v[86:87], v[182:183], v[150:151], v[86:87] op_sel:[1,0,0]
	v_pk_fma_f32 v[104:105], v[186:187], v[150:151], v[104:105] op_sel:[1,0,0]
	v_pk_fma_f32 v[120:121], v[190:191], v[150:151], v[120:121] op_sel:[1,0,0]
	v_pk_fma_f32 v[72:73], v[178:179], v[152:153], v[72:73] op_sel:[1,0,0]
	v_pk_fma_f32 v[88:89], v[182:183], v[152:153], v[88:89] op_sel:[1,0,0]
	v_pk_fma_f32 v[106:107], v[186:187], v[152:153], v[106:107] op_sel:[1,0,0]
	v_pk_fma_f32 v[122:123], v[190:191], v[152:153], v[122:123] op_sel:[1,0,0]
	ds_read_b128 v[150:153], v59 offset:53248
	s_waitcnt lgkmcnt(7)
	v_pk_fma_f32 v[74:75], v[178:179], v[154:155], v[74:75] op_sel:[1,0,0]
	v_pk_fma_f32 v[90:91], v[182:183], v[154:155], v[90:91] op_sel:[1,0,0]
	v_pk_fma_f32 v[108:109], v[186:187], v[154:155], v[108:109] op_sel:[1,0,0]
	v_pk_fma_f32 v[24:25], v[190:191], v[154:155], v[24:25] op_sel:[1,0,0]
	v_pk_fma_f32 v[76:77], v[178:179], v[156:157], v[76:77] op_sel:[1,0,0]
	v_pk_fma_f32 v[94:95], v[182:183], v[156:157], v[94:95] op_sel:[1,0,0]
	v_pk_fma_f32 v[110:111], v[186:187], v[156:157], v[110:111] op_sel:[1,0,0]
	v_pk_fma_f32 v[26:27], v[190:191], v[156:157], v[26:27] op_sel:[1,0,0]
	ds_read_b128 v[154:157], v60 offset:53248
	s_waitcnt lgkmcnt(7)
	v_pk_fma_f32 v[78:79], v[178:179], v[44:45], v[78:79] op_sel:[1,0,0]
	v_pk_fma_f32 v[96:97], v[182:183], v[44:45], v[96:97] op_sel:[1,0,0]
	v_pk_fma_f32 v[112:113], v[186:187], v[44:45], v[112:113] op_sel:[1,0,0]
	v_pk_fma_f32 v[28:29], v[190:191], v[44:45], v[28:29] op_sel:[1,0,0]
	v_pk_fma_f32 v[80:81], v[178:179], v[46:47], v[80:81] op_sel:[1,0,0]
	v_pk_fma_f32 v[98:99], v[182:183], v[46:47], v[98:99] op_sel:[1,0,0]
	v_pk_fma_f32 v[114:115], v[186:187], v[46:47], v[114:115] op_sel:[1,0,0]
	v_pk_fma_f32 v[30:31], v[190:191], v[46:47], v[30:31] op_sel:[1,0,0]
	ds_read_b128 v[44:47], v61 offset:53248
	s_waitcnt vmcnt(19)
	v_cvt_pk_bf16_f32 v244, v192, v193
	v_cvt_pk_bf16_f32 v245, v194, v195
	global_store_dwordx2 v[14:15], v[244:245], off offset:3584
	v_pk_mul_f32 v[22:23], v[192:193], v[192:193]
	v_pk_fma_f32 v[22:23], v[194:195], v[194:195], v[22:23]
	v_add_f32_e32 v22, v22, v23
	v_add_f32_e32 v240, v240, v22
	s_waitcnt vmcnt(19)
	v_cvt_pk_bf16_f32 v246, v196, v197
	v_cvt_pk_bf16_f32 v247, v198, v199
	global_store_dwordx2 v[16:17], v[246:247], off offset:3584
	v_pk_mul_f32 v[22:23], v[196:197], v[196:197]
	v_pk_fma_f32 v[22:23], v[198:199], v[198:199], v[22:23]
	v_add_f32_e32 v22, v22, v23
	v_add_f32_e32 v241, v241, v22
	s_waitcnt vmcnt(19)
	v_cvt_pk_bf16_f32 v248, v200, v201
	v_cvt_pk_bf16_f32 v249, v202, v203
	global_store_dwordx2 v[18:19], v[248:249], off offset:3584
	v_pk_mul_f32 v[22:23], v[200:201], v[200:201]
	v_pk_fma_f32 v[22:23], v[202:203], v[202:203], v[22:23]
	v_add_f32_e32 v22, v22, v23
	v_add_f32_e32 v242, v242, v22
	s_waitcnt vmcnt(19)
	v_cvt_pk_bf16_f32 v232, v204, v205
	v_cvt_pk_bf16_f32 v233, v206, v207
	global_store_dwordx2 v[20:21], v[232:233], off offset:3584
	v_pk_mul_f32 v[22:23], v[204:205], v[204:205]
	v_pk_fma_f32 v[22:23], v[206:207], v[206:207], v[22:23]
	v_add_f32_e32 v22, v22, v23
	v_add_f32_e32 v243, v243, v22
	s_waitcnt lgkmcnt(7)
	v_pk_fma_f32 v[66:67], v[192:193], v[130:131], v[66:67] op_sel_hi:[0,1,1]
	v_pk_fma_f32 v[82:83], v[196:197], v[130:131], v[82:83] op_sel_hi:[0,1,1]
	v_pk_fma_f32 v[100:101], v[200:201], v[130:131], v[100:101] op_sel_hi:[0,1,1]
	v_pk_fma_f32 v[116:117], v[204:205], v[130:131], v[116:117] op_sel_hi:[0,1,1]
	v_pk_fma_f32 v[68:69], v[192:193], v[132:133], v[68:69] op_sel_hi:[0,1,1]
	v_pk_fma_f32 v[84:85], v[196:197], v[132:133], v[84:85] op_sel_hi:[0,1,1]
	v_pk_fma_f32 v[102:103], v[200:201], v[132:133], v[102:103] op_sel_hi:[0,1,1]
	v_pk_fma_f32 v[118:119], v[204:205], v[132:133], v[118:119] op_sel_hi:[0,1,1]
	ds_read_b128 v[130:133], v58 offset:57344
	s_waitcnt lgkmcnt(7)
	v_pk_fma_f32 v[70:71], v[192:193], v[134:135], v[70:71] op_sel_hi:[0,1,1]
	v_pk_fma_f32 v[86:87], v[196:197], v[134:135], v[86:87] op_sel_hi:[0,1,1]
	v_pk_fma_f32 v[104:105], v[200:201], v[134:135], v[104:105] op_sel_hi:[0,1,1]
	v_pk_fma_f32 v[120:121], v[204:205], v[134:135], v[120:121] op_sel_hi:[0,1,1]
	v_pk_fma_f32 v[72:73], v[192:193], v[136:137], v[72:73] op_sel_hi:[0,1,1]
	v_pk_fma_f32 v[88:89], v[196:197], v[136:137], v[88:89] op_sel_hi:[0,1,1]
	v_pk_fma_f32 v[106:107], v[200:201], v[136:137], v[106:107] op_sel_hi:[0,1,1]
	v_pk_fma_f32 v[122:123], v[204:205], v[136:137], v[122:123] op_sel_hi:[0,1,1]
	ds_read_b128 v[134:137], v59 offset:57344
	s_waitcnt lgkmcnt(7)
	v_pk_fma_f32 v[74:75], v[192:193], v[138:139], v[74:75] op_sel_hi:[0,1,1]
	v_pk_fma_f32 v[90:91], v[196:197], v[138:139], v[90:91] op_sel_hi:[0,1,1]
	v_pk_fma_f32 v[108:109], v[200:201], v[138:139], v[108:109] op_sel_hi:[0,1,1]
	v_pk_fma_f32 v[24:25], v[204:205], v[138:139], v[24:25] op_sel_hi:[0,1,1]
	v_pk_fma_f32 v[76:77], v[192:193], v[140:141], v[76:77] op_sel_hi:[0,1,1]
	v_pk_fma_f32 v[94:95], v[196:197], v[140:141], v[94:95] op_sel_hi:[0,1,1]
	v_pk_fma_f32 v[110:111], v[200:201], v[140:141], v[110:111] op_sel_hi:[0,1,1]
	v_pk_fma_f32 v[26:27], v[204:205], v[140:141], v[26:27] op_sel_hi:[0,1,1]
	ds_read_b128 v[138:141], v60 offset:57344
	s_waitcnt lgkmcnt(7)
	v_pk_fma_f32 v[78:79], v[192:193], v[142:143], v[78:79] op_sel_hi:[0,1,1]
	v_pk_fma_f32 v[96:97], v[196:197], v[142:143], v[96:97] op_sel_hi:[0,1,1]
	v_pk_fma_f32 v[112:113], v[200:201], v[142:143], v[112:113] op_sel_hi:[0,1,1]
	v_pk_fma_f32 v[28:29], v[204:205], v[142:143], v[28:29] op_sel_hi:[0,1,1]
	v_pk_fma_f32 v[80:81], v[192:193], v[144:145], v[80:81] op_sel_hi:[0,1,1]
	v_pk_fma_f32 v[98:99], v[196:197], v[144:145], v[98:99] op_sel_hi:[0,1,1]
	v_pk_fma_f32 v[114:115], v[200:201], v[144:145], v[114:115] op_sel_hi:[0,1,1]
	v_pk_fma_f32 v[30:31], v[204:205], v[144:145], v[30:31] op_sel_hi:[0,1,1]
	ds_read_b128 v[142:145], v61 offset:57344
	s_waitcnt lgkmcnt(7)
	v_pk_fma_f32 v[66:67], v[192:193], v[146:147], v[66:67] op_sel:[1,0,0]
	v_pk_fma_f32 v[82:83], v[196:197], v[146:147], v[82:83] op_sel:[1,0,0]
	v_pk_fma_f32 v[100:101], v[200:201], v[146:147], v[100:101] op_sel:[1,0,0]
	v_pk_fma_f32 v[116:117], v[204:205], v[146:147], v[116:117] op_sel:[1,0,0]
	v_pk_fma_f32 v[68:69], v[192:193], v[148:149], v[68:69] op_sel:[1,0,0]
	v_pk_fma_f32 v[84:85], v[196:197], v[148:149], v[84:85] op_sel:[1,0,0]
	v_pk_fma_f32 v[102:103], v[200:201], v[148:149], v[102:103] op_sel:[1,0,0]
	v_pk_fma_f32 v[118:119], v[204:205], v[148:149], v[118:119] op_sel:[1,0,0]
	ds_read_b128 v[146:149], v58 offset:61440
	s_waitcnt lgkmcnt(7)
	v_pk_fma_f32 v[70:71], v[192:193], v[150:151], v[70:71] op_sel:[1,0,0]
	v_pk_fma_f32 v[86:87], v[196:197], v[150:151], v[86:87] op_sel:[1,0,0]
	v_pk_fma_f32 v[104:105], v[200:201], v[150:151], v[104:105] op_sel:[1,0,0]
	v_pk_fma_f32 v[120:121], v[204:205], v[150:151], v[120:121] op_sel:[1,0,0]
	v_pk_fma_f32 v[72:73], v[192:193], v[152:153], v[72:73] op_sel:[1,0,0]
	v_pk_fma_f32 v[88:89], v[196:197], v[152:153], v[88:89] op_sel:[1,0,0]
	v_pk_fma_f32 v[106:107], v[200:201], v[152:153], v[106:107] op_sel:[1,0,0]
	v_pk_fma_f32 v[122:123], v[204:205], v[152:153], v[122:123] op_sel:[1,0,0]
	ds_read_b128 v[150:153], v59 offset:61440
	s_waitcnt lgkmcnt(7)
	v_pk_fma_f32 v[74:75], v[192:193], v[154:155], v[74:75] op_sel:[1,0,0]
	v_pk_fma_f32 v[90:91], v[196:197], v[154:155], v[90:91] op_sel:[1,0,0]
	v_pk_fma_f32 v[108:109], v[200:201], v[154:155], v[108:109] op_sel:[1,0,0]
	v_pk_fma_f32 v[24:25], v[204:205], v[154:155], v[24:25] op_sel:[1,0,0]
	v_pk_fma_f32 v[76:77], v[192:193], v[156:157], v[76:77] op_sel:[1,0,0]
	v_pk_fma_f32 v[94:95], v[196:197], v[156:157], v[94:95] op_sel:[1,0,0]
	v_pk_fma_f32 v[110:111], v[200:201], v[156:157], v[110:111] op_sel:[1,0,0]
	v_pk_fma_f32 v[26:27], v[204:205], v[156:157], v[26:27] op_sel:[1,0,0]
	ds_read_b128 v[154:157], v60 offset:61440
	s_waitcnt lgkmcnt(7)
	v_pk_fma_f32 v[78:79], v[192:193], v[44:45], v[78:79] op_sel:[1,0,0]
	v_pk_fma_f32 v[96:97], v[196:197], v[44:45], v[96:97] op_sel:[1,0,0]
	v_pk_fma_f32 v[112:113], v[200:201], v[44:45], v[112:113] op_sel:[1,0,0]
	v_pk_fma_f32 v[28:29], v[204:205], v[44:45], v[28:29] op_sel:[1,0,0]
	v_pk_fma_f32 v[80:81], v[192:193], v[46:47], v[80:81] op_sel:[1,0,0]
	v_pk_fma_f32 v[98:99], v[196:197], v[46:47], v[98:99] op_sel:[1,0,0]
	v_pk_fma_f32 v[114:115], v[200:201], v[46:47], v[114:115] op_sel:[1,0,0]
	v_pk_fma_f32 v[30:31], v[204:205], v[46:47], v[30:31] op_sel:[1,0,0]
	ds_read_b128 v[44:47], v61 offset:61440
	s_waitcnt lgkmcnt(7)
	v_pk_fma_f32 v[66:67], v[194:195], v[130:131], v[66:67] op_sel_hi:[0,1,1]
	v_pk_fma_f32 v[82:83], v[198:199], v[130:131], v[82:83] op_sel_hi:[0,1,1]
	v_pk_fma_f32 v[100:101], v[202:203], v[130:131], v[100:101] op_sel_hi:[0,1,1]
	v_pk_fma_f32 v[116:117], v[206:207], v[130:131], v[116:117] op_sel_hi:[0,1,1]
	v_pk_fma_f32 v[68:69], v[194:195], v[132:133], v[68:69] op_sel_hi:[0,1,1]
	v_pk_fma_f32 v[84:85], v[198:199], v[132:133], v[84:85] op_sel_hi:[0,1,1]
	v_pk_fma_f32 v[102:103], v[202:203], v[132:133], v[102:103] op_sel_hi:[0,1,1]
	v_pk_fma_f32 v[118:119], v[206:207], v[132:133], v[118:119] op_sel_hi:[0,1,1]
	s_waitcnt lgkmcnt(6)
	v_pk_fma_f32 v[70:71], v[194:195], v[134:135], v[70:71] op_sel_hi:[0,1,1]
	v_pk_fma_f32 v[86:87], v[198:199], v[134:135], v[86:87] op_sel_hi:[0,1,1]
	v_pk_fma_f32 v[104:105], v[202:203], v[134:135], v[104:105] op_sel_hi:[0,1,1]
	v_pk_fma_f32 v[120:121], v[206:207], v[134:135], v[120:121] op_sel_hi:[0,1,1]
	v_pk_fma_f32 v[72:73], v[194:195], v[136:137], v[72:73] op_sel_hi:[0,1,1]
	v_pk_fma_f32 v[88:89], v[198:199], v[136:137], v[88:89] op_sel_hi:[0,1,1]
	v_pk_fma_f32 v[106:107], v[202:203], v[136:137], v[106:107] op_sel_hi:[0,1,1]
	v_pk_fma_f32 v[122:123], v[206:207], v[136:137], v[122:123] op_sel_hi:[0,1,1]
	s_waitcnt lgkmcnt(5)
	v_pk_fma_f32 v[74:75], v[194:195], v[138:139], v[74:75] op_sel_hi:[0,1,1]
	v_pk_fma_f32 v[90:91], v[198:199], v[138:139], v[90:91] op_sel_hi:[0,1,1]
	v_pk_fma_f32 v[108:109], v[202:203], v[138:139], v[108:109] op_sel_hi:[0,1,1]
	v_pk_fma_f32 v[24:25], v[206:207], v[138:139], v[24:25] op_sel_hi:[0,1,1]
	v_pk_fma_f32 v[76:77], v[194:195], v[140:141], v[76:77] op_sel_hi:[0,1,1]
	v_pk_fma_f32 v[94:95], v[198:199], v[140:141], v[94:95] op_sel_hi:[0,1,1]
	v_pk_fma_f32 v[110:111], v[202:203], v[140:141], v[110:111] op_sel_hi:[0,1,1]
	v_pk_fma_f32 v[26:27], v[206:207], v[140:141], v[26:27] op_sel_hi:[0,1,1]
	s_waitcnt lgkmcnt(4)
	v_pk_fma_f32 v[78:79], v[194:195], v[142:143], v[78:79] op_sel_hi:[0,1,1]
	v_pk_fma_f32 v[96:97], v[198:199], v[142:143], v[96:97] op_sel_hi:[0,1,1]
	v_pk_fma_f32 v[112:113], v[202:203], v[142:143], v[112:113] op_sel_hi:[0,1,1]
	v_pk_fma_f32 v[28:29], v[206:207], v[142:143], v[28:29] op_sel_hi:[0,1,1]
	v_pk_fma_f32 v[80:81], v[194:195], v[144:145], v[80:81] op_sel_hi:[0,1,1]
	v_pk_fma_f32 v[98:99], v[198:199], v[144:145], v[98:99] op_sel_hi:[0,1,1]
	v_pk_fma_f32 v[114:115], v[202:203], v[144:145], v[114:115] op_sel_hi:[0,1,1]
	v_pk_fma_f32 v[30:31], v[206:207], v[144:145], v[30:31] op_sel_hi:[0,1,1]
	s_waitcnt lgkmcnt(3)
	v_pk_fma_f32 v[66:67], v[194:195], v[146:147], v[66:67] op_sel:[1,0,0]
	v_pk_fma_f32 v[82:83], v[198:199], v[146:147], v[82:83] op_sel:[1,0,0]
	v_pk_fma_f32 v[100:101], v[202:203], v[146:147], v[100:101] op_sel:[1,0,0]
	v_pk_fma_f32 v[116:117], v[206:207], v[146:147], v[116:117] op_sel:[1,0,0]
	v_pk_fma_f32 v[68:69], v[194:195], v[148:149], v[68:69] op_sel:[1,0,0]
	v_pk_fma_f32 v[84:85], v[198:199], v[148:149], v[84:85] op_sel:[1,0,0]
	v_pk_fma_f32 v[102:103], v[202:203], v[148:149], v[102:103] op_sel:[1,0,0]
	v_pk_fma_f32 v[118:119], v[206:207], v[148:149], v[118:119] op_sel:[1,0,0]
	s_waitcnt lgkmcnt(2)
	v_pk_fma_f32 v[70:71], v[194:195], v[150:151], v[70:71] op_sel:[1,0,0]
	v_pk_fma_f32 v[86:87], v[198:199], v[150:151], v[86:87] op_sel:[1,0,0]
	v_pk_fma_f32 v[104:105], v[202:203], v[150:151], v[104:105] op_sel:[1,0,0]
	v_pk_fma_f32 v[120:121], v[206:207], v[150:151], v[120:121] op_sel:[1,0,0]
	v_pk_fma_f32 v[72:73], v[194:195], v[152:153], v[72:73] op_sel:[1,0,0]
	v_pk_fma_f32 v[88:89], v[198:199], v[152:153], v[88:89] op_sel:[1,0,0]
	v_pk_fma_f32 v[106:107], v[202:203], v[152:153], v[106:107] op_sel:[1,0,0]
	v_pk_fma_f32 v[122:123], v[206:207], v[152:153], v[122:123] op_sel:[1,0,0]
	s_waitcnt lgkmcnt(1)
	v_pk_fma_f32 v[74:75], v[194:195], v[154:155], v[74:75] op_sel:[1,0,0]
	v_pk_fma_f32 v[90:91], v[198:199], v[154:155], v[90:91] op_sel:[1,0,0]
	v_pk_fma_f32 v[108:109], v[202:203], v[154:155], v[108:109] op_sel:[1,0,0]
	v_pk_fma_f32 v[24:25], v[206:207], v[154:155], v[24:25] op_sel:[1,0,0]
	v_pk_fma_f32 v[76:77], v[194:195], v[156:157], v[76:77] op_sel:[1,0,0]
	v_pk_fma_f32 v[94:95], v[198:199], v[156:157], v[94:95] op_sel:[1,0,0]
	v_pk_fma_f32 v[110:111], v[202:203], v[156:157], v[110:111] op_sel:[1,0,0]
	v_pk_fma_f32 v[26:27], v[206:207], v[156:157], v[26:27] op_sel:[1,0,0]
	s_waitcnt lgkmcnt(0)
	v_pk_fma_f32 v[78:79], v[194:195], v[44:45], v[78:79] op_sel:[1,0,0]
	v_pk_fma_f32 v[96:97], v[198:199], v[44:45], v[96:97] op_sel:[1,0,0]
	v_pk_fma_f32 v[112:113], v[202:203], v[44:45], v[112:113] op_sel:[1,0,0]
	v_pk_fma_f32 v[28:29], v[206:207], v[44:45], v[28:29] op_sel:[1,0,0]
	v_pk_fma_f32 v[80:81], v[194:195], v[46:47], v[80:81] op_sel:[1,0,0]
	v_pk_fma_f32 v[98:99], v[198:199], v[46:47], v[98:99] op_sel:[1,0,0]
	v_pk_fma_f32 v[114:115], v[202:203], v[46:47], v[114:115] op_sel:[1,0,0]
	v_pk_fma_f32 v[30:31], v[206:207], v[46:47], v[30:31] op_sel:[1,0,0]
	s_waitcnt lgkmcnt(0)
	ds_bpermute_b32 v160, v48, v240
	ds_bpermute_b32 v161, v48, v241
	ds_bpermute_b32 v162, v48, v242
	ds_bpermute_b32 v163, v48, v243
	s_waitcnt lgkmcnt(0)
	v_add_f32_e32 v240, v240, v160
	v_add_f32_e32 v241, v241, v161
	v_add_f32_e32 v242, v242, v162
	v_add_f32_e32 v243, v243, v163
	ds_bpermute_b32 v160, v49, v240
	ds_bpermute_b32 v161, v49, v241
	ds_bpermute_b32 v162, v49, v242
	ds_bpermute_b32 v163, v49, v243
	s_waitcnt lgkmcnt(0)
	v_add_f32_e32 v240, v240, v160
	v_add_f32_e32 v241, v241, v161
	v_add_f32_e32 v242, v242, v162
	v_add_f32_e32 v243, v243, v163
	ds_bpermute_b32 v160, v50, v240
	ds_bpermute_b32 v161, v50, v241
	ds_bpermute_b32 v162, v50, v242
	ds_bpermute_b32 v163, v50, v243
	s_waitcnt lgkmcnt(0)
	v_add_f32_e32 v240, v240, v160
	v_add_f32_e32 v241, v241, v161
	v_add_f32_e32 v242, v242, v162
	v_add_f32_e32 v243, v243, v163
	ds_bpermute_b32 v160, v51, v240
	ds_bpermute_b32 v161, v51, v241
	ds_bpermute_b32 v162, v51, v242
	ds_bpermute_b32 v163, v51, v243
	s_waitcnt lgkmcnt(0)
	v_add_f32_e32 v240, v240, v160
	v_add_f32_e32 v241, v241, v161
	v_add_f32_e32 v242, v242, v162
	v_add_f32_e32 v243, v243, v163
	ds_bpermute_b32 v160, v52, v240
	ds_bpermute_b32 v161, v52, v241
	ds_bpermute_b32 v162, v52, v242
	ds_bpermute_b32 v163, v52, v243
	s_waitcnt lgkmcnt(0)
	v_add_f32_e32 v240, v240, v160
	v_add_f32_e32 v241, v241, v161
	v_add_f32_e32 v242, v242, v162
	v_add_f32_e32 v243, v243, v163
	ds_bpermute_b32 v160, v53, v240
	ds_bpermute_b32 v161, v53, v241
	ds_bpermute_b32 v162, v53, v242
	ds_bpermute_b32 v163, v53, v243
	s_waitcnt lgkmcnt(0)
	v_add_f32_e32 v240, v240, v160
	v_add_f32_e32 v241, v241, v161
	v_add_f32_e32 v242, v242, v162
	v_add_f32_e32 v243, v243, v163
	v_cndmask_b32_e32 v164, v74, v66, vcc
	v_cndmask_b32_e32 v196, v66, v74, vcc
	ds_bpermute_b32 v196, v53, v196
	v_cndmask_b32_e32 v165, v75, v67, vcc
	v_cndmask_b32_e32 v197, v67, v75, vcc
	ds_bpermute_b32 v197, v53, v197
	v_cndmask_b32_e32 v166, v76, v68, vcc
	v_cndmask_b32_e32 v198, v68, v76, vcc
	ds_bpermute_b32 v198, v53, v198
	v_cndmask_b32_e32 v167, v77, v69, vcc
	v_cndmask_b32_e32 v199, v69, v77, vcc
	ds_bpermute_b32 v199, v53, v199
	v_cndmask_b32_e32 v168, v78, v70, vcc
	v_cndmask_b32_e32 v200, v70, v78, vcc
	ds_bpermute_b32 v200, v53, v200
	v_cndmask_b32_e32 v169, v79, v71, vcc
	v_cndmask_b32_e32 v201, v71, v79, vcc
	ds_bpermute_b32 v201, v53, v201
	v_cndmask_b32_e32 v170, v80, v72, vcc
	v_cndmask_b32_e32 v202, v72, v80, vcc
	ds_bpermute_b32 v202, v53, v202
	v_cndmask_b32_e32 v171, v81, v73, vcc
	v_cndmask_b32_e32 v203, v73, v81, vcc
	ds_bpermute_b32 v203, v53, v203
	v_cndmask_b32_e32 v172, v90, v82, vcc
	v_cndmask_b32_e32 v204, v82, v90, vcc
	ds_bpermute_b32 v204, v53, v204
	v_cndmask_b32_e32 v173, v91, v83, vcc
	v_cndmask_b32_e32 v205, v83, v91, vcc
	ds_bpermute_b32 v205, v53, v205
	v_cndmask_b32_e32 v174, v94, v84, vcc
	v_cndmask_b32_e32 v206, v84, v94, vcc
	ds_bpermute_b32 v206, v53, v206
	v_cndmask_b32_e32 v175, v95, v85, vcc
	v_cndmask_b32_e32 v207, v85, v95, vcc
	ds_bpermute_b32 v207, v53, v207
	v_cndmask_b32_e32 v176, v96, v86, vcc
	v_cndmask_b32_e32 v208, v86, v96, vcc
	ds_bpermute_b32 v208, v53, v208
	v_cndmask_b32_e32 v177, v97, v87, vcc
	v_cndmask_b32_e32 v209, v87, v97, vcc
	ds_bpermute_b32 v209, v53, v209
	v_cndmask_b32_e32 v178, v98, v88, vcc
	v_cndmask_b32_e32 v210, v88, v98, vcc
	ds_bpermute_b32 v210, v53, v210
	v_cndmask_b32_e32 v179, v99, v89, vcc
	v_cndmask_b32_e32 v211, v89, v99, vcc
	ds_bpermute_b32 v211, v53, v211
	v_cndmask_b32_e32 v180, v108, v100, vcc
	v_cndmask_b32_e32 v212, v100, v108, vcc
	ds_bpermute_b32 v212, v53, v212
	v_cndmask_b32_e32 v181, v109, v101, vcc
	v_cndmask_b32_e32 v213, v101, v109, vcc
	ds_bpermute_b32 v213, v53, v213
	v_cndmask_b32_e32 v182, v110, v102, vcc
	v_cndmask_b32_e32 v214, v102, v110, vcc
	ds_bpermute_b32 v214, v53, v214
	v_cndmask_b32_e32 v183, v111, v103, vcc
	v_cndmask_b32_e32 v215, v103, v111, vcc
	ds_bpermute_b32 v215, v53, v215
	v_cndmask_b32_e32 v184, v112, v104, vcc
	v_cndmask_b32_e32 v216, v104, v112, vcc
	ds_bpermute_b32 v216, v53, v216
	v_cndmask_b32_e32 v185, v113, v105, vcc
	v_cndmask_b32_e32 v217, v105, v113, vcc
	ds_bpermute_b32 v217, v53, v217
	v_cndmask_b32_e32 v186, v114, v106, vcc
	v_cndmask_b32_e32 v218, v106, v114, vcc
	ds_bpermute_b32 v218, v53, v218
	v_cndmask_b32_e32 v187, v115, v107, vcc
	v_cndmask_b32_e32 v219, v107, v115, vcc
	ds_bpermute_b32 v219, v53, v219
	v_cndmask_b32_e32 v188, v24, v116, vcc
	v_cndmask_b32_e32 v220, v116, v24, vcc
	ds_bpermute_b32 v220, v53, v220
	v_cndmask_b32_e32 v189, v25, v117, vcc
	v_cndmask_b32_e32 v221, v117, v25, vcc
	ds_bpermute_b32 v221, v53, v221
	v_cndmask_b32_e32 v190, v26, v118, vcc
	v_cndmask_b32_e32 v222, v118, v26, vcc
	ds_bpermute_b32 v222, v53, v222
	v_cndmask_b32_e32 v191, v27, v119, vcc
	v_cndmask_b32_e32 v223, v119, v27, vcc
	ds_bpermute_b32 v223, v53, v223
	v_cndmask_b32_e32 v192, v28, v120, vcc
	v_cndmask_b32_e32 v224, v120, v28, vcc
	ds_bpermute_b32 v224, v53, v224
	v_cndmask_b32_e32 v193, v29, v121, vcc
	v_cndmask_b32_e32 v225, v121, v29, vcc
	ds_bpermute_b32 v225, v53, v225
	v_cndmask_b32_e32 v194, v30, v122, vcc
	v_cndmask_b32_e32 v226, v122, v30, vcc
	ds_bpermute_b32 v226, v53, v226
	v_cndmask_b32_e32 v195, v31, v123, vcc
	v_cndmask_b32_e32 v227, v123, v31, vcc
	ds_bpermute_b32 v227, v53, v227
	s_waitcnt lgkmcnt(0)
	v_add_f32_e32 v164, v164, v196
	v_add_f32_e32 v165, v165, v197
	v_add_f32_e32 v166, v166, v198
	v_add_f32_e32 v167, v167, v199
	v_add_f32_e32 v168, v168, v200
	v_add_f32_e32 v169, v169, v201
	v_add_f32_e32 v170, v170, v202
	v_add_f32_e32 v171, v171, v203
	v_add_f32_e32 v172, v172, v204
	v_add_f32_e32 v173, v173, v205
	v_add_f32_e32 v174, v174, v206
	v_add_f32_e32 v175, v175, v207
	v_add_f32_e32 v176, v176, v208
	v_add_f32_e32 v177, v177, v209
	v_add_f32_e32 v178, v178, v210
	v_add_f32_e32 v179, v179, v211
	v_add_f32_e32 v180, v180, v212
	v_add_f32_e32 v181, v181, v213
	v_add_f32_e32 v182, v182, v214
	v_add_f32_e32 v183, v183, v215
	v_add_f32_e32 v184, v184, v216
	v_add_f32_e32 v185, v185, v217
	v_add_f32_e32 v186, v186, v218
	v_add_f32_e32 v187, v187, v219
	v_add_f32_e32 v188, v188, v220
	v_add_f32_e32 v189, v189, v221
	v_add_f32_e32 v190, v190, v222
	v_add_f32_e32 v191, v191, v223
	v_add_f32_e32 v192, v192, v224
	v_add_f32_e32 v193, v193, v225
	v_add_f32_e32 v194, v194, v226
	v_add_f32_e32 v195, v195, v227
	v_cndmask_b32_e64 v228, v168, v164, s[0:1]
	v_cndmask_b32_e64 v142, v164, v168, s[0:1]
	ds_bpermute_b32 v142, v52, v142
	v_cndmask_b32_e64 v229, v169, v165, s[0:1]
	v_cndmask_b32_e64 v143, v165, v169, s[0:1]
	ds_bpermute_b32 v143, v52, v143
	v_cndmask_b32_e64 v230, v170, v166, s[0:1]
	v_cndmask_b32_e64 v144, v166, v170, s[0:1]
	ds_bpermute_b32 v144, v52, v144
	v_cndmask_b32_e64 v231, v171, v167, s[0:1]
	v_cndmask_b32_e64 v145, v167, v171, s[0:1]
	ds_bpermute_b32 v145, v52, v145
	v_cndmask_b32_e64 v130, v176, v172, s[0:1]
	v_cndmask_b32_e64 v146, v172, v176, s[0:1]
	ds_bpermute_b32 v146, v52, v146
	v_cndmask_b32_e64 v131, v177, v173, s[0:1]
	v_cndmask_b32_e64 v147, v173, v177, s[0:1]
	ds_bpermute_b32 v147, v52, v147
	v_cndmask_b32_e64 v132, v178, v174, s[0:1]
	v_cndmask_b32_e64 v148, v174, v178, s[0:1]
	ds_bpermute_b32 v148, v52, v148
	v_cndmask_b32_e64 v133, v179, v175, s[0:1]
	v_cndmask_b32_e64 v149, v175, v179, s[0:1]
	ds_bpermute_b32 v149, v52, v149
	v_cndmask_b32_e64 v134, v184, v180, s[0:1]
	v_cndmask_b32_e64 v150, v180, v184, s[0:1]
	ds_bpermute_b32 v150, v52, v150
	v_cndmask_b32_e64 v135, v185, v181, s[0:1]
	v_cndmask_b32_e64 v151, v181, v185, s[0:1]
	ds_bpermute_b32 v151, v52, v151
	v_cndmask_b32_e64 v136, v186, v182, s[0:1]
	v_cndmask_b32_e64 v152, v182, v186, s[0:1]
	ds_bpermute_b32 v152, v52, v152
	v_cndmask_b32_e64 v137, v187, v183, s[0:1]
	v_cndmask_b32_e64 v153, v183, v187, s[0:1]
	ds_bpermute_b32 v153, v52, v153
	v_cndmask_b32_e64 v138, v192, v188, s[0:1]
	v_cndmask_b32_e64 v154, v188, v192, s[0:1]
	ds_bpermute_b32 v154, v52, v154
	v_cndmask_b32_e64 v139, v193, v189, s[0:1]
	v_cndmask_b32_e64 v155, v189, v193, s[0:1]
	ds_bpermute_b32 v155, v52, v155
	v_cndmask_b32_e64 v140, v194, v190, s[0:1]
	v_cndmask_b32_e64 v156, v190, v194, s[0:1]
	ds_bpermute_b32 v156, v52, v156
	v_cndmask_b32_e64 v141, v195, v191, s[0:1]
	v_cndmask_b32_e64 v157, v191, v195, s[0:1]
	ds_bpermute_b32 v157, v52, v157
	s_waitcnt lgkmcnt(0)
	v_add_f32_e32 v228, v228, v142
	v_add_f32_e32 v229, v229, v143
	v_add_f32_e32 v230, v230, v144
	v_add_f32_e32 v231, v231, v145
	v_add_f32_e32 v130, v130, v146
	v_add_f32_e32 v131, v131, v147
	v_add_f32_e32 v132, v132, v148
	v_add_f32_e32 v133, v133, v149
	v_add_f32_e32 v134, v134, v150
	v_add_f32_e32 v135, v135, v151
	v_add_f32_e32 v136, v136, v152
	v_add_f32_e32 v137, v137, v153
	v_add_f32_e32 v138, v138, v154
	v_add_f32_e32 v139, v139, v155
	v_add_f32_e32 v140, v140, v156
	v_add_f32_e32 v141, v141, v157
	v_cndmask_b32_e64 v44, v230, v228, s[2:3]
	v_cndmask_b32_e64 v200, v228, v230, s[2:3]
	ds_bpermute_b32 v200, v51, v200
	v_cndmask_b32_e64 v45, v231, v229, s[2:3]
	v_cndmask_b32_e64 v201, v229, v231, s[2:3]
	ds_bpermute_b32 v201, v51, v201
	v_cndmask_b32_e64 v46, v132, v130, s[2:3]
	v_cndmask_b32_e64 v202, v130, v132, s[2:3]
	ds_bpermute_b32 v202, v51, v202
	v_cndmask_b32_e64 v47, v133, v131, s[2:3]
	v_cndmask_b32_e64 v203, v131, v133, s[2:3]
	ds_bpermute_b32 v203, v51, v203
	v_cndmask_b32_e64 v196, v136, v134, s[2:3]
	v_cndmask_b32_e64 v204, v134, v136, s[2:3]
	ds_bpermute_b32 v204, v51, v204
	v_cndmask_b32_e64 v197, v137, v135, s[2:3]
	v_cndmask_b32_e64 v205, v135, v137, s[2:3]
	ds_bpermute_b32 v205, v51, v205
	v_cndmask_b32_e64 v198, v140, v138, s[2:3]
	v_cndmask_b32_e64 v206, v138, v140, s[2:3]
	ds_bpermute_b32 v206, v51, v206
	v_cndmask_b32_e64 v199, v141, v139, s[2:3]
	v_cndmask_b32_e64 v207, v139, v141, s[2:3]
	ds_bpermute_b32 v207, v51, v207
	s_waitcnt lgkmcnt(0)
	v_add_f32_e32 v44, v44, v200
	v_add_f32_e32 v45, v45, v201
	v_add_f32_e32 v46, v46, v202
	v_add_f32_e32 v47, v47, v203
	v_add_f32_e32 v196, v196, v204
	v_add_f32_e32 v197, v197, v205
	v_add_f32_e32 v198, v198, v206
	v_add_f32_e32 v199, v199, v207
	v_cndmask_b32_e64 v208, v45, v44, s[4:5]
	v_cndmask_b32_e64 v212, v44, v45, s[4:5]
	ds_bpermute_b32 v212, v50, v212
	v_cndmask_b32_e64 v209, v47, v46, s[4:5]
	v_cndmask_b32_e64 v213, v46, v47, s[4:5]
	ds_bpermute_b32 v213, v50, v213
	v_cndmask_b32_e64 v210, v197, v196, s[4:5]
	v_cndmask_b32_e64 v214, v196, v197, s[4:5]
	ds_bpermute_b32 v214, v50, v214
	v_cndmask_b32_e64 v211, v199, v198, s[4:5]
	v_cndmask_b32_e64 v215, v198, v199, s[4:5]
	ds_bpermute_b32 v215, v50, v215
	s_waitcnt lgkmcnt(0)
	v_add_f32_e32 v208, v208, v212
	v_add_f32_e32 v209, v209, v213
	v_add_f32_e32 v210, v210, v214
	v_add_f32_e32 v211, v211, v215
	ds_bpermute_b32 v216, v49, v208
	ds_bpermute_b32 v217, v49, v209
	ds_bpermute_b32 v218, v49, v210
	ds_bpermute_b32 v219, v49, v211
	s_waitcnt lgkmcnt(0)
	v_add_f32_e32 v208, v208, v216
	v_add_f32_e32 v209, v209, v217
	v_add_f32_e32 v210, v210, v218
	v_add_f32_e32 v211, v211, v219
	ds_bpermute_b32 v216, v48, v208
	ds_bpermute_b32 v217, v48, v209
	ds_bpermute_b32 v218, v48, v210
	ds_bpermute_b32 v219, v48, v211
	s_waitcnt lgkmcnt(0)
	v_add_f32_e32 v208, v208, v216
	v_add_f32_e32 v209, v209, v217
	v_add_f32_e32 v210, v210, v218
	v_add_f32_e32 v211, v211, v219
	v_fmamk_f32 v224, v240, 0x3a000000, v125
	v_cmp_gt_f32_e64 s[10:11], s13, v224
	v_mul_f32_e32 v225, 0x4b800000, v224
	s_nop 0
	v_cndmask_b32_e64 v225, v224, v225, s[10:11]
	v_rsq_f32_e32 v224, v225
	s_nop 1
	v_mul_f32_e32 v225, 0x45800000, v224
	v_cndmask_b32_e64 v220, v224, v225, s[10:11]
	v_fmamk_f32 v224, v241, 0x3a000000, v125
	v_cmp_gt_f32_e64 s[10:11], s13, v224
	v_mul_f32_e32 v225, 0x4b800000, v224
	s_nop 0
	v_cndmask_b32_e64 v225, v224, v225, s[10:11]
	v_rsq_f32_e32 v224, v225
	s_nop 1
	v_mul_f32_e32 v225, 0x45800000, v224
	v_cndmask_b32_e64 v221, v224, v225, s[10:11]
	v_fmamk_f32 v224, v242, 0x3a000000, v125
	v_cmp_gt_f32_e64 s[10:11], s13, v224
	v_mul_f32_e32 v225, 0x4b800000, v224
	s_nop 0
	v_cndmask_b32_e64 v225, v224, v225, s[10:11]
	v_rsq_f32_e32 v224, v225
	s_nop 1
	v_mul_f32_e32 v225, 0x45800000, v224
	v_cndmask_b32_e64 v222, v224, v225, s[10:11]
	v_fmamk_f32 v224, v243, 0x3a000000, v125
	v_cmp_gt_f32_e64 s[10:11], s13, v224
	v_mul_f32_e32 v225, 0x4b800000, v224
	s_nop 0
	v_cndmask_b32_e64 v225, v224, v225, s[10:11]
	v_rsq_f32_e32 v224, v225
	s_nop 1
	v_mul_f32_e32 v225, 0x45800000, v224
	v_cndmask_b32_e64 v223, v224, v225, s[10:11]
	v_and_b32_e32 v224, 1, v93
	v_cmp_ne_u32_e64 s[24:25], 0, v224
	v_and_b32_e32 v225, 2, v93
	v_cmp_ne_u32_e64 s[26:27], 0, v225
	s_nop 1
	v_cndmask_b32_e64 v226, v208, v209, s[24:25]
	v_cndmask_b32_e64 v142, v210, v211, s[24:25]
	v_cndmask_b32_e64 v226, v226, v142, s[26:27]
	v_cndmask_b32_e64 v227, v220, v221, s[24:25]
	v_cndmask_b32_e64 v142, v222, v223, s[24:25]
	v_cndmask_b32_e64 v227, v227, v142, s[26:27]
	s_waitcnt vmcnt(63)
	v_mov_b32_e32 v1, v253
	v_fmac_f32_e32 v1, v227, v226
	v_cmp_nlt_f32_e64 s[10:11], s31, v1
	s_and_saveexec_b64 s[28:29], s[10:11]
	s_cbranch_execz .Lmy_partb4_sp
	v_mul_f32_e32 v2, 0x3fb8aa3b, v1
	v_rndne_f32_e32 v3, v2
	v_sub_f32_e32 v4, v2, v3
	v_fma_f32 v2, v1, s34, -v2
	v_fmac_f32_e32 v2, 0x32a5705f, v1
	v_add_f32_e32 v2, v4, v2
	v_cvt_i32_f32_e32 v3, v3
	v_exp_f32_e32 v2, v2
	v_cmp_ngt_f32_e64 s[10:11], s35, v1
	v_ldexp_f32 v2, v2, v3
	s_nop 0
	v_cndmask_b32_e64 v2, 0, v2, s[10:11]
	v_cmp_nlt_f32_e64 s[10:11], s36, v1
	s_nop 1
	v_cndmask_b32_e64 v1, v127, v2, s[10:11]
	v_add_f32_e32 v4, 1.0, v1
	v_add_f32_e32 v2, -1.0, v4
	v_sub_f32_e32 v3, v2, v4
	v_add_f32_e32 v3, 1.0, v3
	v_sub_f32_e32 v2, v1, v2
	v_add_f32_e32 v5, v2, v3
	v_frexp_mant_f32_e32 v6, v4
	v_cvt_f64_f32_e32 v[2:3], v4
	v_frexp_exp_i32_f64_e32 v2, v[2:3]
	v_cmp_gt_f32_e64 s[10:11], s38, v6
	s_nop 1
	v_subbrev_co_u32_e64 v10, s[10:11], 0, v2, s[10:11]
	v_sub_u32_e32 v2, 0, v10
	v_ldexp_f32 v3, v4, v2
	v_add_f32_e32 v4, -1.0, v3
	v_add_f32_e32 v6, 1.0, v3
	v_ldexp_f32 v2, v5, v2
	v_add_f32_e32 v5, 1.0, v4
	v_add_f32_e32 v7, -1.0, v6
	v_sub_f32_e32 v5, v3, v5
	v_sub_f32_e32 v3, v3, v7
	v_add_f32_e32 v5, v2, v5
	v_add_f32_e32 v2, v2, v3
	v_add_f32_e32 v11, v6, v2
	v_rcp_f32_e32 v13, v11
	v_sub_f32_e32 v3, v6, v11
	v_add_f32_e32 v12, v2, v3
	v_add_f32_e32 v3, v4, v5
	v_mul_f32_e32 v15, v3, v13
	v_sub_f32_e32 v2, v4, v3
	v_mul_f32_e32 v4, v11, v15
	v_fma_f32 v6, v15, v11, -v4
	v_fmac_f32_e32 v6, v15, v12
	v_add_f32_e32 v14, v5, v2
	v_add_f32_e32 v2, v4, v6
	v_sub_f32_e32 v5, v3, v2
	v_pk_add_f32 v[8:9], v[2:3], v[4:5] neg_lo:[0,1] neg_hi:[0,1]
	v_mov_b32_e32 v7, v2
	v_pk_add_f32 v[2:3], v[8:9], v[6:7] neg_lo:[0,1] neg_hi:[0,1]
	v_cmp_neq_f32_e64 s[10:11], s37, v1
	v_add_f32_e32 v3, v14, v3
	v_add_f32_e32 v2, v2, v3
	v_add_f32_e32 v3, v5, v2
	v_mul_f32_e32 v14, v13, v3
	v_mul_f32_e32 v4, v11, v14
	v_fma_f32 v6, v14, v11, -v4
	v_fmac_f32_e32 v6, v14, v12
	v_sub_f32_e32 v5, v5, v3
	v_add_f32_e32 v11, v2, v5
	v_add_f32_e32 v2, v4, v6
	v_sub_f32_e32 v5, v3, v2
	v_pk_add_f32 v[8:9], v[2:3], v[4:5] neg_lo:[0,1] neg_hi:[0,1]
	v_mov_b32_e32 v7, v2
	v_pk_add_f32 v[2:3], v[8:9], v[6:7] neg_lo:[0,1] neg_hi:[0,1]
	s_nop 0
	v_add_f32_e32 v3, v11, v3
	v_add_f32_e32 v2, v2, v3
	v_add_f32_e32 v3, v15, v14
	v_add_f32_e32 v2, v5, v2
	v_sub_f32_e32 v4, v3, v15
	v_mul_f32_e32 v2, v13, v2
	v_sub_f32_e32 v4, v14, v4
	v_add_f32_e32 v4, v4, v2
	v_add_f32_e32 v6, v3, v4
	v_mul_f32_e32 v7, v6, v6
	v_fmamk_f32 v2, v7, 0x3e9b6dac, v126
	v_fmaak_f32 v43, v7, v2, 0x3f2aaada
	v_cvt_f32_i32_e32 v2, v10
	v_sub_f32_e32 v3, v6, v3
	v_sub_f32_e32 v3, v4, v3
	v_ldexp_f32 v8, v3, 1
	v_mul_f32_e32 v3, v6, v7
	v_ldexp_f32 v5, v6, 1
	v_pk_mul_f32 v[6:7], v[2:3], v[42:43]
	s_nop 0
	v_fma_f32 v4, v2, s39, -v6
	v_fmac_f32_e32 v4, 0xb102e308, v2
	v_pk_add_f32 v[2:3], v[6:7], v[4:5]
	s_nop 0
	v_sub_f32_e32 v5, v3, v5
	v_sub_f32_e32 v5, v7, v5
	v_add_f32_e32 v9, v8, v5
	v_mov_b32_e32 v8, v6
	v_pk_add_f32 v[6:7], v[2:3], v[6:7] neg_lo:[0,1] neg_hi:[0,1]
	v_pk_add_f32 v[10:11], v[2:3], v[8:9]
	v_mov_b32_e32 v5, v2
	v_mov_b32_e32 v7, v11
	v_pk_add_f32 v[12:13], v[4:5], v[6:7] neg_lo:[0,1] neg_hi:[0,1]
	v_pk_add_f32 v[4:5], v[4:5], v[6:7]
	v_mov_b32_e32 v8, v9
	v_pk_add_f32 v[6:7], v[4:5], v[2:3] op_sel:[1,0] op_sel_hi:[0,1] neg_lo:[0,1] neg_hi:[0,1]
	v_pk_add_f32 v[14:15], v[10:11], v[6:7] op_sel_hi:[1,0] neg_lo:[0,1] neg_hi:[0,1]
	v_mov_b32_e32 v10, v11
	v_mov_b32_e32 v11, v5
	v_pk_mov_b32 v[6:7], v[2:3], v[6:7] op_sel:[1,0]
	v_mov_b32_e32 v9, v2
	v_pk_add_f32 v[6:7], v[10:11], v[6:7] neg_lo:[0,1] neg_hi:[0,1]
	v_mov_b32_e32 v14, v12
	v_pk_add_f32 v[2:3], v[8:9], v[6:7] neg_lo:[0,1] neg_hi:[0,1]
	v_mov_b32_e32 v13, v5
	v_pk_add_f32 v[6:7], v[14:15], v[2:3]
	s_nop 0
	v_pk_add_f32 v[8:9], v[6:7], v[6:7] op_sel:[0,1] op_sel_hi:[1,0]
	s_nop 0
	v_pk_add_f32 v[4:5], v[4:5], v[8:9] op_sel:[1,0] op_sel_hi:[0,1]
	v_mov_b32_e32 v7, v4
	v_pk_add_f32 v[10:11], v[6:7], v[12:13] neg_lo:[0,1] neg_hi:[0,1]
	v_mov_b32_e32 v3, v8
	v_sub_f32_e32 v5, v6, v10
	v_pk_add_f32 v[2:3], v[2:3], v[10:11] neg_lo:[0,1] neg_hi:[0,1]
	v_sub_f32_e32 v5, v12, v5
	v_add_f32_e32 v2, v2, v5
	v_add_f32_e32 v2, v2, v3
	v_add_f32_e32 v2, v4, v2
	v_cndmask_b32_e64 v2, v127, v2, s[10:11]
	v_cmp_lt_f32_e64 s[10:11], |v1|, s40
	s_nop 1
	v_cndmask_b32_e64 v1, v2, v1, s[10:11]

.LBB0_208:
	s_waitcnt lgkmcnt(0)
	global_load_dwordx4 v[14:17], v[2:3], off offset:-4096
	global_load_dwordx4 v[18:21], v[2:3], off offset:-3072
	global_load_dwordx4 v[22:25], v[2:3], off offset:-2048
	global_load_dwordx4 v[26:29], v[2:3], off offset:-1024
	global_load_dwordx4 v[30:33], v[2:3], off
	global_load_dwordx4 v[34:37], v[2:3], off offset:1024
	global_load_dwordx4 v[38:41], v[2:3], off offset:2048
	global_load_dwordx4 v[42:45], v[2:3], off offset:3072
	v_lshl_add_u64 v[46:47], s[84:85], 0, v[4:5]
	v_add_co_u32_e64 v46, s[0:1], s13, v46
	s_waitcnt vmcnt(7)
	v_mul_f32_e32 v13, v15, v15
	v_mul_f32_e32 v48, v17, v17
	s_waitcnt vmcnt(6)
	v_mul_f32_e32 v49, v19, v19
	v_mul_f32_e32 v50, v21, v21
	s_waitcnt vmcnt(5)
	v_mul_f32_e32 v51, v23, v23
	v_mul_f32_e32 v52, v25, v25
	v_fmac_f32_e32 v13, v14, v14
	v_fmac_f32_e32 v48, v16, v16
	v_fmac_f32_e32 v49, v18, v18
	v_fmac_f32_e32 v50, v20, v20
	s_waitcnt vmcnt(4)
	v_mul_f32_e32 v53, v27, v27
	v_mul_f32_e32 v54, v29, v29
	v_fmac_f32_e32 v51, v22, v22
	v_fmac_f32_e32 v52, v24, v24
	v_add_f32_e32 v13, v13, v48
	v_add_f32_e32 v48, v49, v50
	s_waitcnt vmcnt(3)
	v_mul_f32_e32 v55, v31, v31
	v_mul_f32_e32 v56, v33, v33
	v_fmac_f32_e32 v53, v26, v26
	v_fmac_f32_e32 v54, v28, v28
	v_add_f32_e32 v49, v51, v52
	v_add_f32_e32 v13, v13, v48
	s_waitcnt vmcnt(2)
	v_mul_f32_e32 v57, v35, v35
	v_mul_f32_e32 v58, v37, v37
	v_fmac_f32_e32 v55, v30, v30
	v_fmac_f32_e32 v56, v32, v32
	v_add_f32_e32 v50, v53, v54
	v_add_f32_e32 v13, v13, v49
	s_waitcnt vmcnt(1)
	v_mul_f32_e32 v59, v39, v39
	v_mul_f32_e32 v60, v41, v41
	v_fmac_f32_e32 v57, v34, v34
	v_fmac_f32_e32 v58, v36, v36
	v_add_f32_e32 v51, v55, v56
	v_add_f32_e32 v13, v13, v50
	s_waitcnt vmcnt(0)
	v_mul_f32_e32 v61, v43, v43
	v_mul_f32_e32 v62, v45, v45
	v_fmac_f32_e32 v59, v38, v38
	v_fmac_f32_e32 v60, v40, v40
	v_add_f32_e32 v52, v57, v58
	v_add_f32_e32 v13, v13, v51
	v_fmac_f32_e32 v61, v42, v42
	v_fmac_f32_e32 v62, v44, v44
	v_add_f32_e32 v53, v59, v60
	v_add_f32_e32 v13, v13, v52
	v_add_f32_e32 v54, v61, v62
	v_add_f32_e32 v13, v13, v53
	v_add_f32_e32 v13, v13, v54
	ds_bpermute_b32 v48, v6, v13
	v_cvt_pk_bf16_f32 v14, v14, v15
	v_cvt_pk_bf16_f32 v15, v16, v17
	v_addc_co_u32_e64 v47, s[0:1], 0, v47, s[0:1]
	s_waitcnt lgkmcnt(0)
	v_add_f32_e32 v13, v13, v48
	ds_bpermute_b32 v16, v7, v13
	global_store_dwordx2 v[46:47], v[14:15], off
	v_cvt_pk_bf16_f32 v14, v18, v19
	v_cvt_pk_bf16_f32 v15, v20, v21
	global_store_dwordx2 v[46:47], v[14:15], off offset:512
	s_waitcnt lgkmcnt(0)
	v_add_f32_e32 v13, v13, v16
	ds_bpermute_b32 v16, v8, v13
	v_cvt_pk_bf16_f32 v14, v22, v23
	v_cvt_pk_bf16_f32 v15, v24, v25
	global_store_dwordx2 v[46:47], v[14:15], off offset:1024
	v_cvt_pk_bf16_f32 v14, v26, v27
	s_waitcnt lgkmcnt(0)
	v_add_f32_e32 v13, v13, v16
	ds_bpermute_b32 v16, v9, v13
	v_cvt_pk_bf16_f32 v15, v28, v29
	global_store_dwordx2 v[46:47], v[14:15], off offset:1536
	v_cvt_pk_bf16_f32 v14, v30, v31
	v_cvt_pk_bf16_f32 v15, v32, v33
	s_waitcnt lgkmcnt(0)
	v_add_f32_e32 v13, v13, v16
	ds_bpermute_b32 v17, v10, v13
	global_store_dwordx2 v[46:47], v[14:15], off offset:2048
	v_cvt_pk_bf16_f32 v14, v34, v35
	v_cvt_pk_bf16_f32 v15, v36, v37
	global_store_dwordx2 v[46:47], v[14:15], off offset:2560
	s_waitcnt lgkmcnt(0)
	v_add_f32_e32 v13, v13, v17
	ds_bpermute_b32 v14, v11, v13
	v_cvt_pk_bf16_f32 v16, v38, v39
	v_cvt_pk_bf16_f32 v17, v40, v41
	global_store_dwordx2 v[46:47], v[16:17], off offset:3072
	v_cvt_pk_bf16_f32 v16, v42, v43
	v_cvt_pk_bf16_f32 v17, v44, v45
	global_store_dwordx2 v[46:47], v[16:17], off offset:3584
	s_and_saveexec_b64 s[14:15], vcc
	s_cbranch_execz .LBB0_207
	s_waitcnt lgkmcnt(0)
	v_add_f32_e32 v13, v13, v14
	v_fmamk_f32 v13, v13, 0x3a000000, v12
	v_mul_f32_e32 v14, 0x4b800000, v13
	v_cmp_gt_f32_e64 s[0:1], s16, v13
	s_nop 1
	v_cndmask_b32_e64 v13, v13, v14, s[0:1]
	v_rsq_f32_e32 v13, v13
	s_nop 0
	v_mul_f32_e32 v14, 0x45800000, v13
	v_cndmask_b32_e64 v13, v13, v14, s[0:1]
	v_lshl_add_u64 v[14:15], s[84:85], 0, v[0:1]
	global_store_dword v[14:15], v13, off
	s_branch .LBB0_207

.Lmy_wup_begin:
	s_cmpk_lg_u32 s88, 0x100
	s_cbranch_scc1 .Lmy_wup_end
	s_waitcnt lgkmcnt(0)
	s_barrier
	v_readlane_b32 s2, v252, 0
	v_readlane_b32 s3, v252, 1
	s_add_u32 s2, s2, 0xffffff20
	s_addc_u32 s3, s3, -1
	s_load_dwordx4 s[4:7], s[2:3], 0xb0
	v_and_b32_e32 v197, 63, v158
	v_lshrrev_b32_e32 v198, 4, v197
	v_and_b32_e32 v194, 15, v197
	v_lshlrev_b32_e32 v194, 2, v194
	v_mul_u32_u24_e32 v193, 0x4100, v159
	v_mul_u32_u24_e32 v192, 65, v198
	v_add_u32_e32 v192, v192, v194
	v_lshl_add_u32 v176, v192, 2, v193
	v_add_u32_e32 v177, 0x410, v176
	v_add_u32_e32 v178, 0x820, v176
	v_add_u32_e32 v179, 0xc30, v176
	v_add_u32_e32 v180, 0x1040, v176
	v_add_u32_e32 v181, 0x1450, v176
	v_add_u32_e32 v182, 0x1860, v176
	v_add_u32_e32 v183, 0x1c70, v176
	v_add_u32_e32 v184, 0x2080, v176
	v_add_u32_e32 v185, 0x2490, v176
	v_add_u32_e32 v186, 0x28a0, v176
	v_add_u32_e32 v187, 0x2cb0, v176
	v_add_u32_e32 v188, 0x30c0, v176
	v_add_u32_e32 v189, 0x34d0, v176
	v_add_u32_e32 v190, 0x38e0, v176
	v_add_u32_e32 v191, 0x3cf0, v176
	v_lshlrev_b32_e32 v195, 2, v198
	v_lshlrev_b32_e32 v194, 2, v194
	v_lshl_add_u32 v194, v198, 15, v194
	v_and_b32_e32 v196, 7, v197
	v_mul_u32_u24_e32 v192, 0x208, v196
	v_lshrrev_b32_e32 v198, 3, v197
	v_add_u32_e32 v192, v192, v198
	v_lshl_add_u32 v192, v192, 2, v193
	v_add_u32_e32 v193, 0x400, v192
	v_lshlrev_b32_e32 v196, 4, v196
	v_lshl_add_u32 v196, v198, 12, v196
	v_readfirstlane_b32 s8, v159
	s_lshl_b32 s9, s33, 3
	s_add_i32 s8, s8, s9
	s_waitcnt lgkmcnt(0)
	s_lshr_b32 s9, s8, 7
	s_and_b32 s10, s8, 0x7f
	s_lshl_b32 s11, s9, 21
	s_lshl_b32 s12, s10, 8
	s_add_u32 s11, s11, s12
	s_add_u32 s16, s6, s11
	s_addc_u32 s17, s7, 0
	s_lshl_b32 s11, s9, 8
	s_add_u32 s18, s4, s11
	s_addc_u32 s19, s5, 0
	s_lshl_b32 s11, s10, 18
	s_lshl_b32 s12, s9, 7
	s_add_u32 s11, s11, s12
	s_add_u32 s11, s11, 0x1000000
	s_add_u32 s20, s84, s11
	s_addc_u32 s21, s85, 0
	s_addk_i32 s8, 0x800
	s_lshr_b32 s9, s8, 7
	s_and_b32 s10, s8, 0x7f
	s_lshl_b32 s11, s9, 21
	s_lshl_b32 s12, s10, 8
	s_add_u32 s11, s11, s12
	s_add_u32 s22, s6, s11
	s_addc_u32 s23, s7, 0
	s_lshl_b32 s11, s9, 8
	s_add_u32 s24, s4, s11
	s_addc_u32 s25, s5, 0
	s_lshl_b32 s11, s10, 18
	s_lshl_b32 s12, s9, 7
	s_add_u32 s11, s11, s12
	s_add_u32 s11, s11, 0x1000000
	s_add_u32 s26, s84, s11
	s_addc_u32 s27, s85, 0
	global_load_dword v128, v195, s[18:19]
	global_load_dword v129, v195, s[18:19] offset:16
	global_load_dword v130, v195, s[18:19] offset:32
	global_load_dword v131, v195, s[18:19] offset:48
	global_load_dword v132, v195, s[18:19] offset:64
	global_load_dword v133, v195, s[18:19] offset:80
	global_load_dword v134, v195, s[18:19] offset:96
	global_load_dword v135, v195, s[18:19] offset:112
	global_load_dword v136, v195, s[18:19] offset:128
	global_load_dword v137, v195, s[18:19] offset:144
	global_load_dword v138, v195, s[18:19] offset:160
	global_load_dword v139, v195, s[18:19] offset:176
	global_load_dword v140, v195, s[18:19] offset:192
	global_load_dword v141, v195, s[18:19] offset:208
	global_load_dword v142, v195, s[18:19] offset:224
	global_load_dword v143, v195, s[18:19] offset:240
	v_mov_b32_e32 v197, v194
	global_load_dwordx4 v[0:3], v197, s[16:17]
	v_add_u32_e32 v197, 0x20000, v197
	global_load_dwordx4 v[4:7], v197, s[16:17]
	v_add_u32_e32 v197, 0x20000, v197
	global_load_dwordx4 v[8:11], v197, s[16:17]
	v_add_u32_e32 v197, 0x20000, v197
	global_load_dwordx4 v[12:15], v197, s[16:17]
	v_add_u32_e32 v197, 0x20000, v197
	global_load_dwordx4 v[16:19], v197, s[16:17]
	v_add_u32_e32 v197, 0x20000, v197
	global_load_dwordx4 v[20:23], v197, s[16:17]
	v_add_u32_e32 v197, 0x20000, v197
	global_load_dwordx4 v[24:27], v197, s[16:17]
	v_add_u32_e32 v197, 0x20000, v197
	global_load_dwordx4 v[28:31], v197, s[16:17]
	v_add_u32_e32 v197, 0x20000, v197
	global_load_dwordx4 v[32:35], v197, s[16:17]
	v_add_u32_e32 v197, 0x20000, v197
	global_load_dwordx4 v[36:39], v197, s[16:17]
	v_add_u32_e32 v197, 0x20000, v197
	global_load_dwordx4 v[40:43], v197, s[16:17]
	v_add_u32_e32 v197, 0x20000, v197
	global_load_dwordx4 v[44:47], v197, s[16:17]
	v_add_u32_e32 v197, 0x20000, v197
	global_load_dwordx4 v[48:51], v197, s[16:17]
	v_add_u32_e32 v197, 0x20000, v197
	global_load_dwordx4 v[52:55], v197, s[16:17]
	v_add_u32_e32 v197, 0x20000, v197
	global_load_dwordx4 v[56:59], v197, s[16:17]
	v_add_u32_e32 v197, 0x20000, v197
	global_load_dwordx4 v[60:63], v197, s[16:17]
	global_load_dword v160, v195, s[24:25]
	global_load_dword v161, v195, s[24:25] offset:16
	global_load_dword v162, v195, s[24:25] offset:32
	global_load_dword v163, v195, s[24:25] offset:48
	global_load_dword v164, v195, s[24:25] offset:64
	global_load_dword v165, v195, s[24:25] offset:80
	global_load_dword v166, v195, s[24:25] offset:96
	global_load_dword v167, v195, s[24:25] offset:112
	global_load_dword v168, v195, s[24:25] offset:128
	global_load_dword v169, v195, s[24:25] offset:144
	global_load_dword v170, v195, s[24:25] offset:160
	global_load_dword v171, v195, s[24:25] offset:176
	global_load_dword v172, v195, s[24:25] offset:192
	global_load_dword v173, v195, s[24:25] offset:208
	global_load_dword v174, v195, s[24:25] offset:224
	global_load_dword v175, v195, s[24:25] offset:240
	v_mov_b32_e32 v197, v194
	global_load_dwordx4 v[64:67], v197, s[22:23]
	v_add_u32_e32 v197, 0x20000, v197
	global_load_dwordx4 v[68:71], v197, s[22:23]
	v_add_u32_e32 v197, 0x20000, v197
	global_load_dwordx4 v[72:75], v197, s[22:23]
	v_add_u32_e32 v197, 0x20000, v197
	global_load_dwordx4 v[76:79], v197, s[22:23]
	v_add_u32_e32 v197, 0x20000, v197
	global_load_dwordx4 v[80:83], v197, s[22:23]
	v_add_u32_e32 v197, 0x20000, v197
	global_load_dwordx4 v[84:87], v197, s[22:23]
	v_add_u32_e32 v197, 0x20000, v197
	global_load_dwordx4 v[88:91], v197, s[22:23]
	v_add_u32_e32 v197, 0x20000, v197
	global_load_dwordx4 v[92:95], v197, s[22:23]
	v_add_u32_e32 v197, 0x20000, v197
	global_load_dwordx4 v[96:99], v197, s[22:23]
	v_add_u32_e32 v197, 0x20000, v197
	global_load_dwordx4 v[100:103], v197, s[22:23]
	v_add_u32_e32 v197, 0x20000, v197
	global_load_dwordx4 v[104:107], v197, s[22:23]
	v_add_u32_e32 v197, 0x20000, v197
	global_load_dwordx4 v[108:111], v197, s[22:23]
	v_add_u32_e32 v197, 0x20000, v197
	global_load_dwordx4 v[112:115], v197, s[22:23]
	v_add_u32_e32 v197, 0x20000, v197
	global_load_dwordx4 v[116:119], v197, s[22:23]
	v_add_u32_e32 v197, 0x20000, v197
	global_load_dwordx4 v[120:123], v197, s[22:23]
	v_add_u32_e32 v197, 0x20000, v197
	global_load_dwordx4 v[124:127], v197, s[22:23]
	s_waitcnt vmcnt(47)
	v_mul_f32_e32 v0, v0, v128
	v_mul_f32_e32 v1, v1, v128
	v_mul_f32_e32 v2, v2, v128
	v_mul_f32_e32 v3, v3, v128
	ds_write2_b32 v176, v0, v1 offset1:1
	ds_write2_b32 v176, v2, v3 offset0:2 offset1:3
	s_waitcnt vmcnt(46)
	v_mul_f32_e32 v4, v4, v129
	v_mul_f32_e32 v5, v5, v129
	v_mul_f32_e32 v6, v6, v129
	v_mul_f32_e32 v7, v7, v129
	ds_write2_b32 v177, v4, v5 offset1:1
	ds_write2_b32 v177, v6, v7 offset0:2 offset1:3
	s_waitcnt vmcnt(45)
	v_mul_f32_e32 v8, v8, v130
	v_mul_f32_e32 v9, v9, v130
	v_mul_f32_e32 v10, v10, v130
	v_mul_f32_e32 v11, v11, v130
	ds_write2_b32 v178, v8, v9 offset1:1
	ds_write2_b32 v178, v10, v11 offset0:2 offset1:3
	s_waitcnt vmcnt(44)
	v_mul_f32_e32 v12, v12, v131
	v_mul_f32_e32 v13, v13, v131
	v_mul_f32_e32 v14, v14, v131
	v_mul_f32_e32 v15, v15, v131
	ds_write2_b32 v179, v12, v13 offset1:1
	ds_write2_b32 v179, v14, v15 offset0:2 offset1:3
	s_waitcnt vmcnt(43)
	v_mul_f32_e32 v16, v16, v132
	v_mul_f32_e32 v17, v17, v132
	v_mul_f32_e32 v18, v18, v132
	v_mul_f32_e32 v19, v19, v132
	ds_write2_b32 v180, v16, v17 offset1:1
	ds_write2_b32 v180, v18, v19 offset0:2 offset1:3
	s_waitcnt vmcnt(42)
	v_mul_f32_e32 v20, v20, v133
	v_mul_f32_e32 v21, v21, v133
	v_mul_f32_e32 v22, v22, v133
	v_mul_f32_e32 v23, v23, v133
	ds_write2_b32 v181, v20, v21 offset1:1
	ds_write2_b32 v181, v22, v23 offset0:2 offset1:3
	s_waitcnt vmcnt(41)
	v_mul_f32_e32 v24, v24, v134
	v_mul_f32_e32 v25, v25, v134
	v_mul_f32_e32 v26, v26, v134
	v_mul_f32_e32 v27, v27, v134
	ds_write2_b32 v182, v24, v25 offset1:1
	ds_write2_b32 v182, v26, v27 offset0:2 offset1:3
	s_waitcnt vmcnt(40)
	v_mul_f32_e32 v28, v28, v135
	v_mul_f32_e32 v29, v29, v135
	v_mul_f32_e32 v30, v30, v135
	v_mul_f32_e32 v31, v31, v135
	ds_write2_b32 v183, v28, v29 offset1:1
	ds_write2_b32 v183, v30, v31 offset0:2 offset1:3
	s_waitcnt vmcnt(39)
	v_mul_f32_e32 v32, v32, v136
	v_mul_f32_e32 v33, v33, v136
	v_mul_f32_e32 v34, v34, v136
	v_mul_f32_e32 v35, v35, v136
	ds_write2_b32 v184, v32, v33 offset1:1
	ds_write2_b32 v184, v34, v35 offset0:2 offset1:3
	s_waitcnt vmcnt(38)
	v_mul_f32_e32 v36, v36, v137
	v_mul_f32_e32 v37, v37, v137
	v_mul_f32_e32 v38, v38, v137
	v_mul_f32_e32 v39, v39, v137
	ds_write2_b32 v185, v36, v37 offset1:1
	ds_write2_b32 v185, v38, v39 offset0:2 offset1:3
	s_waitcnt vmcnt(37)
	v_mul_f32_e32 v40, v40, v138
	v_mul_f32_e32 v41, v41, v138
	v_mul_f32_e32 v42, v42, v138
	v_mul_f32_e32 v43, v43, v138
	ds_write2_b32 v186, v40, v41 offset1:1
	ds_write2_b32 v186, v42, v43 offset0:2 offset1:3
	s_waitcnt vmcnt(36)
	v_mul_f32_e32 v44, v44, v139
	v_mul_f32_e32 v45, v45, v139
	v_mul_f32_e32 v46, v46, v139
	v_mul_f32_e32 v47, v47, v139
	ds_write2_b32 v187, v44, v45 offset1:1
	ds_write2_b32 v187, v46, v47 offset0:2 offset1:3
	s_waitcnt vmcnt(35)
	v_mul_f32_e32 v48, v48, v140
	v_mul_f32_e32 v49, v49, v140
	v_mul_f32_e32 v50, v50, v140
	v_mul_f32_e32 v51, v51, v140
	ds_write2_b32 v188, v48, v49 offset1:1
	ds_write2_b32 v188, v50, v51 offset0:2 offset1:3
	s_waitcnt vmcnt(34)
	v_mul_f32_e32 v52, v52, v141
	v_mul_f32_e32 v53, v53, v141
	v_mul_f32_e32 v54, v54, v141
	v_mul_f32_e32 v55, v55, v141
	ds_write2_b32 v189, v52, v53 offset1:1
	ds_write2_b32 v189, v54, v55 offset0:2 offset1:3
	s_waitcnt vmcnt(33)
	v_mul_f32_e32 v56, v56, v142
	v_mul_f32_e32 v57, v57, v142
	v_mul_f32_e32 v58, v58, v142
	v_mul_f32_e32 v59, v59, v142
	ds_write2_b32 v190, v56, v57 offset1:1
	ds_write2_b32 v190, v58, v59 offset0:2 offset1:3
	s_waitcnt vmcnt(32)
	v_mul_f32_e32 v60, v60, v143
	v_mul_f32_e32 v61, v61, v143
	v_mul_f32_e32 v62, v62, v143
	v_mul_f32_e32 v63, v63, v143
	ds_write2_b32 v191, v60, v61 offset1:1
	ds_write2_b32 v191, v62, v63 offset0:2 offset1:3
	s_waitcnt lgkmcnt(0)
	v_mov_b32_e32 v197, v196
	ds_read2_b32 v[208:209], v192 offset0:0 offset1:65
	ds_read2_b32 v[210:211], v192 offset0:130 offset1:195
	ds_read2_b32 v[212:213], v193 offset0:4 offset1:69
	ds_read2_b32 v[214:215], v193 offset0:134 offset1:199
	ds_read2_b32 v[216:217], v192 offset0:8 offset1:73
	ds_read2_b32 v[218:219], v192 offset0:138 offset1:203
	ds_read2_b32 v[220:221], v193 offset0:12 offset1:77
	ds_read2_b32 v[222:223], v193 offset0:142 offset1:207
	s_waitcnt lgkmcnt(4)
	v_cvt_pk_bf16_f32 v200, v208, v209
	v_cvt_pk_bf16_f32 v201, v210, v211
	v_cvt_pk_bf16_f32 v202, v212, v213
	v_cvt_pk_bf16_f32 v203, v214, v215
	global_store_dwordx4 v197, v[200:203], s[20:21]
	v_add_u32_e32 v197, 0x8000, v197
	s_waitcnt lgkmcnt(0)
	v_cvt_pk_bf16_f32 v204, v216, v217
	v_cvt_pk_bf16_f32 v205, v218, v219
	v_cvt_pk_bf16_f32 v206, v220, v221
	v_cvt_pk_bf16_f32 v207, v222, v223
	global_store_dwordx4 v197, v[204:207], s[20:21]
	v_add_u32_e32 v197, 0x8000, v197
	ds_read2_b32 v[208:209], v192 offset0:16 offset1:81
	ds_read2_b32 v[210:211], v192 offset0:146 offset1:211
	ds_read2_b32 v[212:213], v193 offset0:20 offset1:85
	ds_read2_b32 v[214:215], v193 offset0:150 offset1:215
	ds_read2_b32 v[216:217], v192 offset0:24 offset1:89
	ds_read2_b32 v[218:219], v192 offset0:154 offset1:219
	ds_read2_b32 v[220:221], v193 offset0:28 offset1:93
	ds_read2_b32 v[222:223], v193 offset0:158 offset1:223
	s_waitcnt lgkmcnt(4)
	v_cvt_pk_bf16_f32 v200, v208, v209
	v_cvt_pk_bf16_f32 v201, v210, v211
	v_cvt_pk_bf16_f32 v202, v212, v213
	v_cvt_pk_bf16_f32 v203, v214, v215
	global_store_dwordx4 v197, v[200:203], s[20:21]
	v_add_u32_e32 v197, 0x8000, v197
	s_waitcnt lgkmcnt(0)
	v_cvt_pk_bf16_f32 v204, v216, v217
	v_cvt_pk_bf16_f32 v205, v218, v219
	v_cvt_pk_bf16_f32 v206, v220, v221
	v_cvt_pk_bf16_f32 v207, v222, v223
	global_store_dwordx4 v197, v[204:207], s[20:21]
	v_add_u32_e32 v197, 0x8000, v197
	ds_read2_b32 v[208:209], v192 offset0:32 offset1:97
	ds_read2_b32 v[210:211], v192 offset0:162 offset1:227
	ds_read2_b32 v[212:213], v193 offset0:36 offset1:101
	ds_read2_b32 v[214:215], v193 offset0:166 offset1:231
	ds_read2_b32 v[216:217], v192 offset0:40 offset1:105
	ds_read2_b32 v[218:219], v192 offset0:170 offset1:235
	ds_read2_b32 v[220:221], v193 offset0:44 offset1:109
	ds_read2_b32 v[222:223], v193 offset0:174 offset1:239
	s_waitcnt lgkmcnt(4)
	v_cvt_pk_bf16_f32 v200, v208, v209
	v_cvt_pk_bf16_f32 v201, v210, v211
	v_cvt_pk_bf16_f32 v202, v212, v213
	v_cvt_pk_bf16_f32 v203, v214, v215
	global_store_dwordx4 v197, v[200:203], s[20:21]
	v_add_u32_e32 v197, 0x8000, v197
	s_waitcnt lgkmcnt(0)
	v_cvt_pk_bf16_f32 v204, v216, v217
	v_cvt_pk_bf16_f32 v205, v218, v219
	v_cvt_pk_bf16_f32 v206, v220, v221
	v_cvt_pk_bf16_f32 v207, v222, v223
	global_store_dwordx4 v197, v[204:207], s[20:21]
	v_add_u32_e32 v197, 0x8000, v197
	ds_read2_b32 v[208:209], v192 offset0:48 offset1:113
	ds_read2_b32 v[210:211], v192 offset0:178 offset1:243
	ds_read2_b32 v[212:213], v193 offset0:52 offset1:117
	ds_read2_b32 v[214:215], v193 offset0:182 offset1:247
	ds_read2_b32 v[216:217], v192 offset0:56 offset1:121
	ds_read2_b32 v[218:219], v192 offset0:186 offset1:251
	ds_read2_b32 v[220:221], v193 offset0:60 offset1:125
	ds_read2_b32 v[222:223], v193 offset0:190 offset1:255
	s_waitcnt lgkmcnt(4)
	v_cvt_pk_bf16_f32 v200, v208, v209
	v_cvt_pk_bf16_f32 v201, v210, v211
	v_cvt_pk_bf16_f32 v202, v212, v213
	v_cvt_pk_bf16_f32 v203, v214, v215
	global_store_dwordx4 v197, v[200:203], s[20:21]
	v_add_u32_e32 v197, 0x8000, v197
	s_waitcnt lgkmcnt(0)
	v_cvt_pk_bf16_f32 v204, v216, v217
	v_cvt_pk_bf16_f32 v205, v218, v219
	v_cvt_pk_bf16_f32 v206, v220, v221
	v_cvt_pk_bf16_f32 v207, v222, v223
	global_store_dwordx4 v197, v[204:207], s[20:21]
	v_add_u32_e32 v197, 0x8000, v197
	s_waitcnt lgkmcnt(0)
	s_waitcnt vmcnt(23)
	v_mul_f32_e32 v64, v64, v160
	v_mul_f32_e32 v65, v65, v160
	v_mul_f32_e32 v66, v66, v160
	v_mul_f32_e32 v67, v67, v160
	ds_write2_b32 v176, v64, v65 offset1:1
	ds_write2_b32 v176, v66, v67 offset0:2 offset1:3
	s_waitcnt vmcnt(22)
	v_mul_f32_e32 v68, v68, v161
	v_mul_f32_e32 v69, v69, v161
	v_mul_f32_e32 v70, v70, v161
	v_mul_f32_e32 v71, v71, v161
	ds_write2_b32 v177, v68, v69 offset1:1
	ds_write2_b32 v177, v70, v71 offset0:2 offset1:3
	s_waitcnt vmcnt(21)
	v_mul_f32_e32 v72, v72, v162
	v_mul_f32_e32 v73, v73, v162
	v_mul_f32_e32 v74, v74, v162
	v_mul_f32_e32 v75, v75, v162
	ds_write2_b32 v178, v72, v73 offset1:1
	ds_write2_b32 v178, v74, v75 offset0:2 offset1:3
	s_waitcnt vmcnt(20)
	v_mul_f32_e32 v76, v76, v163
	v_mul_f32_e32 v77, v77, v163
	v_mul_f32_e32 v78, v78, v163
	v_mul_f32_e32 v79, v79, v163
	ds_write2_b32 v179, v76, v77 offset1:1
	ds_write2_b32 v179, v78, v79 offset0:2 offset1:3
	s_waitcnt vmcnt(19)
	v_mul_f32_e32 v80, v80, v164
	v_mul_f32_e32 v81, v81, v164
	v_mul_f32_e32 v82, v82, v164
	v_mul_f32_e32 v83, v83, v164
	ds_write2_b32 v180, v80, v81 offset1:1
	ds_write2_b32 v180, v82, v83 offset0:2 offset1:3
	s_waitcnt vmcnt(18)
	v_mul_f32_e32 v84, v84, v165
	v_mul_f32_e32 v85, v85, v165
	v_mul_f32_e32 v86, v86, v165
	v_mul_f32_e32 v87, v87, v165
	ds_write2_b32 v181, v84, v85 offset1:1
	ds_write2_b32 v181, v86, v87 offset0:2 offset1:3
	s_waitcnt vmcnt(17)
	v_mul_f32_e32 v88, v88, v166
	v_mul_f32_e32 v89, v89, v166
	v_mul_f32_e32 v90, v90, v166
	v_mul_f32_e32 v91, v91, v166
	ds_write2_b32 v182, v88, v89 offset1:1
	ds_write2_b32 v182, v90, v91 offset0:2 offset1:3
	s_waitcnt vmcnt(16)
	v_mul_f32_e32 v92, v92, v167
	v_mul_f32_e32 v93, v93, v167
	v_mul_f32_e32 v94, v94, v167
	v_mul_f32_e32 v95, v95, v167
	ds_write2_b32 v183, v92, v93 offset1:1
	ds_write2_b32 v183, v94, v95 offset0:2 offset1:3
	s_waitcnt vmcnt(15)
	v_mul_f32_e32 v96, v96, v168
	v_mul_f32_e32 v97, v97, v168
	v_mul_f32_e32 v98, v98, v168
	v_mul_f32_e32 v99, v99, v168
	ds_write2_b32 v184, v96, v97 offset1:1
	ds_write2_b32 v184, v98, v99 offset0:2 offset1:3
	s_waitcnt vmcnt(14)
	v_mul_f32_e32 v100, v100, v169
	v_mul_f32_e32 v101, v101, v169
	v_mul_f32_e32 v102, v102, v169
	v_mul_f32_e32 v103, v103, v169
	ds_write2_b32 v185, v100, v101 offset1:1
	ds_write2_b32 v185, v102, v103 offset0:2 offset1:3
	s_waitcnt vmcnt(13)
	v_mul_f32_e32 v104, v104, v170
	v_mul_f32_e32 v105, v105, v170
	v_mul_f32_e32 v106, v106, v170
	v_mul_f32_e32 v107, v107, v170
	ds_write2_b32 v186, v104, v105 offset1:1
	ds_write2_b32 v186, v106, v107 offset0:2 offset1:3
	s_waitcnt vmcnt(12)
	v_mul_f32_e32 v108, v108, v171
	v_mul_f32_e32 v109, v109, v171
	v_mul_f32_e32 v110, v110, v171
	v_mul_f32_e32 v111, v111, v171
	ds_write2_b32 v187, v108, v109 offset1:1
	ds_write2_b32 v187, v110, v111 offset0:2 offset1:3
	s_waitcnt vmcnt(11)
	v_mul_f32_e32 v112, v112, v172
	v_mul_f32_e32 v113, v113, v172
	v_mul_f32_e32 v114, v114, v172
	v_mul_f32_e32 v115, v115, v172
	ds_write2_b32 v188, v112, v113 offset1:1
	ds_write2_b32 v188, v114, v115 offset0:2 offset1:3
	s_waitcnt vmcnt(10)
	v_mul_f32_e32 v116, v116, v173
	v_mul_f32_e32 v117, v117, v173
	v_mul_f32_e32 v118, v118, v173
	v_mul_f32_e32 v119, v119, v173
	ds_write2_b32 v189, v116, v117 offset1:1
	ds_write2_b32 v189, v118, v119 offset0:2 offset1:3
	s_waitcnt vmcnt(9)
	v_mul_f32_e32 v120, v120, v174
	v_mul_f32_e32 v121, v121, v174
	v_mul_f32_e32 v122, v122, v174
	v_mul_f32_e32 v123, v123, v174
	ds_write2_b32 v190, v120, v121 offset1:1
	ds_write2_b32 v190, v122, v123 offset0:2 offset1:3
	s_waitcnt vmcnt(8)
	v_mul_f32_e32 v124, v124, v175
	v_mul_f32_e32 v125, v125, v175
	v_mul_f32_e32 v126, v126, v175
	v_mul_f32_e32 v127, v127, v175
	ds_write2_b32 v191, v124, v125 offset1:1
	ds_write2_b32 v191, v126, v127 offset0:2 offset1:3
	s_waitcnt lgkmcnt(0)
	v_mov_b32_e32 v197, v196
	ds_read2_b32 v[208:209], v192 offset0:0 offset1:65
	ds_read2_b32 v[210:211], v192 offset0:130 offset1:195
	ds_read2_b32 v[212:213], v193 offset0:4 offset1:69
	ds_read2_b32 v[214:215], v193 offset0:134 offset1:199
	ds_read2_b32 v[216:217], v192 offset0:8 offset1:73
	ds_read2_b32 v[218:219], v192 offset0:138 offset1:203
	ds_read2_b32 v[220:221], v193 offset0:12 offset1:77
	ds_read2_b32 v[222:223], v193 offset0:142 offset1:207
	s_waitcnt lgkmcnt(4)
	v_cvt_pk_bf16_f32 v200, v208, v209
	v_cvt_pk_bf16_f32 v201, v210, v211
	v_cvt_pk_bf16_f32 v202, v212, v213
	v_cvt_pk_bf16_f32 v203, v214, v215
	global_store_dwordx4 v197, v[200:203], s[26:27]
	v_add_u32_e32 v197, 0x8000, v197
	s_waitcnt lgkmcnt(0)
	v_cvt_pk_bf16_f32 v204, v216, v217
	v_cvt_pk_bf16_f32 v205, v218, v219
	v_cvt_pk_bf16_f32 v206, v220, v221
	v_cvt_pk_bf16_f32 v207, v222, v223
	global_store_dwordx4 v197, v[204:207], s[26:27]
	v_add_u32_e32 v197, 0x8000, v197
	ds_read2_b32 v[208:209], v192 offset0:16 offset1:81
	ds_read2_b32 v[210:211], v192 offset0:146 offset1:211
	ds_read2_b32 v[212:213], v193 offset0:20 offset1:85
	ds_read2_b32 v[214:215], v193 offset0:150 offset1:215
	ds_read2_b32 v[216:217], v192 offset0:24 offset1:89
	ds_read2_b32 v[218:219], v192 offset0:154 offset1:219
	ds_read2_b32 v[220:221], v193 offset0:28 offset1:93
	ds_read2_b32 v[222:223], v193 offset0:158 offset1:223
	s_waitcnt lgkmcnt(4)
	v_cvt_pk_bf16_f32 v200, v208, v209
	v_cvt_pk_bf16_f32 v201, v210, v211
	v_cvt_pk_bf16_f32 v202, v212, v213
	v_cvt_pk_bf16_f32 v203, v214, v215
	global_store_dwordx4 v197, v[200:203], s[26:27]
	v_add_u32_e32 v197, 0x8000, v197
	s_waitcnt lgkmcnt(0)
	v_cvt_pk_bf16_f32 v204, v216, v217
	v_cvt_pk_bf16_f32 v205, v218, v219
	v_cvt_pk_bf16_f32 v206, v220, v221
	v_cvt_pk_bf16_f32 v207, v222, v223
	global_store_dwordx4 v197, v[204:207], s[26:27]
	v_add_u32_e32 v197, 0x8000, v197
	ds_read2_b32 v[208:209], v192 offset0:32 offset1:97
	ds_read2_b32 v[210:211], v192 offset0:162 offset1:227
	ds_read2_b32 v[212:213], v193 offset0:36 offset1:101
	ds_read2_b32 v[214:215], v193 offset0:166 offset1:231
	ds_read2_b32 v[216:217], v192 offset0:40 offset1:105
	ds_read2_b32 v[218:219], v192 offset0:170 offset1:235
	ds_read2_b32 v[220:221], v193 offset0:44 offset1:109
	ds_read2_b32 v[222:223], v193 offset0:174 offset1:239
	s_waitcnt lgkmcnt(4)
	v_cvt_pk_bf16_f32 v200, v208, v209
	v_cvt_pk_bf16_f32 v201, v210, v211
	v_cvt_pk_bf16_f32 v202, v212, v213
	v_cvt_pk_bf16_f32 v203, v214, v215
	global_store_dwordx4 v197, v[200:203], s[26:27]
	v_add_u32_e32 v197, 0x8000, v197
	s_waitcnt lgkmcnt(0)
	v_cvt_pk_bf16_f32 v204, v216, v217
	v_cvt_pk_bf16_f32 v205, v218, v219
	v_cvt_pk_bf16_f32 v206, v220, v221
	v_cvt_pk_bf16_f32 v207, v222, v223
	global_store_dwordx4 v197, v[204:207], s[26:27]
	v_add_u32_e32 v197, 0x8000, v197
	ds_read2_b32 v[208:209], v192 offset0:48 offset1:113
	ds_read2_b32 v[210:211], v192 offset0:178 offset1:243
	ds_read2_b32 v[212:213], v193 offset0:52 offset1:117
	ds_read2_b32 v[214:215], v193 offset0:182 offset1:247
	ds_read2_b32 v[216:217], v192 offset0:56 offset1:121
	ds_read2_b32 v[218:219], v192 offset0:186 offset1:251
	ds_read2_b32 v[220:221], v193 offset0:60 offset1:125
	ds_read2_b32 v[222:223], v193 offset0:190 offset1:255
	s_waitcnt lgkmcnt(4)
	v_cvt_pk_bf16_f32 v200, v208, v209
	v_cvt_pk_bf16_f32 v201, v210, v211
	v_cvt_pk_bf16_f32 v202, v212, v213
	v_cvt_pk_bf16_f32 v203, v214, v215
	global_store_dwordx4 v197, v[200:203], s[26:27]
	v_add_u32_e32 v197, 0x8000, v197
	s_waitcnt lgkmcnt(0)
	v_cvt_pk_bf16_f32 v204, v216, v217
	v_cvt_pk_bf16_f32 v205, v218, v219
	v_cvt_pk_bf16_f32 v206, v220, v221
	v_cvt_pk_bf16_f32 v207, v222, v223
	global_store_dwordx4 v197, v[204:207], s[26:27]
	v_add_u32_e32 v197, 0x8000, v197

.LBB0_1256:
	v_ashrrev_i32_e32 v4, 31, v8
	v_lshrrev_b32_e32 v4, 27, v4
	v_add_u32_e32 v4, v8, v4
	v_ashrrev_i32_e32 v4, 5, v4
	v_lshlrev_b32_e32 v5, 11, v4
	v_lshlrev_b32_e32 v4, 6, v4
	v_or_b32_e32 v48, v4, v9
	v_sub_u32_e32 v46, v12, v5
	v_or_b32_e32 v50, 4, v48
	v_or_b32_e32 v52, 8, v48
	v_or_b32_e32 v54, 12, v48
	v_or_b32_e32 v56, 16, v48
	v_or_b32_e32 v58, 20, v48
	v_or_b32_e32 v60, 24, v48
	v_or_b32_e32 v62, 28, v48
	v_or_b32_e32 v64, 32, v48
	v_or_b32_e32 v66, 36, v48
	v_or_b32_e32 v68, 40, v48
	v_or_b32_e32 v70, 44, v48
	v_ashrrev_i32_e32 v47, 31, v46
	v_ashrrev_i32_e32 v49, 31, v48
	v_or_b32_e32 v72, 48, v48
	v_or_b32_e32 v74, 52, v48
	v_or_b32_e32 v76, 56, v48
	v_or_b32_e32 v78, 60, v48
	v_ashrrev_i32_e32 v51, 31, v50
	v_ashrrev_i32_e32 v53, 31, v52
	v_ashrrev_i32_e32 v55, 31, v54
	v_ashrrev_i32_e32 v57, 31, v56
	v_ashrrev_i32_e32 v59, 31, v58
	v_ashrrev_i32_e32 v61, 31, v60
	v_ashrrev_i32_e32 v63, 31, v62
	v_ashrrev_i32_e32 v65, 31, v64
	v_ashrrev_i32_e32 v67, 31, v66
	v_ashrrev_i32_e32 v69, 31, v68
	v_ashrrev_i32_e32 v71, 31, v70
	v_add_u32_e32 v6, v46, v10
	v_lshl_add_u64 v[80:81], v[46:47], 2, v[0:1]
	v_lshlrev_b64 v[46:47], 13, v[48:49]
	v_ashrrev_i32_e32 v73, 31, v72
	v_ashrrev_i32_e32 v75, 31, v74
	v_ashrrev_i32_e32 v77, 31, v76
	v_ashrrev_i32_e32 v79, 31, v78
	v_lshlrev_b64 v[50:51], 13, v[50:51]
	v_lshlrev_b64 v[52:53], 13, v[52:53]
	v_lshlrev_b64 v[54:55], 13, v[54:55]
	v_lshlrev_b64 v[56:57], 13, v[56:57]
	v_lshlrev_b64 v[58:59], 13, v[58:59]
	v_lshlrev_b64 v[60:61], 13, v[60:61]
	v_lshlrev_b64 v[62:63], 13, v[62:63]
	v_lshlrev_b64 v[64:65], 13, v[64:65]
	v_lshlrev_b64 v[66:67], 13, v[66:67]
	v_lshlrev_b64 v[68:69], 13, v[68:69]
	v_lshlrev_b64 v[70:71], 13, v[70:71]
	v_lshl_add_u64 v[46:47], v[80:81], 0, v[46:47]
	v_lshlrev_b64 v[72:73], 13, v[72:73]
	v_lshlrev_b64 v[74:75], 13, v[74:75]
	v_lshlrev_b64 v[76:77], 13, v[76:77]
	v_lshlrev_b64 v[78:79], 13, v[78:79]
	v_lshl_add_u64 v[86:87], v[80:81], 0, v[50:51]
	v_lshl_add_u64 v[88:89], v[80:81], 0, v[52:53]
	v_lshl_add_u64 v[90:91], v[80:81], 0, v[54:55]
	v_lshl_add_u64 v[92:93], v[80:81], 0, v[56:57]
	v_lshl_add_u64 v[94:95], v[80:81], 0, v[58:59]
	v_lshl_add_u64 v[96:97], v[80:81], 0, v[60:61]
	v_lshl_add_u64 v[98:99], v[80:81], 0, v[62:63]
	v_lshl_add_u64 v[100:101], v[80:81], 0, v[64:65]
	v_lshl_add_u64 v[102:103], v[80:81], 0, v[66:67]
	v_lshl_add_u64 v[106:107], v[80:81], 0, v[68:69]
	v_lshl_add_u64 v[108:109], v[80:81], 0, v[70:71]
	global_load_dwordx4 v[46:49], v[46:47], off
	v_lshl_add_u64 v[124:125], v[80:81], 0, v[72:73]
	v_lshl_add_u64 v[126:127], v[80:81], 0, v[74:75]
	v_lshl_add_u64 v[128:129], v[80:81], 0, v[76:77]
	v_lshl_add_u64 v[130:131], v[80:81], 0, v[78:79]
	global_load_dwordx4 v[50:53], v[86:87], off
	global_load_dwordx4 v[54:57], v[88:89], off
	global_load_dwordx4 v[58:61], v[90:91], off
	global_load_dwordx4 v[62:65], v[92:93], off
	global_load_dwordx4 v[66:69], v[94:95], off
	global_load_dwordx4 v[70:73], v[96:97], off
	global_load_dwordx4 v[74:77], v[98:99], off
	global_load_dwordx4 v[78:81], v[100:101], off
	global_load_dwordx4 v[82:85], v[102:103], off
	global_load_dwordx4 v[86:89], v[106:107], off
	global_load_dwordx4 v[90:93], v[108:109], off
	global_load_dwordx4 v[94:97], v[124:125], off
	s_nop 0
	global_load_dwordx4 v[98:101], v[126:127], off
	global_load_dwordx4 v[102:105], v[128:129], off
	global_load_dwordx4 v[106:109], v[130:131], off
.Lmy_cv_loop:
	v_add_u32_e32 v132, s4, v8
	v_add_u32_e32 v133, s6, v12
	v_cmp_gt_i32_e32 vcc, s5, v132
	s_cbranch_vccz .Lmy_cv_nonext
	v_ashrrev_i32_e32 v246, 31, v132
	v_lshrrev_b32_e32 v246, 27, v246
	v_add_u32_e32 v246, v132, v246
	v_ashrrev_i32_e32 v246, 5, v246
	v_lshlrev_b32_e32 v247, 11, v246
	v_lshlrev_b32_e32 v246, 6, v246
	v_or_b32_e32 v162, v246, v9
	v_sub_u32_e32 v160, v133, v247
	v_or_b32_e32 v164, 4, v162
	v_or_b32_e32 v166, 8, v162
	v_or_b32_e32 v168, 12, v162
	v_or_b32_e32 v170, 16, v162
	v_or_b32_e32 v172, 20, v162
	v_or_b32_e32 v174, 24, v162
	v_or_b32_e32 v176, 28, v162
	v_or_b32_e32 v178, 32, v162
	v_or_b32_e32 v180, 36, v162
	v_or_b32_e32 v182, 40, v162
	v_or_b32_e32 v184, 44, v162
	v_ashrrev_i32_e32 v161, 31, v160
	v_ashrrev_i32_e32 v163, 31, v162
	v_or_b32_e32 v186, 48, v162
	v_or_b32_e32 v188, 52, v162
	v_or_b32_e32 v190, 56, v162
	v_or_b32_e32 v192, 60, v162
	v_ashrrev_i32_e32 v165, 31, v164
	v_ashrrev_i32_e32 v167, 31, v166
	v_ashrrev_i32_e32 v169, 31, v168
	v_ashrrev_i32_e32 v171, 31, v170
	v_ashrrev_i32_e32 v173, 31, v172
	v_ashrrev_i32_e32 v175, 31, v174
	v_ashrrev_i32_e32 v177, 31, v176
	v_ashrrev_i32_e32 v179, 31, v178
	v_ashrrev_i32_e32 v181, 31, v180
	v_ashrrev_i32_e32 v183, 31, v182
	v_ashrrev_i32_e32 v185, 31, v184
	v_add_u32_e32 v248, v160, v10
	v_lshl_add_u64 v[194:195], v[160:161], 2, v[0:1]
	v_lshlrev_b64 v[160:161], 13, v[162:163]
	v_ashrrev_i32_e32 v187, 31, v186
	v_ashrrev_i32_e32 v189, 31, v188
	v_ashrrev_i32_e32 v191, 31, v190
	v_ashrrev_i32_e32 v193, 31, v192
	v_lshlrev_b64 v[164:165], 13, v[164:165]
	v_lshlrev_b64 v[166:167], 13, v[166:167]
	v_lshlrev_b64 v[168:169], 13, v[168:169]
	v_lshlrev_b64 v[170:171], 13, v[170:171]
	v_lshlrev_b64 v[172:173], 13, v[172:173]
	v_lshlrev_b64 v[174:175], 13, v[174:175]
	v_lshlrev_b64 v[176:177], 13, v[176:177]
	v_lshlrev_b64 v[178:179], 13, v[178:179]
	v_lshlrev_b64 v[180:181], 13, v[180:181]
	v_lshlrev_b64 v[182:183], 13, v[182:183]
	v_lshlrev_b64 v[184:185], 13, v[184:185]
	v_lshl_add_u64 v[160:161], v[194:195], 0, v[160:161]
	v_lshlrev_b64 v[186:187], 13, v[186:187]
	v_lshlrev_b64 v[188:189], 13, v[188:189]
	v_lshlrev_b64 v[190:191], 13, v[190:191]
	v_lshlrev_b64 v[192:193], 13, v[192:193]
	v_lshl_add_u64 v[200:201], v[194:195], 0, v[164:165]
	v_lshl_add_u64 v[202:203], v[194:195], 0, v[166:167]
	v_lshl_add_u64 v[204:205], v[194:195], 0, v[168:169]
	v_lshl_add_u64 v[206:207], v[194:195], 0, v[170:171]
	v_lshl_add_u64 v[208:209], v[194:195], 0, v[172:173]
	v_lshl_add_u64 v[210:211], v[194:195], 0, v[174:175]
	v_lshl_add_u64 v[212:213], v[194:195], 0, v[176:177]
	v_lshl_add_u64 v[214:215], v[194:195], 0, v[178:179]
	v_lshl_add_u64 v[216:217], v[194:195], 0, v[180:181]
	v_lshl_add_u64 v[220:221], v[194:195], 0, v[182:183]
	v_lshl_add_u64 v[222:223], v[194:195], 0, v[184:185]
	global_load_dwordx4 v[160:163], v[160:161], off
	v_lshl_add_u64 v[238:239], v[194:195], 0, v[186:187]
	v_lshl_add_u64 v[240:241], v[194:195], 0, v[188:189]
	v_lshl_add_u64 v[242:243], v[194:195], 0, v[190:191]
	v_lshl_add_u64 v[244:245], v[194:195], 0, v[192:193]
	global_load_dwordx4 v[164:167], v[200:201], off
	global_load_dwordx4 v[168:171], v[202:203], off
	global_load_dwordx4 v[172:175], v[204:205], off
	global_load_dwordx4 v[176:179], v[206:207], off
	global_load_dwordx4 v[180:183], v[208:209], off
	global_load_dwordx4 v[184:187], v[210:211], off
	global_load_dwordx4 v[188:191], v[212:213], off
	global_load_dwordx4 v[192:195], v[214:215], off
	global_load_dwordx4 v[196:199], v[216:217], off
	global_load_dwordx4 v[200:203], v[220:221], off
	global_load_dwordx4 v[204:207], v[222:223], off
	global_load_dwordx4 v[208:211], v[238:239], off
	s_nop 0
	global_load_dwordx4 v[212:215], v[240:241], off
	global_load_dwordx4 v[216:219], v[242:243], off
	global_load_dwordx4 v[220:223], v[244:245], off
	s_waitcnt vmcnt(16)
	s_branch .Lmy_cv_wr
